# v089 with the softmax VALU stream alternating transcendental and plain ops between the MFMAs (ALT_TRANS)
# baseline (speedup 1.0000x reference)
; __device__ __forceinline__ void attn_unit(LAS unsigned char* lds, const bf16_t* Z, bf16_t* A2, const float* tabg, int seq_base, int S, int h, int qb, float lam) {
;     ...
;         if (kv0 - (qlo + 31) >= 128) { near = false; cc = tabR; } else if (qlo - (kv0 + 63) >= 128) { near = false; cc = tabL; }
;         { const float coff = cc - mu;
;           if (__any(!(coff == coff_cur))) { coff_cur = coff;
; #pragma unroll
;               for (int r = 0; r < 16; ++r) cblk[r] = coff;
;               asm volatile("" : "+v"(cblk)); } }
;         f32x16 p0, p1;
;         {
;             bf16x8 kf[8];
; #pragma unroll
;     ...
;         float mx = max2f(max16f(p0), max16f(p1));
;         const bool first = (t == 0);
;         if (first || __any(mx > THR)) {
;             { auto rr = __builtin_amdgcn_permlane32_swap(__float_as_uint(mx), __float_as_uint(mx), false, false); mx = max2f(__uint_as_float(rr[0]), __uint_as_float(rr[1])); }
;             const float delta = first ? mx : fmaxf(mx, 0.f);
;             const float alpha = first ? 1.0f : __builtin_amdgcn_exp2f(-delta);
;             mu += delta; ls2 *= alpha;
;             if (!first) {
;                 asm volatile("" ::: "memory");
;                 scr[r32] = alpha;
;                 asm volatile("s_waitcnt lgkmcnt(0)" ::: "memory");
; #pragma unroll
;                 for (int g = 0; g < 4; ++g) { const f32x4 a4 = *(const LAS f32x4*)(scr + 8 * g + 4 * hi);
; #pragma unroll
;                     for (int d = 0; d < 4; ++d) { O[d][4 * g + 0] *= a4[0]; O[d][4 * g + 1] *= a4[1]; O[d][4 * g + 2] *= a4[2]; O[d][4 * g + 3] *= a4[3]; } }
;                 asm volatile("s_waitcnt lgkmcnt(0)" ::: "memory");
;             }
; #pragma unroll
;             for (int r = 0; r < 16; ++r) { p0[r] -= delta; p1[r] -= delta; }
;             asm volatile("" : "+v"(p0), "+v"(p1));
;         }
; #pragma unroll
;         for (int r = 0; r < 16; ++r) { p0[r] = __builtin_amdgcn_exp2f(p0[r]); p1[r] = __builtin_amdgcn_exp2f(p1[r]); }
; #pragma unroll
;         for (int r = 0; r < 16; r += 2) { ls2 += (f32x2){p0[r], p0[r + 1]}; ls2 += (f32x2){p1[r], p1[r + 1]}; }
;         bf16x8 pa[4]; pa[0] = pack8(p0, 0); pa[1] = pack8(p0, 8); pa[2] = pack8(p1, 0); pa[3] = pack8(p1, 8);
;         LGKM0(); VREADS1(vb, 1); PV1(va, 0); LGKM0(); VREADS1(va, 2); PV1(vb, 1); LGKM0(); VREADS1(vb, 3); PV1(va, 2); LGKM0(); PV1(vb, 3);
.LatA_p0_nonear:
	v_max3_f32 v251, v84, v85, v86
	v_max3_f32 v252, v87, v88, v89
	v_max3_f32 v251, v251, v90, v91
	v_max3_f32 v252, v252, v92, v93
	v_max3_f32 v251, v251, v94, v95
	v_max3_f32 v252, v252, v96, v97
	v_max3_f32 v251, v251, v98, v99
	v_max3_f32 v252, v252, v100, v101
	v_max3_f32 v251, v251, v102, v103
	v_max3_f32 v252, v252, v104, v105
	v_max3_f32 v251, v251, v106, v107
	v_max3_f32 v252, v252, v108, v109
	v_max3_f32 v251, v251, v110, v111
	v_max3_f32 v252, v252, v112, v113
	v_max3_f32 v251, v251, v114, v115
	v_max_f32_e32 v251, v251, v252
	v_mov_b32_e32 v252, v251
	s_nop 1
	v_permlane32_swap_b32_e32 v251, v252
	v_max_f32_e32 v186, v251, v252
	v_sub_f32_e32 v84, v84, v186
	v_sub_f32_e32 v85, v85, v186
	v_sub_f32_e32 v86, v86, v186
	v_sub_f32_e32 v87, v87, v186
	v_sub_f32_e32 v88, v88, v186
	v_sub_f32_e32 v89, v89, v186
	v_sub_f32_e32 v90, v90, v186
	v_sub_f32_e32 v91, v91, v186
	v_sub_f32_e32 v92, v92, v186
	v_sub_f32_e32 v93, v93, v186
	v_sub_f32_e32 v94, v94, v186
	v_sub_f32_e32 v95, v95, v186
	v_sub_f32_e32 v96, v96, v186
	v_sub_f32_e32 v97, v97, v186
	v_sub_f32_e32 v98, v98, v186
	v_sub_f32_e32 v99, v99, v186
	v_sub_f32_e32 v100, v100, v186
	v_sub_f32_e32 v101, v101, v186
	v_sub_f32_e32 v102, v102, v186
	v_sub_f32_e32 v103, v103, v186
	v_sub_f32_e32 v104, v104, v186
	v_sub_f32_e32 v105, v105, v186
	v_sub_f32_e32 v106, v106, v186
	v_sub_f32_e32 v107, v107, v186
	v_sub_f32_e32 v108, v108, v186
	v_sub_f32_e32 v109, v109, v186
	v_sub_f32_e32 v110, v110, v186
	v_sub_f32_e32 v111, v111, v186
	v_sub_f32_e32 v112, v112, v186
	v_sub_f32_e32 v113, v113, v186
	v_sub_f32_e32 v114, v114, v186
	v_sub_f32_e32 v115, v115, v186
	s_add_u32 s38, s5, 64
	s_cmp_lt_u32 s38, s11
	s_cselect_b32 s37, 1, 0
	s_cmp_gt_u32 s38, s31
	s_cselect_b32 s40, 2, 0
	s_or_b32 s37, s37, s40
	s_mov_b32 s35, s37
	v_mov_b32_e32 v251, 0
	s_cmp_eq_u32 s37, 1
	s_cselect_b64 vcc, -1, 0
	v_cndmask_b32_e32 v251, v251, v177, vcc
	s_cmp_eq_u32 s37, 2
	s_cselect_b64 vcc, -1, 0
	v_cndmask_b32_e32 v251, v251, v178, vcc
	v_sub_f32_e32 v2, v251, v186
	v_mov_b32_e32 v3, v2
	v_mov_b64_e32 v[4:5], v[2:3]
	v_mov_b64_e32 v[6:7], v[2:3]
	v_mov_b64_e32 v[8:9], v[2:3]
	v_mov_b64_e32 v[10:11], v[2:3]
	v_mov_b64_e32 v[12:13], v[2:3]
	v_mov_b64_e32 v[14:15], v[2:3]
	v_mov_b64_e32 v[16:17], v[2:3]
	s_waitcnt vmcnt(0)
	s_barrier
	ds_read_b128 v[132:135], v19 offset:16384
	ds_read_b128 v[136:139], v19 offset:24576
	ds_read_b128 v[140:143], v180 offset:16384
	ds_read_b128 v[144:147], v180 offset:24576
	ds_read_b128 v[220:223], v181 offset:16384
	ds_read_b128 v[224:227], v181 offset:24576
	ds_read_b128 v[232:235], v182 offset:16384
	s_waitcnt lgkmcnt(6)
	s_add_u32 m0, s28, 0x1d000
	v_mfma_f32_32x32x16_bf16 v[188:203], v[132:135], v[116:119], v[2:17]
	global_load_lds_dwordx4 v172, s[8:9]
	ds_read_b128 v[236:239], v182 offset:24576
	v_exp_f32_e32 v84, v84
	v_exp_f32_e32 v85, v85
	v_exp_f32_e32 v86, v86
	v_exp_f32_e32 v87, v87
	v_add_f32_e32 v252, v84, v86
	v_exp_f32_e32 v88, v88
	v_add_f32_e32 v253, v85, v87
	v_exp_f32_e32 v89, v89
	s_waitcnt lgkmcnt(6)
	s_add_u32 m0, s29, 0x8000
	v_mfma_f32_32x32x16_bf16 v[204:219], v[136:139], v[116:119], v[2:17]
	global_load_lds_dwordx4 v174, s[8:9]
	ds_read_b64_tr_b16 v[132:133], v228 offset:0
	ds_read_b64_tr_b16 v[134:135], v228 offset:2048
	v_cvt_pk_bf16_f32 v84, v84, v85
	v_exp_f32_e32 v90, v90
	v_cvt_pk_bf16_f32 v85, v86, v87
	v_exp_f32_e32 v91, v91
	v_add_f32_e32 v252, v252, v88
	v_add_f32_e32 v253, v253, v89
	v_cvt_pk_bf16_f32 v86, v88, v89
	v_add_f32_e32 v252, v252, v90
	v_add_f32_e32 v253, v253, v91
	v_cvt_pk_bf16_f32 v87, v90, v91
	v_exp_f32_e32 v92, v92
	s_waitcnt lgkmcnt(7)
	s_add_u32 m0, s28, 0x1f000
	v_mfma_f32_32x32x16_bf16 v[188:203], v[140:143], v[120:123], v[188:203]
	global_load_lds_dwordx4 v173, s[8:9]
	ds_read_b64_tr_b16 v[136:137], v229 offset:0
	ds_read_b64_tr_b16 v[138:139], v229 offset:2048
	v_exp_f32_e32 v93, v93
	v_exp_f32_e32 v94, v94
	v_add_f32_e32 v252, v252, v92
	v_exp_f32_e32 v95, v95
	v_add_f32_e32 v253, v253, v93
	v_exp_f32_e32 v96, v96
	v_add_f32_e32 v252, v252, v94
	v_exp_f32_e32 v97, v97
	s_waitcnt lgkmcnt(8)
	s_add_u32 m0, s29, 0xa000
	v_mfma_f32_32x32x16_bf16 v[204:219], v[144:147], v[120:123], v[204:219]
	global_load_lds_dwordx4 v175, s[8:9]
	ds_read_b64_tr_b16 v[140:141], v230 offset:0
	ds_read_b64_tr_b16 v[142:143], v230 offset:2048
	v_add_f32_e32 v253, v253, v95
	v_exp_f32_e32 v98, v98
	v_cvt_pk_bf16_f32 v88, v92, v93
	v_exp_f32_e32 v99, v99
	v_cvt_pk_bf16_f32 v89, v94, v95
	v_add_f32_e32 v252, v252, v96
	v_add_f32_e32 v253, v253, v97
	v_cvt_pk_bf16_f32 v90, v96, v97
	v_add_f32_e32 v252, v252, v98
	v_add_f32_e32 v253, v253, v99
	v_cvt_pk_bf16_f32 v91, v98, v99
	s_waitcnt lgkmcnt(9)
	v_mfma_f32_32x32x16_bf16 v[188:203], v[220:223], v[124:127], v[188:203]
	ds_read_b64_tr_b16 v[144:145], v231 offset:0
	ds_read_b64_tr_b16 v[146:147], v231 offset:2048
	v_exp_f32_e32 v100, v100
	v_exp_f32_e32 v101, v101
	v_exp_f32_e32 v102, v102
	v_add_f32_e32 v252, v252, v100
	v_exp_f32_e32 v103, v103
	v_add_f32_e32 v253, v253, v101
	v_exp_f32_e32 v104, v104
	v_add_f32_e32 v252, v252, v102
	v_exp_f32_e32 v105, v105
	s_waitcnt lgkmcnt(10)
	v_mfma_f32_32x32x16_bf16 v[204:219], v[224:227], v[124:127], v[204:219]
	ds_read_b64_tr_b16 v[220:221], v228 offset:4096
	ds_read_b64_tr_b16 v[222:223], v228 offset:6144
	v_add_f32_e32 v253, v253, v103
	v_exp_f32_e32 v106, v106
	v_cvt_pk_bf16_f32 v100, v100, v101
	v_exp_f32_e32 v107, v107
	v_cvt_pk_bf16_f32 v101, v102, v103
	v_add_f32_e32 v252, v252, v104
	v_add_f32_e32 v253, v253, v105
	v_cvt_pk_bf16_f32 v102, v104, v105
	v_add_f32_e32 v252, v252, v106
	v_add_f32_e32 v253, v253, v107
	v_cvt_pk_bf16_f32 v103, v106, v107
	s_waitcnt lgkmcnt(11)
	v_mfma_f32_32x32x16_bf16 v[188:203], v[232:235], v[128:131], v[188:203]
	ds_read_b64_tr_b16 v[224:225], v229 offset:4096
	ds_read_b64_tr_b16 v[226:227], v229 offset:6144
	v_exp_f32_e32 v108, v108
	v_exp_f32_e32 v109, v109
	v_exp_f32_e32 v110, v110
	v_add_f32_e32 v252, v252, v108
	v_exp_f32_e32 v111, v111
	v_add_f32_e32 v253, v253, v109
	v_exp_f32_e32 v112, v112
	v_add_f32_e32 v252, v252, v110
	s_waitcnt lgkmcnt(12)
	v_mfma_f32_32x32x16_bf16 v[204:219], v[236:239], v[128:131], v[204:219]
	ds_read_b64_tr_b16 v[232:233], v230 offset:4096
	ds_read_b64_tr_b16 v[234:235], v230 offset:6144
	v_exp_f32_e32 v113, v113
	v_add_f32_e32 v253, v253, v111
	v_exp_f32_e32 v114, v114
	v_cvt_pk_bf16_f32 v104, v108, v109
	v_exp_f32_e32 v115, v115
	v_cvt_pk_bf16_f32 v105, v110, v111
	v_add_f32_e32 v252, v252, v112
	v_add_f32_e32 v253, v253, v113
	v_cvt_pk_bf16_f32 v106, v112, v113
	v_add_f32_e32 v252, v252, v114
	v_add_f32_e32 v253, v253, v115
	v_cvt_pk_bf16_f32 v107, v114, v115
	v_max_f32_e32 v251, v252, v253
	v_cmp_nge_f32_e32 vcc, 0x45800000, v251
	s_cbranch_vccnz .LatA_recs_h0

; #define LAS __attribute__((address_space(3)))
; #define VREADS1(arr, d_) do { const unsigned ad_ = vbase ^ (unsigned)((d_) << 6); __builtin_amdgcn_sched_barrier(0); \
;         _Pragma("unroll") for (int ks_ = 0; ks_ < 4; ++ks_) { VTR(arr[ks_ * 2], ad_, ks_ * 4096); VTR(arr[ks_ * 2 + 1], ad_, ks_ * 4096 + 2048); } __builtin_amdgcn_sched_barrier(0); } while (0)
; #define PV1(arr, d_) do { _Pragma("unroll") for (int ks_ = 0; ks_ < 4; ++ks_) { const s16x4 lo_ = arr[ks_ * 2], hh_ = arr[ks_ * 2 + 1]; \
;         const bf16x8 bv_ = (bf16x8){lo_[0], lo_[1], lo_[2], lo_[3], hh_[0], hh_[1], hh_[2], hh_[3]}; \
;         O[d_] = __builtin_amdgcn_mfma_f32_32x32x16_bf16(pa[ks_], bv_, O[d_], 0, 0, 0); } __builtin_amdgcn_sched_barrier(0); } while (0)
; #define LGKM0() do { __builtin_amdgcn_sched_barrier(0); asm volatile("s_waitcnt lgkmcnt(0)" ::: "memory"); __builtin_amdgcn_sched_barrier(0); } while (0)
; __device__ __forceinline__ void attn_unit(LAS unsigned char* lds, const bf16_t* Z, bf16_t* A2, const float* tabg, int seq_base, int S, int h, int qb, float lam) {
;     ...
;             for (int ds = 0; ds < 4; ++ds) { kf[2 * ds] = *(const LAS bf16x8*)(Kt + (kfo ^ (unsigned)(ds << 5))); kf[2 * ds + 1] = *(const LAS bf16x8*)(Kt + 32 * 256 + (kfo ^ (unsigned)(ds << 5))); }
;             __builtin_amdgcn_sched_barrier(0);
;             p0 = __builtin_amdgcn_mfma_f32_32x32x16_bf16(kf[0], qf[0], cblk, 0, 0, 0);
;             p1 = __builtin_amdgcn_mfma_f32_32x32x16_bf16(kf[1], qf[0], cblk, 0, 0, 0);
; #pragma unroll
;             for (int ds = 1; ds < 4; ++ds) {
;                 p0 = __builtin_amdgcn_mfma_f32_32x32x16_bf16(kf[2 * ds], qf[ds], p0, 0, 0, 0);
;                 p1 = __builtin_amdgcn_mfma_f32_32x32x16_bf16(kf[2 * ds + 1], qf[ds], p1, 0, 0, 0);
;             }
;     ...
; #pragma unroll
;         for (int r = 0; r < 16; ++r) { p0[r] = __builtin_amdgcn_exp2f(p0[r]); p1[r] = __builtin_amdgcn_exp2f(p1[r]); }
; #pragma unroll
;         for (int r = 0; r < 16; r += 2) { ls2 += (f32x2){p0[r], p0[r + 1]}; ls2 += (f32x2){p1[r], p1[r + 1]}; }
;         bf16x8 pa[4]; pa[0] = pack8(p0, 0); pa[1] = pack8(p0, 8); pa[2] = pack8(p1, 0); pa[3] = pack8(p1, 8);
;         LGKM0(); VREADS1(vb, 1); PV1(va, 0); LGKM0(); VREADS1(va, 2); PV1(vb, 1); LGKM0(); VREADS1(vb, 3); PV1(va, 2); LGKM0(); PV1(vb, 3);
.LatA_evret_h1:
	s_waitcnt lgkmcnt(12)
	v_mfma_f32_32x32x16_bf16 v[20:35], v[84:87], v[132:135], v[20:35]
	ds_read_b64_tr_b16 v[236:237], v231 offset:4096
	ds_read_b64_tr_b16 v[238:239], v231 offset:6144
	v_exp_f32_e32 v188, v188
	v_exp_f32_e32 v189, v189
	s_waitcnt lgkmcnt(12)
	v_mfma_f32_32x32x16_bf16 v[36:51], v[84:87], v[136:139], v[36:51]
	ds_read_b64_tr_b16 v[132:133], v228 offset:8192
	ds_read_b64_tr_b16 v[134:135], v228 offset:10240
	v_exp_f32_e32 v190, v190
	v_exp_f32_e32 v191, v191
	v_add_f32_e32 v252, v188, v190
	s_waitcnt lgkmcnt(12)
	v_mfma_f32_32x32x16_bf16 v[52:67], v[84:87], v[140:143], v[52:67]
	ds_read_b64_tr_b16 v[136:137], v229 offset:8192
	ds_read_b64_tr_b16 v[138:139], v229 offset:10240
	v_exp_f32_e32 v192, v192
	v_add_f32_e32 v253, v189, v191
	v_exp_f32_e32 v193, v193
	s_waitcnt lgkmcnt(12)
	s_mov_b32 m0, s28
	v_mfma_f32_32x32x16_bf16 v[68:83], v[84:87], v[144:147], v[68:83]
	global_load_lds_dwordx4 v172, s[8:9]
	ds_read_b64_tr_b16 v[140:141], v230 offset:8192
	ds_read_b64_tr_b16 v[142:143], v230 offset:10240
	v_cvt_pk_bf16_f32 v188, v188, v189
	v_exp_f32_e32 v194, v194
	v_cvt_pk_bf16_f32 v189, v190, v191
	s_waitcnt lgkmcnt(12)
	v_mfma_f32_32x32x16_bf16 v[20:35], v[88:91], v[220:223], v[20:35]
	ds_read_b64_tr_b16 v[144:145], v231 offset:8192
	ds_read_b64_tr_b16 v[146:147], v231 offset:10240
	v_exp_f32_e32 v195, v195
	v_add_f32_e32 v252, v252, v192
	v_add_f32_e32 v253, v253, v193
	v_cvt_pk_bf16_f32 v190, v192, v193
	s_waitcnt lgkmcnt(12)
	v_mfma_f32_32x32x16_bf16 v[36:51], v[88:91], v[224:227], v[36:51]
	ds_read_b64_tr_b16 v[220:221], v228 offset:12288
	ds_read_b64_tr_b16 v[222:223], v228 offset:14336
	v_add_f32_e32 v252, v252, v194
	v_add_f32_e32 v253, v253, v195
	v_cvt_pk_bf16_f32 v191, v194, v195
	v_exp_f32_e32 v196, v196
	s_waitcnt lgkmcnt(12)
	v_mfma_f32_32x32x16_bf16 v[52:67], v[88:91], v[232:235], v[52:67]
	ds_read_b64_tr_b16 v[224:225], v229 offset:12288
	ds_read_b64_tr_b16 v[226:227], v229 offset:14336
	v_exp_f32_e32 v197, v197
	v_exp_f32_e32 v198, v198
	s_waitcnt lgkmcnt(12)
	s_add_u32 m0, s29, 0xd000
	v_mfma_f32_32x32x16_bf16 v[68:83], v[88:91], v[236:239], v[68:83]
	global_load_lds_dwordx4 v174, s[8:9]
	ds_read_b64_tr_b16 v[232:233], v230 offset:12288
	ds_read_b64_tr_b16 v[234:235], v230 offset:14336
	v_add_f32_e32 v252, v252, v196
	v_exp_f32_e32 v199, v199
	v_add_f32_e32 v253, v253, v197
	s_waitcnt lgkmcnt(12)
	v_mfma_f32_32x32x16_bf16 v[20:35], v[100:103], v[132:135], v[20:35]
	ds_read_b64_tr_b16 v[236:237], v231 offset:12288
	ds_read_b64_tr_b16 v[238:239], v231 offset:14336
	v_exp_f32_e32 v200, v200
	v_add_f32_e32 v252, v252, v198
	v_exp_f32_e32 v201, v201
	s_waitcnt lgkmcnt(12)
	v_mfma_f32_32x32x16_bf16 v[36:51], v[100:103], v[136:139], v[36:51]
	ds_read_b128 v[132:135], v19 offset:32768
	v_add_f32_e32 v253, v253, v199
	v_exp_f32_e32 v202, v202
	v_cvt_pk_bf16_f32 v192, v196, v197
	s_waitcnt lgkmcnt(11)
	v_mfma_f32_32x32x16_bf16 v[52:67], v[100:103], v[140:143], v[52:67]
	ds_read_b128 v[136:139], v19 offset:40960
	v_exp_f32_e32 v203, v203
	v_cvt_pk_bf16_f32 v193, v198, v199
	v_add_f32_e32 v252, v252, v200
	v_add_f32_e32 v253, v253, v201
	s_waitcnt lgkmcnt(10)
	s_add_u32 m0, s28, 0x2000
	v_mfma_f32_32x32x16_bf16 v[68:83], v[100:103], v[144:147], v[68:83]
	global_load_lds_dwordx4 v173, s[8:9]
	ds_read_b128 v[140:143], v180 offset:32768
	v_cvt_pk_bf16_f32 v194, v200, v201
	v_add_f32_e32 v252, v252, v202
	v_add_f32_e32 v253, v253, v203
	v_cvt_pk_bf16_f32 v195, v202, v203
	s_waitcnt lgkmcnt(9)
	v_mfma_f32_32x32x16_bf16 v[20:35], v[104:107], v[220:223], v[20:35]
	ds_read_b128 v[144:147], v180 offset:40960
	v_exp_f32_e32 v204, v204
	v_exp_f32_e32 v205, v205
	v_exp_f32_e32 v206, v206
	s_waitcnt lgkmcnt(8)
	v_mfma_f32_32x32x16_bf16 v[36:51], v[104:107], v[224:227], v[36:51]
	ds_read_b128 v[220:223], v181 offset:32768
	v_add_f32_e32 v252, v252, v204
	v_exp_f32_e32 v207, v207
	v_add_f32_e32 v253, v253, v205
	s_waitcnt lgkmcnt(7)
	v_mfma_f32_32x32x16_bf16 v[52:67], v[104:107], v[232:235], v[52:67]
	ds_read_b128 v[224:227], v181 offset:40960
	v_exp_f32_e32 v208, v208
	v_add_f32_e32 v252, v252, v206
	v_exp_f32_e32 v209, v209
	s_waitcnt lgkmcnt(6)
	s_add_u32 m0, s29, 0xf000
	v_mfma_f32_32x32x16_bf16 v[68:83], v[104:107], v[236:239], v[68:83]
	global_load_lds_dwordx4 v175, s[8:9]
	ds_read_b128 v[232:235], v182 offset:32768
	v_add_f32_e32 v253, v253, v207
	v_exp_f32_e32 v210, v210
	v_cvt_pk_bf16_f32 v204, v204, v205
	s_waitcnt lgkmcnt(6)
	v_mfma_f32_32x32x16_bf16 v[84:99], v[132:135], v[116:119], v[2:17]
	ds_read_b128 v[236:239], v182 offset:40960
	v_exp_f32_e32 v211, v211
	v_cvt_pk_bf16_f32 v205, v206, v207
	v_add_f32_e32 v252, v252, v208
	v_add_f32_e32 v253, v253, v209
	s_waitcnt lgkmcnt(6)
	v_mfma_f32_32x32x16_bf16 v[100:115], v[136:139], v[116:119], v[2:17]
	ds_read_b64_tr_b16 v[132:133], v228 offset:16384
	ds_read_b64_tr_b16 v[134:135], v228 offset:18432
	v_cvt_pk_bf16_f32 v206, v208, v209
	v_add_f32_e32 v252, v252, v210
	v_add_f32_e32 v253, v253, v211
	v_cvt_pk_bf16_f32 v207, v210, v211
	s_waitcnt lgkmcnt(7)
	v_mfma_f32_32x32x16_bf16 v[84:99], v[140:143], v[120:123], v[84:99]
	ds_read_b64_tr_b16 v[136:137], v229 offset:16384
	ds_read_b64_tr_b16 v[138:139], v229 offset:18432
	v_exp_f32_e32 v212, v212
	v_exp_f32_e32 v213, v213
	s_waitcnt lgkmcnt(8)
	v_mfma_f32_32x32x16_bf16 v[100:115], v[144:147], v[120:123], v[100:115]
	ds_read_b64_tr_b16 v[140:141], v230 offset:16384
	ds_read_b64_tr_b16 v[142:143], v230 offset:18432
	v_exp_f32_e32 v214, v214
	v_add_f32_e32 v252, v252, v212
	v_exp_f32_e32 v215, v215
	v_add_f32_e32 v253, v253, v213
	s_waitcnt lgkmcnt(9)
	v_mfma_f32_32x32x16_bf16 v[84:99], v[220:223], v[124:127], v[84:99]
	ds_read_b64_tr_b16 v[144:145], v231 offset:16384
	ds_read_b64_tr_b16 v[146:147], v231 offset:18432
	v_exp_f32_e32 v216, v216
	v_add_f32_e32 v252, v252, v214
	s_waitcnt lgkmcnt(10)
	v_mfma_f32_32x32x16_bf16 v[100:115], v[224:227], v[124:127], v[100:115]
	ds_read_b64_tr_b16 v[220:221], v228 offset:20480
	ds_read_b64_tr_b16 v[222:223], v228 offset:22528
	v_exp_f32_e32 v217, v217
	v_add_f32_e32 v253, v253, v215
	v_exp_f32_e32 v218, v218
	v_cvt_pk_bf16_f32 v208, v212, v213
	s_waitcnt lgkmcnt(11)
	v_mfma_f32_32x32x16_bf16 v[84:99], v[232:235], v[128:131], v[84:99]
	ds_read_b64_tr_b16 v[224:225], v229 offset:20480
	ds_read_b64_tr_b16 v[226:227], v229 offset:22528
	v_exp_f32_e32 v219, v219
	v_cvt_pk_bf16_f32 v209, v214, v215
	v_add_f32_e32 v252, v252, v216
	s_waitcnt lgkmcnt(12)
	v_mfma_f32_32x32x16_bf16 v[100:115], v[236:239], v[128:131], v[100:115]
	ds_read_b64_tr_b16 v[232:233], v230 offset:20480
	ds_read_b64_tr_b16 v[234:235], v230 offset:22528
	v_add_f32_e32 v253, v253, v217
	v_cvt_pk_bf16_f32 v210, v216, v217
	v_add_f32_e32 v252, v252, v218
	v_add_f32_e32 v253, v253, v219
	v_cvt_pk_bf16_f32 v211, v218, v219
	v_max_f32_e32 v251, v252, v253
	v_cmp_nge_f32_e32 vcc, 0x45800000, v251
	s_cbranch_vccnz .LatA_recs_h1

; #define LAS __attribute__((address_space(3)))
; #define VREADS1(arr, d_) do { const unsigned ad_ = vbase ^ (unsigned)((d_) << 6); __builtin_amdgcn_sched_barrier(0); \
;         _Pragma("unroll") for (int ks_ = 0; ks_ < 4; ++ks_) { VTR(arr[ks_ * 2], ad_, ks_ * 4096); VTR(arr[ks_ * 2 + 1], ad_, ks_ * 4096 + 2048); } __builtin_amdgcn_sched_barrier(0); } while (0)
; #define PV1(arr, d_) do { _Pragma("unroll") for (int ks_ = 0; ks_ < 4; ++ks_) { const s16x4 lo_ = arr[ks_ * 2], hh_ = arr[ks_ * 2 + 1]; \
;         const bf16x8 bv_ = (bf16x8){lo_[0], lo_[1], lo_[2], lo_[3], hh_[0], hh_[1], hh_[2], hh_[3]}; \
;         O[d_] = __builtin_amdgcn_mfma_f32_32x32x16_bf16(pa[ks_], bv_, O[d_], 0, 0, 0); } __builtin_amdgcn_sched_barrier(0); } while (0)
; #define LGKM0() do { __builtin_amdgcn_sched_barrier(0); asm volatile("s_waitcnt lgkmcnt(0)" ::: "memory"); __builtin_amdgcn_sched_barrier(0); } while (0)
; __device__ __forceinline__ void attn_unit(LAS unsigned char* lds, const bf16_t* Z, bf16_t* A2, const float* tabg, int seq_base, int S, int h, int qb, float lam) {
;     ...
;             for (int ds = 0; ds < 4; ++ds) { kf[2 * ds] = *(const LAS bf16x8*)(Kt + (kfo ^ (unsigned)(ds << 5))); kf[2 * ds + 1] = *(const LAS bf16x8*)(Kt + 32 * 256 + (kfo ^ (unsigned)(ds << 5))); }
;             __builtin_amdgcn_sched_barrier(0);
;             p0 = __builtin_amdgcn_mfma_f32_32x32x16_bf16(kf[0], qf[0], cblk, 0, 0, 0);
;             p1 = __builtin_amdgcn_mfma_f32_32x32x16_bf16(kf[1], qf[0], cblk, 0, 0, 0);
; #pragma unroll
;             for (int ds = 1; ds < 4; ++ds) {
;                 p0 = __builtin_amdgcn_mfma_f32_32x32x16_bf16(kf[2 * ds], qf[ds], p0, 0, 0, 0);
;                 p1 = __builtin_amdgcn_mfma_f32_32x32x16_bf16(kf[2 * ds + 1], qf[ds], p1, 0, 0, 0);
;             }
;     ...
; #pragma unroll
;         for (int r = 0; r < 16; ++r) { p0[r] = __builtin_amdgcn_exp2f(p0[r]); p1[r] = __builtin_amdgcn_exp2f(p1[r]); }
; #pragma unroll
;         for (int r = 0; r < 16; r += 2) { ls2 += (f32x2){p0[r], p0[r + 1]}; ls2 += (f32x2){p1[r], p1[r + 1]}; }
;         bf16x8 pa[4]; pa[0] = pack8(p0, 0); pa[1] = pack8(p0, 8); pa[2] = pack8(p1, 0); pa[3] = pack8(p1, 8);
;         LGKM0(); VREADS1(vb, 1); PV1(va, 0); LGKM0(); VREADS1(va, 2); PV1(vb, 1); LGKM0(); VREADS1(vb, 3); PV1(va, 2); LGKM0(); PV1(vb, 3);
.LatA_evret_h2:
	s_waitcnt lgkmcnt(12)
	v_mfma_f32_32x32x16_bf16 v[20:35], v[188:191], v[132:135], v[20:35]
	ds_read_b64_tr_b16 v[236:237], v231 offset:20480
	ds_read_b64_tr_b16 v[238:239], v231 offset:22528
	v_exp_f32_e32 v84, v84
	v_exp_f32_e32 v85, v85
	s_waitcnt lgkmcnt(12)
	v_mfma_f32_32x32x16_bf16 v[36:51], v[188:191], v[136:139], v[36:51]
	ds_read_b64_tr_b16 v[132:133], v228 offset:24576
	ds_read_b64_tr_b16 v[134:135], v228 offset:26624
	v_exp_f32_e32 v86, v86
	v_exp_f32_e32 v87, v87
	v_add_f32_e32 v252, v84, v86
	s_waitcnt lgkmcnt(12)
	v_mfma_f32_32x32x16_bf16 v[52:67], v[188:191], v[140:143], v[52:67]
	ds_read_b64_tr_b16 v[136:137], v229 offset:24576
	ds_read_b64_tr_b16 v[138:139], v229 offset:26624
	v_exp_f32_e32 v88, v88
	v_add_f32_e32 v253, v85, v87
	v_exp_f32_e32 v89, v89
	s_waitcnt lgkmcnt(12)
	s_add_u32 m0, s28, 0x4000
	v_mfma_f32_32x32x16_bf16 v[68:83], v[188:191], v[144:147], v[68:83]
	global_load_lds_dwordx4 v172, s[8:9]
	ds_read_b64_tr_b16 v[140:141], v230 offset:24576
	ds_read_b64_tr_b16 v[142:143], v230 offset:26624
	v_cvt_pk_bf16_f32 v84, v84, v85
	v_exp_f32_e32 v90, v90
	v_cvt_pk_bf16_f32 v85, v86, v87
	s_waitcnt lgkmcnt(12)
	v_mfma_f32_32x32x16_bf16 v[20:35], v[192:195], v[220:223], v[20:35]
	ds_read_b64_tr_b16 v[144:145], v231 offset:24576
	ds_read_b64_tr_b16 v[146:147], v231 offset:26624
	v_exp_f32_e32 v91, v91
	v_add_f32_e32 v252, v252, v88
	v_add_f32_e32 v253, v253, v89
	v_cvt_pk_bf16_f32 v86, v88, v89
	s_waitcnt lgkmcnt(12)
	v_mfma_f32_32x32x16_bf16 v[36:51], v[192:195], v[224:227], v[36:51]
	ds_read_b64_tr_b16 v[220:221], v228 offset:28672
	ds_read_b64_tr_b16 v[222:223], v228 offset:30720
	v_add_f32_e32 v252, v252, v90
	v_add_f32_e32 v253, v253, v91
	v_cvt_pk_bf16_f32 v87, v90, v91
	v_exp_f32_e32 v92, v92
	s_waitcnt lgkmcnt(12)
	v_mfma_f32_32x32x16_bf16 v[52:67], v[192:195], v[232:235], v[52:67]
	ds_read_b64_tr_b16 v[224:225], v229 offset:28672
	ds_read_b64_tr_b16 v[226:227], v229 offset:30720
	v_exp_f32_e32 v93, v93
	v_exp_f32_e32 v94, v94
	s_waitcnt lgkmcnt(12)
	s_mov_b32 m0, s29
	v_mfma_f32_32x32x16_bf16 v[68:83], v[192:195], v[236:239], v[68:83]
	global_load_lds_dwordx4 v174, s[8:9]
	ds_read_b64_tr_b16 v[232:233], v230 offset:28672
	ds_read_b64_tr_b16 v[234:235], v230 offset:30720
	v_add_f32_e32 v252, v252, v92
	v_exp_f32_e32 v95, v95
	v_add_f32_e32 v253, v253, v93
	s_waitcnt lgkmcnt(12)
	v_mfma_f32_32x32x16_bf16 v[20:35], v[204:207], v[132:135], v[20:35]
	ds_read_b64_tr_b16 v[236:237], v231 offset:28672
	ds_read_b64_tr_b16 v[238:239], v231 offset:30720
	v_exp_f32_e32 v96, v96
	v_add_f32_e32 v252, v252, v94
	v_exp_f32_e32 v97, v97
	s_waitcnt lgkmcnt(12)
	v_mfma_f32_32x32x16_bf16 v[36:51], v[204:207], v[136:139], v[36:51]
	ds_read_b128 v[132:135], v164
	v_add_f32_e32 v253, v253, v95
	v_exp_f32_e32 v98, v98
	v_cvt_pk_bf16_f32 v88, v92, v93
	s_waitcnt lgkmcnt(11)
	v_mfma_f32_32x32x16_bf16 v[52:67], v[204:207], v[140:143], v[52:67]
	ds_read_b128 v[136:139], v164 offset:8192
	v_exp_f32_e32 v99, v99
	v_cvt_pk_bf16_f32 v89, v94, v95
	v_add_f32_e32 v252, v252, v96
	v_add_f32_e32 v253, v253, v97
	s_waitcnt lgkmcnt(10)
	s_add_u32 m0, s28, 0x6000
	v_mfma_f32_32x32x16_bf16 v[68:83], v[204:207], v[144:147], v[68:83]
	global_load_lds_dwordx4 v173, s[8:9]
	ds_read_b128 v[140:143], v165
	v_cvt_pk_bf16_f32 v90, v96, v97
	v_add_f32_e32 v252, v252, v98
	v_add_f32_e32 v253, v253, v99
	v_cvt_pk_bf16_f32 v91, v98, v99
	s_waitcnt lgkmcnt(9)
	v_mfma_f32_32x32x16_bf16 v[20:35], v[208:211], v[220:223], v[20:35]
	ds_read_b128 v[144:147], v165 offset:8192
	v_exp_f32_e32 v100, v100
	v_exp_f32_e32 v101, v101
	v_exp_f32_e32 v102, v102
	s_waitcnt lgkmcnt(8)
	v_mfma_f32_32x32x16_bf16 v[36:51], v[208:211], v[224:227], v[36:51]
	ds_read_b128 v[220:223], v166
	v_add_f32_e32 v252, v252, v100
	v_exp_f32_e32 v103, v103
	v_add_f32_e32 v253, v253, v101
	s_waitcnt lgkmcnt(7)
	v_mfma_f32_32x32x16_bf16 v[52:67], v[208:211], v[232:235], v[52:67]
	ds_read_b128 v[224:227], v166 offset:8192
	v_exp_f32_e32 v104, v104
	v_add_f32_e32 v252, v252, v102
	v_exp_f32_e32 v105, v105
	s_waitcnt lgkmcnt(6)
	s_add_u32 m0, s29, 0x2000
	v_mfma_f32_32x32x16_bf16 v[68:83], v[208:211], v[236:239], v[68:83]
	global_load_lds_dwordx4 v175, s[8:9]
	ds_read_b128 v[232:235], v167
	v_add_f32_e32 v253, v253, v103
	v_exp_f32_e32 v106, v106
	v_cvt_pk_bf16_f32 v100, v100, v101
	s_waitcnt lgkmcnt(6)
	v_mfma_f32_32x32x16_bf16 v[188:203], v[132:135], v[116:119], v[2:17]
	ds_read_b128 v[236:239], v167 offset:8192
	v_exp_f32_e32 v107, v107
	v_cvt_pk_bf16_f32 v101, v102, v103
	v_add_f32_e32 v252, v252, v104
	v_add_f32_e32 v253, v253, v105
	s_waitcnt lgkmcnt(6)
	v_mfma_f32_32x32x16_bf16 v[204:219], v[136:139], v[116:119], v[2:17]
	ds_read_b64_tr_b16 v[132:133], v228 offset:32768
	ds_read_b64_tr_b16 v[134:135], v228 offset:34816
	v_cvt_pk_bf16_f32 v102, v104, v105
	v_add_f32_e32 v252, v252, v106
	v_add_f32_e32 v253, v253, v107
	v_cvt_pk_bf16_f32 v103, v106, v107
	s_waitcnt lgkmcnt(7)
	v_mfma_f32_32x32x16_bf16 v[188:203], v[140:143], v[120:123], v[188:203]
	ds_read_b64_tr_b16 v[136:137], v229 offset:32768
	ds_read_b64_tr_b16 v[138:139], v229 offset:34816
	v_exp_f32_e32 v108, v108
	v_exp_f32_e32 v109, v109
	s_waitcnt lgkmcnt(8)
	v_mfma_f32_32x32x16_bf16 v[204:219], v[144:147], v[120:123], v[204:219]
	ds_read_b64_tr_b16 v[140:141], v230 offset:32768
	ds_read_b64_tr_b16 v[142:143], v230 offset:34816
	v_exp_f32_e32 v110, v110
	v_add_f32_e32 v252, v252, v108
	v_exp_f32_e32 v111, v111
	v_add_f32_e32 v253, v253, v109
	s_waitcnt lgkmcnt(9)
	v_mfma_f32_32x32x16_bf16 v[188:203], v[220:223], v[124:127], v[188:203]
	ds_read_b64_tr_b16 v[144:145], v231 offset:32768
	ds_read_b64_tr_b16 v[146:147], v231 offset:34816
	v_exp_f32_e32 v112, v112
	v_add_f32_e32 v252, v252, v110
	s_waitcnt lgkmcnt(10)
	v_mfma_f32_32x32x16_bf16 v[204:219], v[224:227], v[124:127], v[204:219]
	ds_read_b64_tr_b16 v[220:221], v228 offset:36864
	ds_read_b64_tr_b16 v[222:223], v228 offset:38912
	v_exp_f32_e32 v113, v113
	v_add_f32_e32 v253, v253, v111
	v_exp_f32_e32 v114, v114
	v_cvt_pk_bf16_f32 v104, v108, v109
	s_waitcnt lgkmcnt(11)
	v_mfma_f32_32x32x16_bf16 v[188:203], v[232:235], v[128:131], v[188:203]
	ds_read_b64_tr_b16 v[224:225], v229 offset:36864
	ds_read_b64_tr_b16 v[226:227], v229 offset:38912
	v_exp_f32_e32 v115, v115
	v_cvt_pk_bf16_f32 v105, v110, v111
	v_add_f32_e32 v252, v252, v112
	s_waitcnt lgkmcnt(12)
	v_mfma_f32_32x32x16_bf16 v[204:219], v[236:239], v[128:131], v[204:219]
	ds_read_b64_tr_b16 v[232:233], v230 offset:36864
	ds_read_b64_tr_b16 v[234:235], v230 offset:38912
	v_add_f32_e32 v253, v253, v113
	v_cvt_pk_bf16_f32 v106, v112, v113
	v_add_f32_e32 v252, v252, v114
	v_add_f32_e32 v253, v253, v115
	v_cvt_pk_bf16_f32 v107, v114, v115
	v_max_f32_e32 v251, v252, v253
	v_cmp_nge_f32_e32 vcc, 0x45800000, v251
	s_cbranch_vccnz .LatA_recs_h2

; #define LAS __attribute__((address_space(3)))
; #define VREADS1(arr, d_) do { const unsigned ad_ = vbase ^ (unsigned)((d_) << 6); __builtin_amdgcn_sched_barrier(0); \
;         _Pragma("unroll") for (int ks_ = 0; ks_ < 4; ++ks_) { VTR(arr[ks_ * 2], ad_, ks_ * 4096); VTR(arr[ks_ * 2 + 1], ad_, ks_ * 4096 + 2048); } __builtin_amdgcn_sched_barrier(0); } while (0)
; #define PV1(arr, d_) do { _Pragma("unroll") for (int ks_ = 0; ks_ < 4; ++ks_) { const s16x4 lo_ = arr[ks_ * 2], hh_ = arr[ks_ * 2 + 1]; \
;         const bf16x8 bv_ = (bf16x8){lo_[0], lo_[1], lo_[2], lo_[3], hh_[0], hh_[1], hh_[2], hh_[3]}; \
;         O[d_] = __builtin_amdgcn_mfma_f32_32x32x16_bf16(pa[ks_], bv_, O[d_], 0, 0, 0); } __builtin_amdgcn_sched_barrier(0); } while (0)
; #define LGKM0() do { __builtin_amdgcn_sched_barrier(0); asm volatile("s_waitcnt lgkmcnt(0)" ::: "memory"); __builtin_amdgcn_sched_barrier(0); } while (0)
; __device__ __forceinline__ void attn_unit(LAS unsigned char* lds, const bf16_t* Z, bf16_t* A2, const float* tabg, int seq_base, int S, int h, int qb, float lam) {
;     ...
;             for (int ds = 0; ds < 4; ++ds) { kf[2 * ds] = *(const LAS bf16x8*)(Kt + (kfo ^ (unsigned)(ds << 5))); kf[2 * ds + 1] = *(const LAS bf16x8*)(Kt + 32 * 256 + (kfo ^ (unsigned)(ds << 5))); }
;             __builtin_amdgcn_sched_barrier(0);
;             p0 = __builtin_amdgcn_mfma_f32_32x32x16_bf16(kf[0], qf[0], cblk, 0, 0, 0);
;             p1 = __builtin_amdgcn_mfma_f32_32x32x16_bf16(kf[1], qf[0], cblk, 0, 0, 0);
; #pragma unroll
;             for (int ds = 1; ds < 4; ++ds) {
;                 p0 = __builtin_amdgcn_mfma_f32_32x32x16_bf16(kf[2 * ds], qf[ds], p0, 0, 0, 0);
;                 p1 = __builtin_amdgcn_mfma_f32_32x32x16_bf16(kf[2 * ds + 1], qf[ds], p1, 0, 0, 0);
;             }
;     ...
; #pragma unroll
;         for (int r = 0; r < 16; ++r) { p0[r] = __builtin_amdgcn_exp2f(p0[r]); p1[r] = __builtin_amdgcn_exp2f(p1[r]); }
; #pragma unroll
;         for (int r = 0; r < 16; r += 2) { ls2 += (f32x2){p0[r], p0[r + 1]}; ls2 += (f32x2){p1[r], p1[r + 1]}; }
;         bf16x8 pa[4]; pa[0] = pack8(p0, 0); pa[1] = pack8(p0, 8); pa[2] = pack8(p1, 0); pa[3] = pack8(p1, 8);
;         LGKM0(); VREADS1(vb, 1); PV1(va, 0); LGKM0(); VREADS1(va, 2); PV1(vb, 1); LGKM0(); VREADS1(vb, 3); PV1(va, 2); LGKM0(); PV1(vb, 3);
.LatA_evret_h3:
	s_waitcnt lgkmcnt(12)
	v_mfma_f32_32x32x16_bf16 v[20:35], v[84:87], v[132:135], v[20:35]
	ds_read_b64_tr_b16 v[236:237], v231 offset:36864
	ds_read_b64_tr_b16 v[238:239], v231 offset:38912
	v_exp_f32_e32 v188, v188
	v_exp_f32_e32 v189, v189
	s_waitcnt lgkmcnt(12)
	v_mfma_f32_32x32x16_bf16 v[36:51], v[84:87], v[136:139], v[36:51]
	ds_read_b64_tr_b16 v[132:133], v228 offset:40960
	ds_read_b64_tr_b16 v[134:135], v228 offset:43008
	v_exp_f32_e32 v190, v190
	v_exp_f32_e32 v191, v191
	v_add_f32_e32 v252, v188, v190
	s_waitcnt lgkmcnt(12)
	v_mfma_f32_32x32x16_bf16 v[52:67], v[84:87], v[140:143], v[52:67]
	ds_read_b64_tr_b16 v[136:137], v229 offset:40960
	ds_read_b64_tr_b16 v[138:139], v229 offset:43008
	v_exp_f32_e32 v192, v192
	v_add_f32_e32 v253, v189, v191
	v_exp_f32_e32 v193, v193
	s_waitcnt lgkmcnt(12)
	s_add_u32 m0, s28, 0x8000
	v_mfma_f32_32x32x16_bf16 v[68:83], v[84:87], v[144:147], v[68:83]
	global_load_lds_dwordx4 v172, s[8:9]
	ds_read_b64_tr_b16 v[140:141], v230 offset:40960
	ds_read_b64_tr_b16 v[142:143], v230 offset:43008
	v_cvt_pk_bf16_f32 v188, v188, v189
	v_exp_f32_e32 v194, v194
	v_cvt_pk_bf16_f32 v189, v190, v191
	s_waitcnt lgkmcnt(12)
	v_mfma_f32_32x32x16_bf16 v[20:35], v[88:91], v[220:223], v[20:35]
	ds_read_b64_tr_b16 v[144:145], v231 offset:40960
	ds_read_b64_tr_b16 v[146:147], v231 offset:43008
	v_exp_f32_e32 v195, v195
	v_add_f32_e32 v252, v252, v192
	v_add_f32_e32 v253, v253, v193
	v_cvt_pk_bf16_f32 v190, v192, v193
	s_waitcnt lgkmcnt(12)
	v_mfma_f32_32x32x16_bf16 v[36:51], v[88:91], v[224:227], v[36:51]
	ds_read_b64_tr_b16 v[220:221], v228 offset:45056
	ds_read_b64_tr_b16 v[222:223], v228 offset:47104
	v_add_f32_e32 v252, v252, v194
	v_add_f32_e32 v253, v253, v195
	v_cvt_pk_bf16_f32 v191, v194, v195
	v_exp_f32_e32 v196, v196
	s_waitcnt lgkmcnt(12)
	v_mfma_f32_32x32x16_bf16 v[52:67], v[88:91], v[232:235], v[52:67]
	ds_read_b64_tr_b16 v[224:225], v229 offset:45056
	ds_read_b64_tr_b16 v[226:227], v229 offset:47104
	v_exp_f32_e32 v197, v197
	v_exp_f32_e32 v198, v198
	s_waitcnt lgkmcnt(12)
	s_add_u32 m0, s29, 0x4000
	v_mfma_f32_32x32x16_bf16 v[68:83], v[88:91], v[236:239], v[68:83]
	global_load_lds_dwordx4 v174, s[8:9]
	ds_read_b64_tr_b16 v[232:233], v230 offset:45056
	ds_read_b64_tr_b16 v[234:235], v230 offset:47104
	v_add_f32_e32 v252, v252, v196
	v_exp_f32_e32 v199, v199
	v_add_f32_e32 v253, v253, v197
	s_waitcnt lgkmcnt(12)
	v_mfma_f32_32x32x16_bf16 v[20:35], v[100:103], v[132:135], v[20:35]
	ds_read_b64_tr_b16 v[236:237], v231 offset:45056
	ds_read_b64_tr_b16 v[238:239], v231 offset:47104
	v_exp_f32_e32 v200, v200
	v_add_f32_e32 v252, v252, v198
	v_exp_f32_e32 v201, v201
	s_waitcnt lgkmcnt(12)
	v_mfma_f32_32x32x16_bf16 v[36:51], v[100:103], v[136:139], v[36:51]
	ds_read_b128 v[132:135], v19
	v_add_f32_e32 v253, v253, v199
	v_exp_f32_e32 v202, v202
	v_cvt_pk_bf16_f32 v192, v196, v197
	s_waitcnt lgkmcnt(11)
	v_mfma_f32_32x32x16_bf16 v[52:67], v[100:103], v[140:143], v[52:67]
	ds_read_b128 v[136:139], v19 offset:8192
	v_exp_f32_e32 v203, v203
	v_cvt_pk_bf16_f32 v193, v198, v199
	v_add_f32_e32 v252, v252, v200
	v_add_f32_e32 v253, v253, v201
	s_waitcnt lgkmcnt(10)
	s_add_u32 m0, s28, 0xa000
	v_mfma_f32_32x32x16_bf16 v[68:83], v[100:103], v[144:147], v[68:83]
	global_load_lds_dwordx4 v173, s[8:9]
	ds_read_b128 v[140:143], v180
	v_cvt_pk_bf16_f32 v194, v200, v201
	v_add_f32_e32 v252, v252, v202
	v_add_f32_e32 v253, v253, v203
	v_cvt_pk_bf16_f32 v195, v202, v203
	s_waitcnt lgkmcnt(9)
	v_mfma_f32_32x32x16_bf16 v[20:35], v[104:107], v[220:223], v[20:35]
	ds_read_b128 v[144:147], v180 offset:8192
	v_exp_f32_e32 v204, v204
	v_exp_f32_e32 v205, v205
	v_exp_f32_e32 v206, v206
	s_waitcnt lgkmcnt(8)
	v_mfma_f32_32x32x16_bf16 v[36:51], v[104:107], v[224:227], v[36:51]
	ds_read_b128 v[220:223], v181
	v_add_f32_e32 v252, v252, v204
	v_exp_f32_e32 v207, v207
	v_add_f32_e32 v253, v253, v205
	s_waitcnt lgkmcnt(7)
	v_mfma_f32_32x32x16_bf16 v[52:67], v[104:107], v[232:235], v[52:67]
	ds_read_b128 v[224:227], v181 offset:8192
	v_exp_f32_e32 v208, v208
	v_add_f32_e32 v252, v252, v206
	v_exp_f32_e32 v209, v209
	s_waitcnt lgkmcnt(6)
	s_add_u32 m0, s29, 0x6000
	v_mfma_f32_32x32x16_bf16 v[68:83], v[104:107], v[236:239], v[68:83]
	global_load_lds_dwordx4 v175, s[8:9]
	ds_read_b128 v[232:235], v182
	v_add_f32_e32 v253, v253, v207
	v_exp_f32_e32 v210, v210
	v_cvt_pk_bf16_f32 v204, v204, v205
	s_waitcnt lgkmcnt(6)
	v_mfma_f32_32x32x16_bf16 v[84:99], v[132:135], v[116:119], v[2:17]
	ds_read_b128 v[236:239], v182 offset:8192
	v_exp_f32_e32 v211, v211
	v_cvt_pk_bf16_f32 v205, v206, v207
	v_add_f32_e32 v252, v252, v208
	v_add_f32_e32 v253, v253, v209
	s_waitcnt lgkmcnt(6)
	v_mfma_f32_32x32x16_bf16 v[100:115], v[136:139], v[116:119], v[2:17]
	ds_read_b64_tr_b16 v[132:133], v168 offset:0
	ds_read_b64_tr_b16 v[134:135], v168 offset:2048
	v_cvt_pk_bf16_f32 v206, v208, v209
	v_add_f32_e32 v252, v252, v210
	v_add_f32_e32 v253, v253, v211
	v_cvt_pk_bf16_f32 v207, v210, v211
	s_waitcnt lgkmcnt(7)
	v_mfma_f32_32x32x16_bf16 v[84:99], v[140:143], v[120:123], v[84:99]
	ds_read_b64_tr_b16 v[136:137], v169 offset:0
	ds_read_b64_tr_b16 v[138:139], v169 offset:2048
	v_exp_f32_e32 v212, v212
	v_exp_f32_e32 v213, v213
	s_waitcnt lgkmcnt(8)
	v_mfma_f32_32x32x16_bf16 v[100:115], v[144:147], v[120:123], v[100:115]
	ds_read_b64_tr_b16 v[140:141], v170 offset:0
	ds_read_b64_tr_b16 v[142:143], v170 offset:2048
	v_exp_f32_e32 v214, v214
	v_add_f32_e32 v252, v252, v212
	v_exp_f32_e32 v215, v215
	v_add_f32_e32 v253, v253, v213
	s_waitcnt lgkmcnt(9)
	v_mfma_f32_32x32x16_bf16 v[84:99], v[220:223], v[124:127], v[84:99]
	ds_read_b64_tr_b16 v[144:145], v171 offset:0
	ds_read_b64_tr_b16 v[146:147], v171 offset:2048
	v_exp_f32_e32 v216, v216
	v_add_f32_e32 v252, v252, v214
	s_waitcnt lgkmcnt(10)
	v_mfma_f32_32x32x16_bf16 v[100:115], v[224:227], v[124:127], v[100:115]
	ds_read_b64_tr_b16 v[220:221], v168 offset:4096
	ds_read_b64_tr_b16 v[222:223], v168 offset:6144
	v_exp_f32_e32 v217, v217
	v_add_f32_e32 v253, v253, v215
	v_exp_f32_e32 v218, v218
	v_cvt_pk_bf16_f32 v208, v212, v213
	s_waitcnt lgkmcnt(11)
	v_mfma_f32_32x32x16_bf16 v[84:99], v[232:235], v[128:131], v[84:99]
	ds_read_b64_tr_b16 v[224:225], v169 offset:4096
	ds_read_b64_tr_b16 v[226:227], v169 offset:6144
	v_exp_f32_e32 v219, v219
	v_cvt_pk_bf16_f32 v209, v214, v215
	v_add_f32_e32 v252, v252, v216
	s_waitcnt lgkmcnt(12)
	v_mfma_f32_32x32x16_bf16 v[100:115], v[236:239], v[128:131], v[100:115]
	ds_read_b64_tr_b16 v[232:233], v170 offset:4096
	ds_read_b64_tr_b16 v[234:235], v170 offset:6144
	v_add_f32_e32 v253, v253, v217
	v_cvt_pk_bf16_f32 v210, v216, v217
	v_add_f32_e32 v252, v252, v218
	v_add_f32_e32 v253, v253, v219
	v_cvt_pk_bf16_f32 v211, v218, v219
	v_max_f32_e32 v251, v252, v253
	v_cmp_nge_f32_e32 vcc, 0x45800000, v251
	s_cbranch_vccnz .LatA_recs_h3

; #define LAS __attribute__((address_space(3)))
; #define VREADS1(arr, d_) do { const unsigned ad_ = vbase ^ (unsigned)((d_) << 6); __builtin_amdgcn_sched_barrier(0); \
;         _Pragma("unroll") for (int ks_ = 0; ks_ < 4; ++ks_) { VTR(arr[ks_ * 2], ad_, ks_ * 4096); VTR(arr[ks_ * 2 + 1], ad_, ks_ * 4096 + 2048); } __builtin_amdgcn_sched_barrier(0); } while (0)
; #define PV1(arr, d_) do { _Pragma("unroll") for (int ks_ = 0; ks_ < 4; ++ks_) { const s16x4 lo_ = arr[ks_ * 2], hh_ = arr[ks_ * 2 + 1]; \
;         const bf16x8 bv_ = (bf16x8){lo_[0], lo_[1], lo_[2], lo_[3], hh_[0], hh_[1], hh_[2], hh_[3]}; \
;         O[d_] = __builtin_amdgcn_mfma_f32_32x32x16_bf16(pa[ks_], bv_, O[d_], 0, 0, 0); } __builtin_amdgcn_sched_barrier(0); } while (0)
; #define LGKM0() do { __builtin_amdgcn_sched_barrier(0); asm volatile("s_waitcnt lgkmcnt(0)" ::: "memory"); __builtin_amdgcn_sched_barrier(0); } while (0)
; __device__ __forceinline__ void attn_unit(LAS unsigned char* lds, const bf16_t* Z, bf16_t* A2, const float* tabg, int seq_base, int S, int h, int qb, float lam) {
;     ...
;             for (int ds = 0; ds < 4; ++ds) { kf[2 * ds] = *(const LAS bf16x8*)(Kt + (kfo ^ (unsigned)(ds << 5))); kf[2 * ds + 1] = *(const LAS bf16x8*)(Kt + 32 * 256 + (kfo ^ (unsigned)(ds << 5))); }
;             __builtin_amdgcn_sched_barrier(0);
;             p0 = __builtin_amdgcn_mfma_f32_32x32x16_bf16(kf[0], qf[0], cblk, 0, 0, 0);
;             p1 = __builtin_amdgcn_mfma_f32_32x32x16_bf16(kf[1], qf[0], cblk, 0, 0, 0);
; #pragma unroll
;             for (int ds = 1; ds < 4; ++ds) {
;                 p0 = __builtin_amdgcn_mfma_f32_32x32x16_bf16(kf[2 * ds], qf[ds], p0, 0, 0, 0);
;                 p1 = __builtin_amdgcn_mfma_f32_32x32x16_bf16(kf[2 * ds + 1], qf[ds], p1, 0, 0, 0);
;             }
;     ...
; #pragma unroll
;         for (int r = 0; r < 16; ++r) { p0[r] = __builtin_amdgcn_exp2f(p0[r]); p1[r] = __builtin_amdgcn_exp2f(p1[r]); }
; #pragma unroll
;         for (int r = 0; r < 16; r += 2) { ls2 += (f32x2){p0[r], p0[r + 1]}; ls2 += (f32x2){p1[r], p1[r + 1]}; }
;         bf16x8 pa[4]; pa[0] = pack8(p0, 0); pa[1] = pack8(p0, 8); pa[2] = pack8(p1, 0); pa[3] = pack8(p1, 8);
;         LGKM0(); VREADS1(vb, 1); PV1(va, 0); LGKM0(); VREADS1(va, 2); PV1(vb, 1); LGKM0(); VREADS1(vb, 3); PV1(va, 2); LGKM0(); PV1(vb, 3);
.LatA_evret_m0:
	s_waitcnt lgkmcnt(12)
	v_mfma_f32_32x32x16_bf16 v[20:35], v[188:191], v[132:135], v[20:35]
	ds_read_b64_tr_b16 v[236:237], v171 offset:4096
	ds_read_b64_tr_b16 v[238:239], v171 offset:6144
	v_exp_f32_e32 v84, v84
	v_exp_f32_e32 v85, v85
	s_waitcnt lgkmcnt(12)
	v_mfma_f32_32x32x16_bf16 v[36:51], v[188:191], v[136:139], v[36:51]
	ds_read_b64_tr_b16 v[132:133], v168 offset:8192
	ds_read_b64_tr_b16 v[134:135], v168 offset:10240
	v_exp_f32_e32 v86, v86
	v_exp_f32_e32 v87, v87
	v_add_f32_e32 v252, v84, v86
	s_waitcnt lgkmcnt(12)
	v_mfma_f32_32x32x16_bf16 v[52:67], v[188:191], v[140:143], v[52:67]
	ds_read_b64_tr_b16 v[136:137], v169 offset:8192
	ds_read_b64_tr_b16 v[138:139], v169 offset:10240
	v_exp_f32_e32 v88, v88
	v_add_f32_e32 v253, v85, v87
	v_exp_f32_e32 v89, v89
	s_waitcnt lgkmcnt(12)
	s_add_u32 m0, s28, 0x1d000
	v_mfma_f32_32x32x16_bf16 v[68:83], v[188:191], v[144:147], v[68:83]
	global_load_lds_dwordx4 v172, s[8:9]
	ds_read_b64_tr_b16 v[140:141], v170 offset:8192
	ds_read_b64_tr_b16 v[142:143], v170 offset:10240
	v_cvt_pk_bf16_f32 v84, v84, v85
	v_exp_f32_e32 v90, v90
	v_cvt_pk_bf16_f32 v85, v86, v87
	s_waitcnt lgkmcnt(12)
	v_mfma_f32_32x32x16_bf16 v[20:35], v[192:195], v[220:223], v[20:35]
	ds_read_b64_tr_b16 v[144:145], v171 offset:8192
	ds_read_b64_tr_b16 v[146:147], v171 offset:10240
	v_exp_f32_e32 v91, v91
	v_add_f32_e32 v252, v252, v88
	v_add_f32_e32 v253, v253, v89
	v_cvt_pk_bf16_f32 v86, v88, v89
	s_waitcnt lgkmcnt(12)
	v_mfma_f32_32x32x16_bf16 v[36:51], v[192:195], v[224:227], v[36:51]
	ds_read_b64_tr_b16 v[220:221], v168 offset:12288
	ds_read_b64_tr_b16 v[222:223], v168 offset:14336
	v_add_f32_e32 v252, v252, v90
	v_add_f32_e32 v253, v253, v91
	v_cvt_pk_bf16_f32 v87, v90, v91
	v_exp_f32_e32 v92, v92
	s_waitcnt lgkmcnt(12)
	v_mfma_f32_32x32x16_bf16 v[52:67], v[192:195], v[232:235], v[52:67]
	ds_read_b64_tr_b16 v[224:225], v169 offset:12288
	ds_read_b64_tr_b16 v[226:227], v169 offset:14336
	v_exp_f32_e32 v93, v93
	v_exp_f32_e32 v94, v94
	s_waitcnt lgkmcnt(12)
	s_add_u32 m0, s29, 0x8000
	v_mfma_f32_32x32x16_bf16 v[68:83], v[192:195], v[236:239], v[68:83]
	global_load_lds_dwordx4 v174, s[8:9]
	ds_read_b64_tr_b16 v[232:233], v170 offset:12288
	ds_read_b64_tr_b16 v[234:235], v170 offset:14336
	v_add_f32_e32 v252, v252, v92
	v_exp_f32_e32 v95, v95
	v_add_f32_e32 v253, v253, v93
	s_waitcnt lgkmcnt(12)
	v_mfma_f32_32x32x16_bf16 v[20:35], v[204:207], v[132:135], v[20:35]
	ds_read_b64_tr_b16 v[236:237], v171 offset:12288
	ds_read_b64_tr_b16 v[238:239], v171 offset:14336
	v_exp_f32_e32 v96, v96
	v_add_f32_e32 v252, v252, v94
	v_exp_f32_e32 v97, v97
	s_waitcnt lgkmcnt(12)
	v_mfma_f32_32x32x16_bf16 v[36:51], v[204:207], v[136:139], v[36:51]
	ds_read_b128 v[132:135], v19 offset:16384
	v_add_f32_e32 v253, v253, v95
	v_exp_f32_e32 v98, v98
	v_cvt_pk_bf16_f32 v88, v92, v93
	s_waitcnt lgkmcnt(11)
	v_mfma_f32_32x32x16_bf16 v[52:67], v[204:207], v[140:143], v[52:67]
	ds_read_b128 v[136:139], v19 offset:24576
	v_exp_f32_e32 v99, v99
	v_cvt_pk_bf16_f32 v89, v94, v95
	v_add_f32_e32 v252, v252, v96
	v_add_f32_e32 v253, v253, v97
	s_waitcnt lgkmcnt(10)
	s_add_u32 m0, s28, 0x1f000
	v_mfma_f32_32x32x16_bf16 v[68:83], v[204:207], v[144:147], v[68:83]
	global_load_lds_dwordx4 v173, s[8:9]
	ds_read_b128 v[140:143], v180 offset:16384
	v_cvt_pk_bf16_f32 v90, v96, v97
	v_add_f32_e32 v252, v252, v98
	v_add_f32_e32 v253, v253, v99
	v_cvt_pk_bf16_f32 v91, v98, v99
	s_waitcnt lgkmcnt(9)
	v_mfma_f32_32x32x16_bf16 v[20:35], v[208:211], v[220:223], v[20:35]
	ds_read_b128 v[144:147], v180 offset:24576
	v_exp_f32_e32 v100, v100
	v_exp_f32_e32 v101, v101
	v_exp_f32_e32 v102, v102
	s_waitcnt lgkmcnt(8)
	v_mfma_f32_32x32x16_bf16 v[36:51], v[208:211], v[224:227], v[36:51]
	ds_read_b128 v[220:223], v181 offset:16384
	v_add_f32_e32 v252, v252, v100
	v_exp_f32_e32 v103, v103
	v_add_f32_e32 v253, v253, v101
	s_waitcnt lgkmcnt(7)
	v_mfma_f32_32x32x16_bf16 v[52:67], v[208:211], v[232:235], v[52:67]
	ds_read_b128 v[224:227], v181 offset:24576
	v_exp_f32_e32 v104, v104
	v_add_f32_e32 v252, v252, v102
	v_exp_f32_e32 v105, v105
	s_waitcnt lgkmcnt(6)
	s_add_u32 m0, s29, 0xa000
	v_mfma_f32_32x32x16_bf16 v[68:83], v[208:211], v[236:239], v[68:83]
	global_load_lds_dwordx4 v175, s[8:9]
	ds_read_b128 v[232:235], v182 offset:16384
	v_add_f32_e32 v253, v253, v103
	v_exp_f32_e32 v106, v106
	v_cvt_pk_bf16_f32 v100, v100, v101
	s_waitcnt lgkmcnt(6)
	v_mfma_f32_32x32x16_bf16 v[188:203], v[132:135], v[116:119], v[2:17]
	ds_read_b128 v[236:239], v182 offset:24576
	v_exp_f32_e32 v107, v107
	v_cvt_pk_bf16_f32 v101, v102, v103
	v_add_f32_e32 v252, v252, v104
	v_add_f32_e32 v253, v253, v105
	s_waitcnt lgkmcnt(6)
	v_mfma_f32_32x32x16_bf16 v[204:219], v[136:139], v[116:119], v[2:17]
	ds_read_b64_tr_b16 v[132:133], v228 offset:0
	ds_read_b64_tr_b16 v[134:135], v228 offset:2048
	v_cvt_pk_bf16_f32 v102, v104, v105
	v_add_f32_e32 v252, v252, v106
	v_add_f32_e32 v253, v253, v107
	v_cvt_pk_bf16_f32 v103, v106, v107
	s_waitcnt lgkmcnt(7)
	v_mfma_f32_32x32x16_bf16 v[188:203], v[140:143], v[120:123], v[188:203]
	ds_read_b64_tr_b16 v[136:137], v229 offset:0
	ds_read_b64_tr_b16 v[138:139], v229 offset:2048
	v_exp_f32_e32 v108, v108
	v_exp_f32_e32 v109, v109
	s_waitcnt lgkmcnt(8)
	v_mfma_f32_32x32x16_bf16 v[204:219], v[144:147], v[120:123], v[204:219]
	ds_read_b64_tr_b16 v[140:141], v230 offset:0
	ds_read_b64_tr_b16 v[142:143], v230 offset:2048
	v_exp_f32_e32 v110, v110
	v_add_f32_e32 v252, v252, v108
	v_exp_f32_e32 v111, v111
	v_add_f32_e32 v253, v253, v109
	s_waitcnt lgkmcnt(9)
	v_mfma_f32_32x32x16_bf16 v[188:203], v[220:223], v[124:127], v[188:203]
	ds_read_b64_tr_b16 v[144:145], v231 offset:0
	ds_read_b64_tr_b16 v[146:147], v231 offset:2048
	v_exp_f32_e32 v112, v112
	v_add_f32_e32 v252, v252, v110
	s_waitcnt lgkmcnt(10)
	v_mfma_f32_32x32x16_bf16 v[204:219], v[224:227], v[124:127], v[204:219]
	ds_read_b64_tr_b16 v[220:221], v228 offset:4096
	ds_read_b64_tr_b16 v[222:223], v228 offset:6144
	v_exp_f32_e32 v113, v113
	v_add_f32_e32 v253, v253, v111
	v_exp_f32_e32 v114, v114
	v_cvt_pk_bf16_f32 v104, v108, v109
	s_waitcnt lgkmcnt(11)
	v_mfma_f32_32x32x16_bf16 v[188:203], v[232:235], v[128:131], v[188:203]
	ds_read_b64_tr_b16 v[224:225], v229 offset:4096
	ds_read_b64_tr_b16 v[226:227], v229 offset:6144
	v_exp_f32_e32 v115, v115
	v_cvt_pk_bf16_f32 v105, v110, v111
	v_add_f32_e32 v252, v252, v112
	s_waitcnt lgkmcnt(12)
	v_mfma_f32_32x32x16_bf16 v[204:219], v[236:239], v[128:131], v[204:219]
	ds_read_b64_tr_b16 v[232:233], v230 offset:4096
	ds_read_b64_tr_b16 v[234:235], v230 offset:6144
	v_add_f32_e32 v253, v253, v113
	v_cvt_pk_bf16_f32 v106, v112, v113
	v_add_f32_e32 v252, v252, v114
	v_add_f32_e32 v253, v253, v115
	v_cvt_pk_bf16_f32 v107, v114, v115
	v_max_f32_e32 v251, v252, v253
	v_cmp_nge_f32_e32 vcc, 0x45800000, v251
	s_cbranch_vccnz .LatA_recs_m0

; #define LAS __attribute__((address_space(3)))
; #define VREADS1(arr, d_) do { const unsigned ad_ = vbase ^ (unsigned)((d_) << 6); __builtin_amdgcn_sched_barrier(0); \
;         _Pragma("unroll") for (int ks_ = 0; ks_ < 4; ++ks_) { VTR(arr[ks_ * 2], ad_, ks_ * 4096); VTR(arr[ks_ * 2 + 1], ad_, ks_ * 4096 + 2048); } __builtin_amdgcn_sched_barrier(0); } while (0)
; #define PV1(arr, d_) do { _Pragma("unroll") for (int ks_ = 0; ks_ < 4; ++ks_) { const s16x4 lo_ = arr[ks_ * 2], hh_ = arr[ks_ * 2 + 1]; \
;         const bf16x8 bv_ = (bf16x8){lo_[0], lo_[1], lo_[2], lo_[3], hh_[0], hh_[1], hh_[2], hh_[3]}; \
;         O[d_] = __builtin_amdgcn_mfma_f32_32x32x16_bf16(pa[ks_], bv_, O[d_], 0, 0, 0); } __builtin_amdgcn_sched_barrier(0); } while (0)
; #define LGKM0() do { __builtin_amdgcn_sched_barrier(0); asm volatile("s_waitcnt lgkmcnt(0)" ::: "memory"); __builtin_amdgcn_sched_barrier(0); } while (0)
; __device__ __forceinline__ void attn_unit(LAS unsigned char* lds, const bf16_t* Z, bf16_t* A2, const float* tabg, int seq_base, int S, int h, int qb, float lam) {
;     ...
;             for (int ds = 0; ds < 4; ++ds) { kf[2 * ds] = *(const LAS bf16x8*)(Kt + (kfo ^ (unsigned)(ds << 5))); kf[2 * ds + 1] = *(const LAS bf16x8*)(Kt + 32 * 256 + (kfo ^ (unsigned)(ds << 5))); }
;             __builtin_amdgcn_sched_barrier(0);
;             p0 = __builtin_amdgcn_mfma_f32_32x32x16_bf16(kf[0], qf[0], cblk, 0, 0, 0);
;             p1 = __builtin_amdgcn_mfma_f32_32x32x16_bf16(kf[1], qf[0], cblk, 0, 0, 0);
; #pragma unroll
;             for (int ds = 1; ds < 4; ++ds) {
;                 p0 = __builtin_amdgcn_mfma_f32_32x32x16_bf16(kf[2 * ds], qf[ds], p0, 0, 0, 0);
;                 p1 = __builtin_amdgcn_mfma_f32_32x32x16_bf16(kf[2 * ds + 1], qf[ds], p1, 0, 0, 0);
;             }
;     ...
; #pragma unroll
;         for (int r = 0; r < 16; ++r) { p0[r] = __builtin_amdgcn_exp2f(p0[r]); p1[r] = __builtin_amdgcn_exp2f(p1[r]); }
; #pragma unroll
;         for (int r = 0; r < 16; r += 2) { ls2 += (f32x2){p0[r], p0[r + 1]}; ls2 += (f32x2){p1[r], p1[r + 1]}; }
;         bf16x8 pa[4]; pa[0] = pack8(p0, 0); pa[1] = pack8(p0, 8); pa[2] = pack8(p1, 0); pa[3] = pack8(p1, 8);
;         LGKM0(); VREADS1(vb, 1); PV1(va, 0); LGKM0(); VREADS1(va, 2); PV1(vb, 1); LGKM0(); VREADS1(vb, 3); PV1(va, 2); LGKM0(); PV1(vb, 3);
.LatA_evret_x3:
	s_waitcnt lgkmcnt(12)
	v_mfma_f32_32x32x16_bf16 v[20:35], v[84:87], v[132:135], v[20:35]
	ds_read_b64_tr_b16 v[236:237], v231 offset:4096
	ds_read_b64_tr_b16 v[238:239], v231 offset:6144
	v_exp_f32_e32 v188, v188
	v_exp_f32_e32 v189, v189
	s_waitcnt lgkmcnt(12)
	v_mfma_f32_32x32x16_bf16 v[36:51], v[84:87], v[136:139], v[36:51]
	ds_read_b64_tr_b16 v[132:133], v228 offset:8192
	ds_read_b64_tr_b16 v[134:135], v228 offset:10240
	v_exp_f32_e32 v190, v190
	v_exp_f32_e32 v191, v191
	v_add_f32_e32 v252, v188, v190
	s_waitcnt lgkmcnt(12)
	v_mfma_f32_32x32x16_bf16 v[52:67], v[84:87], v[140:143], v[52:67]
	ds_read_b64_tr_b16 v[136:137], v229 offset:8192
	ds_read_b64_tr_b16 v[138:139], v229 offset:10240
	v_exp_f32_e32 v192, v192
	v_add_f32_e32 v253, v189, v191
	v_exp_f32_e32 v193, v193
	s_waitcnt lgkmcnt(12)
	v_mfma_f32_32x32x16_bf16 v[68:83], v[84:87], v[144:147], v[68:83]
	ds_read_b64_tr_b16 v[140:141], v230 offset:8192
	ds_read_b64_tr_b16 v[142:143], v230 offset:10240
	v_cvt_pk_bf16_f32 v188, v188, v189
	v_exp_f32_e32 v194, v194
	v_cvt_pk_bf16_f32 v189, v190, v191
	s_waitcnt lgkmcnt(12)
	v_mfma_f32_32x32x16_bf16 v[20:35], v[88:91], v[220:223], v[20:35]
	ds_read_b64_tr_b16 v[144:145], v231 offset:8192
	ds_read_b64_tr_b16 v[146:147], v231 offset:10240
	v_exp_f32_e32 v195, v195
	v_add_f32_e32 v252, v252, v192
	v_add_f32_e32 v253, v253, v193
	v_cvt_pk_bf16_f32 v190, v192, v193
	s_waitcnt lgkmcnt(12)
	v_mfma_f32_32x32x16_bf16 v[36:51], v[88:91], v[224:227], v[36:51]
	ds_read_b64_tr_b16 v[220:221], v228 offset:12288
	ds_read_b64_tr_b16 v[222:223], v228 offset:14336
	v_add_f32_e32 v252, v252, v194
	v_add_f32_e32 v253, v253, v195
	v_cvt_pk_bf16_f32 v191, v194, v195
	v_exp_f32_e32 v196, v196
	s_waitcnt lgkmcnt(12)
	v_mfma_f32_32x32x16_bf16 v[52:67], v[88:91], v[232:235], v[52:67]
	ds_read_b64_tr_b16 v[224:225], v229 offset:12288
	ds_read_b64_tr_b16 v[226:227], v229 offset:14336
	v_exp_f32_e32 v197, v197
	v_exp_f32_e32 v198, v198
	s_waitcnt lgkmcnt(12)
	s_add_u32 m0, s29, 0xd000
	v_mfma_f32_32x32x16_bf16 v[68:83], v[88:91], v[236:239], v[68:83]
	global_load_lds_dwordx4 v174, s[8:9]
	ds_read_b64_tr_b16 v[232:233], v230 offset:12288
	ds_read_b64_tr_b16 v[234:235], v230 offset:14336
	v_add_f32_e32 v252, v252, v196
	v_exp_f32_e32 v199, v199
	v_add_f32_e32 v253, v253, v197
	s_waitcnt lgkmcnt(12)
	v_mfma_f32_32x32x16_bf16 v[20:35], v[100:103], v[132:135], v[20:35]
	ds_read_b64_tr_b16 v[236:237], v231 offset:12288
	ds_read_b64_tr_b16 v[238:239], v231 offset:14336
	v_exp_f32_e32 v200, v200
	v_add_f32_e32 v252, v252, v198
	v_exp_f32_e32 v201, v201
	s_waitcnt lgkmcnt(12)
	v_mfma_f32_32x32x16_bf16 v[36:51], v[100:103], v[136:139], v[36:51]
	ds_read_b128 v[132:135], v19 offset:32768
	v_add_f32_e32 v253, v253, v199
	v_exp_f32_e32 v202, v202
	v_cvt_pk_bf16_f32 v192, v196, v197
	s_waitcnt lgkmcnt(11)
	v_mfma_f32_32x32x16_bf16 v[52:67], v[100:103], v[140:143], v[52:67]
	ds_read_b128 v[136:139], v19 offset:40960
	v_exp_f32_e32 v203, v203
	v_cvt_pk_bf16_f32 v193, v198, v199
	v_add_f32_e32 v252, v252, v200
	v_add_f32_e32 v253, v253, v201
	s_waitcnt lgkmcnt(10)
	v_mfma_f32_32x32x16_bf16 v[68:83], v[100:103], v[144:147], v[68:83]
	ds_read_b128 v[140:143], v180 offset:32768
	v_cvt_pk_bf16_f32 v194, v200, v201
	v_add_f32_e32 v252, v252, v202
	v_add_f32_e32 v253, v253, v203
	v_cvt_pk_bf16_f32 v195, v202, v203
	s_waitcnt lgkmcnt(9)
	v_mfma_f32_32x32x16_bf16 v[20:35], v[104:107], v[220:223], v[20:35]
	ds_read_b128 v[144:147], v180 offset:40960
	v_exp_f32_e32 v204, v204
	v_exp_f32_e32 v205, v205
	v_exp_f32_e32 v206, v206
	s_waitcnt lgkmcnt(8)
	v_mfma_f32_32x32x16_bf16 v[36:51], v[104:107], v[224:227], v[36:51]
	ds_read_b128 v[220:223], v181 offset:32768
	v_add_f32_e32 v252, v252, v204
	v_exp_f32_e32 v207, v207
	v_add_f32_e32 v253, v253, v205
	s_waitcnt lgkmcnt(7)
	v_mfma_f32_32x32x16_bf16 v[52:67], v[104:107], v[232:235], v[52:67]
	ds_read_b128 v[224:227], v181 offset:40960
	v_exp_f32_e32 v208, v208
	v_add_f32_e32 v252, v252, v206
	v_exp_f32_e32 v209, v209
	s_waitcnt lgkmcnt(6)
	s_add_u32 m0, s29, 0xf000
	v_mfma_f32_32x32x16_bf16 v[68:83], v[104:107], v[236:239], v[68:83]
	global_load_lds_dwordx4 v175, s[8:9]
	ds_read_b128 v[232:235], v182 offset:32768
	v_add_f32_e32 v253, v253, v207
	v_exp_f32_e32 v210, v210
	v_cvt_pk_bf16_f32 v204, v204, v205
	s_waitcnt lgkmcnt(6)
	v_mfma_f32_32x32x16_bf16 v[84:99], v[132:135], v[116:119], v[2:17]
	ds_read_b128 v[236:239], v182 offset:40960
	v_exp_f32_e32 v211, v211
	v_cvt_pk_bf16_f32 v205, v206, v207
	v_add_f32_e32 v252, v252, v208
	v_add_f32_e32 v253, v253, v209
	s_waitcnt lgkmcnt(6)
	v_mfma_f32_32x32x16_bf16 v[100:115], v[136:139], v[116:119], v[2:17]
	ds_read_b64_tr_b16 v[132:133], v228 offset:16384
	ds_read_b64_tr_b16 v[134:135], v228 offset:18432
	v_cvt_pk_bf16_f32 v206, v208, v209
	v_add_f32_e32 v252, v252, v210
	v_add_f32_e32 v253, v253, v211
	v_cvt_pk_bf16_f32 v207, v210, v211
	s_waitcnt lgkmcnt(7)
	v_mfma_f32_32x32x16_bf16 v[84:99], v[140:143], v[120:123], v[84:99]
	ds_read_b64_tr_b16 v[136:137], v229 offset:16384
	ds_read_b64_tr_b16 v[138:139], v229 offset:18432
	v_exp_f32_e32 v212, v212
	v_exp_f32_e32 v213, v213
	s_waitcnt lgkmcnt(8)
	v_mfma_f32_32x32x16_bf16 v[100:115], v[144:147], v[120:123], v[100:115]
	ds_read_b64_tr_b16 v[140:141], v230 offset:16384
	ds_read_b64_tr_b16 v[142:143], v230 offset:18432
	v_exp_f32_e32 v214, v214
	v_add_f32_e32 v252, v252, v212
	v_exp_f32_e32 v215, v215
	v_add_f32_e32 v253, v253, v213
	s_waitcnt lgkmcnt(9)
	v_mfma_f32_32x32x16_bf16 v[84:99], v[220:223], v[124:127], v[84:99]
	ds_read_b64_tr_b16 v[144:145], v231 offset:16384
	ds_read_b64_tr_b16 v[146:147], v231 offset:18432
	v_exp_f32_e32 v216, v216
	v_add_f32_e32 v252, v252, v214
	s_waitcnt lgkmcnt(10)
	v_mfma_f32_32x32x16_bf16 v[100:115], v[224:227], v[124:127], v[100:115]
	ds_read_b64_tr_b16 v[220:221], v228 offset:20480
	ds_read_b64_tr_b16 v[222:223], v228 offset:22528
	v_exp_f32_e32 v217, v217
	v_add_f32_e32 v253, v253, v215
	v_exp_f32_e32 v218, v218
	v_cvt_pk_bf16_f32 v208, v212, v213
	s_waitcnt lgkmcnt(11)
	v_mfma_f32_32x32x16_bf16 v[84:99], v[232:235], v[128:131], v[84:99]
	ds_read_b64_tr_b16 v[224:225], v229 offset:20480
	ds_read_b64_tr_b16 v[226:227], v229 offset:22528
	v_exp_f32_e32 v219, v219
	v_cvt_pk_bf16_f32 v209, v214, v215
	v_add_f32_e32 v252, v252, v216
	s_waitcnt lgkmcnt(12)
	v_mfma_f32_32x32x16_bf16 v[100:115], v[236:239], v[128:131], v[100:115]
	ds_read_b64_tr_b16 v[232:233], v230 offset:20480
	ds_read_b64_tr_b16 v[234:235], v230 offset:22528
	v_add_f32_e32 v253, v253, v217
	v_cvt_pk_bf16_f32 v210, v216, v217
	v_add_f32_e32 v252, v252, v218
	v_add_f32_e32 v253, v253, v219
	v_cvt_pk_bf16_f32 v211, v218, v219
	v_max_f32_e32 v251, v252, v253
	v_cmp_nge_f32_e32 vcc, 0x45800000, v251
	s_cbranch_vccnz .LatA_recs_x3

; #define LAS __attribute__((address_space(3)))
; #define VREADS1(arr, d_) do { const unsigned ad_ = vbase ^ (unsigned)((d_) << 6); __builtin_amdgcn_sched_barrier(0); \
;         _Pragma("unroll") for (int ks_ = 0; ks_ < 4; ++ks_) { VTR(arr[ks_ * 2], ad_, ks_ * 4096); VTR(arr[ks_ * 2 + 1], ad_, ks_ * 4096 + 2048); } __builtin_amdgcn_sched_barrier(0); } while (0)
; #define PV1(arr, d_) do { _Pragma("unroll") for (int ks_ = 0; ks_ < 4; ++ks_) { const s16x4 lo_ = arr[ks_ * 2], hh_ = arr[ks_ * 2 + 1]; \
;         const bf16x8 bv_ = (bf16x8){lo_[0], lo_[1], lo_[2], lo_[3], hh_[0], hh_[1], hh_[2], hh_[3]}; \
;         O[d_] = __builtin_amdgcn_mfma_f32_32x32x16_bf16(pa[ks_], bv_, O[d_], 0, 0, 0); } __builtin_amdgcn_sched_barrier(0); } while (0)
; #define LGKM0() do { __builtin_amdgcn_sched_barrier(0); asm volatile("s_waitcnt lgkmcnt(0)" ::: "memory"); __builtin_amdgcn_sched_barrier(0); } while (0)
; __device__ __forceinline__ void attn_unit(LAS unsigned char* lds, const bf16_t* Z, bf16_t* A2, const float* tabg, int seq_base, int S, int h, int qb, float lam) {
;     ...
;             for (int ds = 0; ds < 4; ++ds) { kf[2 * ds] = *(const LAS bf16x8*)(Kt + (kfo ^ (unsigned)(ds << 5))); kf[2 * ds + 1] = *(const LAS bf16x8*)(Kt + 32 * 256 + (kfo ^ (unsigned)(ds << 5))); }
;             __builtin_amdgcn_sched_barrier(0);
;             p0 = __builtin_amdgcn_mfma_f32_32x32x16_bf16(kf[0], qf[0], cblk, 0, 0, 0);
;             p1 = __builtin_amdgcn_mfma_f32_32x32x16_bf16(kf[1], qf[0], cblk, 0, 0, 0);
; #pragma unroll
;             for (int ds = 1; ds < 4; ++ds) {
;                 p0 = __builtin_amdgcn_mfma_f32_32x32x16_bf16(kf[2 * ds], qf[ds], p0, 0, 0, 0);
;                 p1 = __builtin_amdgcn_mfma_f32_32x32x16_bf16(kf[2 * ds + 1], qf[ds], p1, 0, 0, 0);
;             }
;     ...
; #pragma unroll
;         for (int r = 0; r < 16; ++r) { p0[r] = __builtin_amdgcn_exp2f(p0[r]); p1[r] = __builtin_amdgcn_exp2f(p1[r]); }
; #pragma unroll
;         for (int r = 0; r < 16; r += 2) { ls2 += (f32x2){p0[r], p0[r + 1]}; ls2 += (f32x2){p1[r], p1[r + 1]}; }
;         bf16x8 pa[4]; pa[0] = pack8(p0, 0); pa[1] = pack8(p0, 8); pa[2] = pack8(p1, 0); pa[3] = pack8(p1, 8);
;         LGKM0(); VREADS1(vb, 1); PV1(va, 0); LGKM0(); VREADS1(va, 2); PV1(vb, 1); LGKM0(); VREADS1(vb, 3); PV1(va, 2); LGKM0(); PV1(vb, 3);
.LatA_evret_x2:
	s_waitcnt lgkmcnt(12)
	v_mfma_f32_32x32x16_bf16 v[20:35], v[188:191], v[132:135], v[20:35]
	ds_read_b64_tr_b16 v[236:237], v231 offset:20480
	ds_read_b64_tr_b16 v[238:239], v231 offset:22528
	v_exp_f32_e32 v84, v84
	v_exp_f32_e32 v85, v85
	s_waitcnt lgkmcnt(12)
	v_mfma_f32_32x32x16_bf16 v[36:51], v[188:191], v[136:139], v[36:51]
	ds_read_b64_tr_b16 v[132:133], v228 offset:24576
	ds_read_b64_tr_b16 v[134:135], v228 offset:26624
	v_exp_f32_e32 v86, v86
	v_exp_f32_e32 v87, v87
	v_add_f32_e32 v252, v84, v86
	s_waitcnt lgkmcnt(12)
	v_mfma_f32_32x32x16_bf16 v[52:67], v[188:191], v[140:143], v[52:67]
	ds_read_b64_tr_b16 v[136:137], v229 offset:24576
	ds_read_b64_tr_b16 v[138:139], v229 offset:26624
	v_exp_f32_e32 v88, v88
	v_add_f32_e32 v253, v85, v87
	v_exp_f32_e32 v89, v89
	s_waitcnt lgkmcnt(12)
	v_mfma_f32_32x32x16_bf16 v[68:83], v[188:191], v[144:147], v[68:83]
	ds_read_b64_tr_b16 v[140:141], v230 offset:24576
	ds_read_b64_tr_b16 v[142:143], v230 offset:26624
	v_cvt_pk_bf16_f32 v84, v84, v85
	v_exp_f32_e32 v90, v90
	v_cvt_pk_bf16_f32 v85, v86, v87
	s_waitcnt lgkmcnt(12)
	v_mfma_f32_32x32x16_bf16 v[20:35], v[192:195], v[220:223], v[20:35]
	ds_read_b64_tr_b16 v[144:145], v231 offset:24576
	ds_read_b64_tr_b16 v[146:147], v231 offset:26624
	v_exp_f32_e32 v91, v91
	v_add_f32_e32 v252, v252, v88
	v_add_f32_e32 v253, v253, v89
	v_cvt_pk_bf16_f32 v86, v88, v89
	s_waitcnt lgkmcnt(12)
	v_mfma_f32_32x32x16_bf16 v[36:51], v[192:195], v[224:227], v[36:51]
	ds_read_b64_tr_b16 v[220:221], v228 offset:28672
	ds_read_b64_tr_b16 v[222:223], v228 offset:30720
	v_add_f32_e32 v252, v252, v90
	v_add_f32_e32 v253, v253, v91
	v_cvt_pk_bf16_f32 v87, v90, v91
	v_exp_f32_e32 v92, v92
	s_waitcnt lgkmcnt(12)
	v_mfma_f32_32x32x16_bf16 v[52:67], v[192:195], v[232:235], v[52:67]
	ds_read_b64_tr_b16 v[224:225], v229 offset:28672
	ds_read_b64_tr_b16 v[226:227], v229 offset:30720
	v_exp_f32_e32 v93, v93
	v_exp_f32_e32 v94, v94
	s_waitcnt lgkmcnt(12)
	v_mfma_f32_32x32x16_bf16 v[68:83], v[192:195], v[236:239], v[68:83]
	ds_read_b64_tr_b16 v[232:233], v230 offset:28672
	ds_read_b64_tr_b16 v[234:235], v230 offset:30720
	v_add_f32_e32 v252, v252, v92
	v_exp_f32_e32 v95, v95
	v_add_f32_e32 v253, v253, v93
	s_waitcnt lgkmcnt(12)
	v_mfma_f32_32x32x16_bf16 v[20:35], v[204:207], v[132:135], v[20:35]
	ds_read_b64_tr_b16 v[236:237], v231 offset:28672
	ds_read_b64_tr_b16 v[238:239], v231 offset:30720
	v_exp_f32_e32 v96, v96
	v_add_f32_e32 v252, v252, v94
	v_exp_f32_e32 v97, v97
	s_waitcnt lgkmcnt(12)
	v_mfma_f32_32x32x16_bf16 v[36:51], v[204:207], v[136:139], v[36:51]
	ds_read_b128 v[132:135], v164
	v_add_f32_e32 v253, v253, v95
	v_exp_f32_e32 v98, v98
	v_cvt_pk_bf16_f32 v88, v92, v93
	s_waitcnt lgkmcnt(11)
	v_mfma_f32_32x32x16_bf16 v[52:67], v[204:207], v[140:143], v[52:67]
	ds_read_b128 v[136:139], v164 offset:8192
	v_exp_f32_e32 v99, v99
	v_cvt_pk_bf16_f32 v89, v94, v95
	v_add_f32_e32 v252, v252, v96
	v_add_f32_e32 v253, v253, v97
	s_waitcnt lgkmcnt(10)
	v_mfma_f32_32x32x16_bf16 v[68:83], v[204:207], v[144:147], v[68:83]
	ds_read_b128 v[140:143], v165
	v_cvt_pk_bf16_f32 v90, v96, v97
	v_add_f32_e32 v252, v252, v98
	v_add_f32_e32 v253, v253, v99
	v_cvt_pk_bf16_f32 v91, v98, v99
	s_waitcnt lgkmcnt(9)
	v_mfma_f32_32x32x16_bf16 v[20:35], v[208:211], v[220:223], v[20:35]
	ds_read_b128 v[144:147], v165 offset:8192
	v_exp_f32_e32 v100, v100
	v_exp_f32_e32 v101, v101
	v_exp_f32_e32 v102, v102
	s_waitcnt lgkmcnt(8)
	v_mfma_f32_32x32x16_bf16 v[36:51], v[208:211], v[224:227], v[36:51]
	ds_read_b128 v[220:223], v166
	v_add_f32_e32 v252, v252, v100
	v_exp_f32_e32 v103, v103
	v_add_f32_e32 v253, v253, v101
	s_waitcnt lgkmcnt(7)
	v_mfma_f32_32x32x16_bf16 v[52:67], v[208:211], v[232:235], v[52:67]
	ds_read_b128 v[224:227], v166 offset:8192
	v_exp_f32_e32 v104, v104
	v_add_f32_e32 v252, v252, v102
	v_exp_f32_e32 v105, v105
	s_waitcnt lgkmcnt(6)
	v_mfma_f32_32x32x16_bf16 v[68:83], v[208:211], v[236:239], v[68:83]
	ds_read_b128 v[232:235], v167
	v_add_f32_e32 v253, v253, v103
	v_exp_f32_e32 v106, v106
	v_cvt_pk_bf16_f32 v100, v100, v101
	s_waitcnt lgkmcnt(6)
	v_mfma_f32_32x32x16_bf16 v[188:203], v[132:135], v[116:119], v[2:17]
	ds_read_b128 v[236:239], v167 offset:8192
	v_exp_f32_e32 v107, v107
	v_cvt_pk_bf16_f32 v101, v102, v103
	v_add_f32_e32 v252, v252, v104
	v_add_f32_e32 v253, v253, v105
	s_waitcnt lgkmcnt(6)
	v_mfma_f32_32x32x16_bf16 v[204:219], v[136:139], v[116:119], v[2:17]
	ds_read_b64_tr_b16 v[132:133], v228 offset:32768
	ds_read_b64_tr_b16 v[134:135], v228 offset:34816
	v_cvt_pk_bf16_f32 v102, v104, v105
	v_add_f32_e32 v252, v252, v106
	v_add_f32_e32 v253, v253, v107
	v_cvt_pk_bf16_f32 v103, v106, v107
	s_waitcnt lgkmcnt(7)
	v_mfma_f32_32x32x16_bf16 v[188:203], v[140:143], v[120:123], v[188:203]
	ds_read_b64_tr_b16 v[136:137], v229 offset:32768
	ds_read_b64_tr_b16 v[138:139], v229 offset:34816
	v_exp_f32_e32 v108, v108
	v_exp_f32_e32 v109, v109
	s_waitcnt lgkmcnt(8)
	v_mfma_f32_32x32x16_bf16 v[204:219], v[144:147], v[120:123], v[204:219]
	ds_read_b64_tr_b16 v[140:141], v230 offset:32768
	ds_read_b64_tr_b16 v[142:143], v230 offset:34816
	v_exp_f32_e32 v110, v110
	v_add_f32_e32 v252, v252, v108
	v_exp_f32_e32 v111, v111
	v_add_f32_e32 v253, v253, v109
	s_waitcnt lgkmcnt(9)
	v_mfma_f32_32x32x16_bf16 v[188:203], v[220:223], v[124:127], v[188:203]
	ds_read_b64_tr_b16 v[144:145], v231 offset:32768
	ds_read_b64_tr_b16 v[146:147], v231 offset:34816
	v_exp_f32_e32 v112, v112
	v_add_f32_e32 v252, v252, v110
	s_waitcnt lgkmcnt(10)
	v_mfma_f32_32x32x16_bf16 v[204:219], v[224:227], v[124:127], v[204:219]
	ds_read_b64_tr_b16 v[220:221], v228 offset:36864
	ds_read_b64_tr_b16 v[222:223], v228 offset:38912
	v_exp_f32_e32 v113, v113
	v_add_f32_e32 v253, v253, v111
	v_exp_f32_e32 v114, v114
	v_cvt_pk_bf16_f32 v104, v108, v109
	s_waitcnt lgkmcnt(11)
	v_mfma_f32_32x32x16_bf16 v[188:203], v[232:235], v[128:131], v[188:203]
	ds_read_b64_tr_b16 v[224:225], v229 offset:36864
	ds_read_b64_tr_b16 v[226:227], v229 offset:38912
	v_exp_f32_e32 v115, v115
	v_cvt_pk_bf16_f32 v105, v110, v111
	v_add_f32_e32 v252, v252, v112
	s_waitcnt lgkmcnt(12)
	v_mfma_f32_32x32x16_bf16 v[204:219], v[236:239], v[128:131], v[204:219]
	ds_read_b64_tr_b16 v[232:233], v230 offset:36864
	ds_read_b64_tr_b16 v[234:235], v230 offset:38912
	v_add_f32_e32 v253, v253, v113
	v_cvt_pk_bf16_f32 v106, v112, v113
	v_add_f32_e32 v252, v252, v114
	v_add_f32_e32 v253, v253, v115
	v_cvt_pk_bf16_f32 v107, v114, v115
	v_max_f32_e32 v251, v252, v253
	v_cmp_nge_f32_e32 vcc, 0x45800000, v251
	s_cbranch_vccnz .LatA_recs_x2

; #define VREADS1(arr, d_) do { const unsigned ad_ = vbase ^ (unsigned)((d_) << 6); __builtin_amdgcn_sched_barrier(0); \
;         _Pragma("unroll") for (int ks_ = 0; ks_ < 4; ++ks_) { VTR(arr[ks_ * 2], ad_, ks_ * 4096); VTR(arr[ks_ * 2 + 1], ad_, ks_ * 4096 + 2048); } __builtin_amdgcn_sched_barrier(0); } while (0)
; #define PV1(arr, d_) do { _Pragma("unroll") for (int ks_ = 0; ks_ < 4; ++ks_) { const s16x4 lo_ = arr[ks_ * 2], hh_ = arr[ks_ * 2 + 1]; \
;         const bf16x8 bv_ = (bf16x8){lo_[0], lo_[1], lo_[2], lo_[3], hh_[0], hh_[1], hh_[2], hh_[3]}; \
;         O[d_] = __builtin_amdgcn_mfma_f32_32x32x16_bf16(pa[ks_], bv_, O[d_], 0, 0, 0); } __builtin_amdgcn_sched_barrier(0); } while (0)
; #define LGKM0() do { __builtin_amdgcn_sched_barrier(0); asm volatile("s_waitcnt lgkmcnt(0)" ::: "memory"); __builtin_amdgcn_sched_barrier(0); } while (0)
; __device__ __forceinline__ void attn_unit(LAS unsigned char* lds, const bf16_t* Z, bf16_t* A2, const float* tabg, int seq_base, int S, int h, int qb, float lam) {
;     ...
; #pragma unroll
;         for (int r = 0; r < 16; ++r) { p0[r] = __builtin_amdgcn_exp2f(p0[r]); p1[r] = __builtin_amdgcn_exp2f(p1[r]); }
; #pragma unroll
;         for (int r = 0; r < 16; r += 2) { ls2 += (f32x2){p0[r], p0[r + 1]}; ls2 += (f32x2){p1[r], p1[r + 1]}; }
;         bf16x8 pa[4]; pa[0] = pack8(p0, 0); pa[1] = pack8(p0, 8); pa[2] = pack8(p1, 0); pa[3] = pack8(p1, 8);
;         LGKM0(); VREADS1(vb, 1); PV1(va, 0); LGKM0(); VREADS1(va, 2); PV1(vb, 1); LGKM0(); VREADS1(vb, 3); PV1(va, 2); LGKM0(); PV1(vb, 3);
.LatA_evret_x1:
	s_waitcnt lgkmcnt(12)
	v_mfma_f32_32x32x16_bf16 v[20:35], v[84:87], v[132:135], v[20:35]
	ds_read_b64_tr_b16 v[236:237], v231 offset:36864
	ds_read_b64_tr_b16 v[238:239], v231 offset:38912
	v_exp_f32_e32 v188, v188
	v_exp_f32_e32 v189, v189
	v_exp_f32_e32 v190, v190
	s_waitcnt lgkmcnt(12)
	v_mfma_f32_32x32x16_bf16 v[36:51], v[84:87], v[136:139], v[36:51]
	ds_read_b64_tr_b16 v[132:133], v228 offset:40960
	ds_read_b64_tr_b16 v[134:135], v228 offset:43008
	v_exp_f32_e32 v191, v191
	v_add_f32_e32 v252, v188, v190
	v_exp_f32_e32 v192, v192
	v_add_f32_e32 v253, v189, v191
	v_exp_f32_e32 v193, v193
	s_waitcnt lgkmcnt(12)
	v_mfma_f32_32x32x16_bf16 v[52:67], v[84:87], v[140:143], v[52:67]
	ds_read_b64_tr_b16 v[136:137], v229 offset:40960
	ds_read_b64_tr_b16 v[138:139], v229 offset:43008
	v_cvt_pk_bf16_f32 v188, v188, v189
	v_exp_f32_e32 v194, v194
	v_cvt_pk_bf16_f32 v189, v190, v191
	v_exp_f32_e32 v195, v195
	v_add_f32_e32 v252, v252, v192
	s_waitcnt lgkmcnt(12)
	v_mfma_f32_32x32x16_bf16 v[68:83], v[84:87], v[144:147], v[68:83]
	ds_read_b64_tr_b16 v[140:141], v230 offset:40960
	ds_read_b64_tr_b16 v[142:143], v230 offset:43008
	v_add_f32_e32 v253, v253, v193
	v_cvt_pk_bf16_f32 v190, v192, v193
	v_add_f32_e32 v252, v252, v194
	v_add_f32_e32 v253, v253, v195
	v_cvt_pk_bf16_f32 v191, v194, v195
	v_exp_f32_e32 v196, v196
	s_waitcnt lgkmcnt(12)
	v_mfma_f32_32x32x16_bf16 v[20:35], v[88:91], v[220:223], v[20:35]
	ds_read_b64_tr_b16 v[144:145], v231 offset:40960
	ds_read_b64_tr_b16 v[146:147], v231 offset:43008
	v_exp_f32_e32 v197, v197
	v_exp_f32_e32 v198, v198
	v_add_f32_e32 v252, v252, v196
	s_waitcnt lgkmcnt(12)
	v_mfma_f32_32x32x16_bf16 v[36:51], v[88:91], v[224:227], v[36:51]
	ds_read_b64_tr_b16 v[220:221], v228 offset:45056
	ds_read_b64_tr_b16 v[222:223], v228 offset:47104
	v_exp_f32_e32 v199, v199
	v_add_f32_e32 v253, v253, v197
	v_exp_f32_e32 v200, v200
	v_add_f32_e32 v252, v252, v198
	v_exp_f32_e32 v201, v201
	s_waitcnt lgkmcnt(12)
	v_mfma_f32_32x32x16_bf16 v[52:67], v[88:91], v[232:235], v[52:67]
	ds_read_b64_tr_b16 v[224:225], v229 offset:45056
	ds_read_b64_tr_b16 v[226:227], v229 offset:47104
	v_add_f32_e32 v253, v253, v199
	v_exp_f32_e32 v202, v202
	v_cvt_pk_bf16_f32 v192, v196, v197
	v_exp_f32_e32 v203, v203
	v_cvt_pk_bf16_f32 v193, v198, v199
	s_waitcnt lgkmcnt(12)
	v_mfma_f32_32x32x16_bf16 v[68:83], v[88:91], v[236:239], v[68:83]
	ds_read_b64_tr_b16 v[232:233], v230 offset:45056
	ds_read_b64_tr_b16 v[234:235], v230 offset:47104
	v_add_f32_e32 v252, v252, v200
	v_add_f32_e32 v253, v253, v201
	v_cvt_pk_bf16_f32 v194, v200, v201
	v_add_f32_e32 v252, v252, v202
	v_add_f32_e32 v253, v253, v203
	v_cvt_pk_bf16_f32 v195, v202, v203
	s_waitcnt lgkmcnt(12)
	v_mfma_f32_32x32x16_bf16 v[20:35], v[100:103], v[132:135], v[20:35]
	ds_read_b64_tr_b16 v[236:237], v231 offset:45056
	ds_read_b64_tr_b16 v[238:239], v231 offset:47104
	v_exp_f32_e32 v204, v204
	v_exp_f32_e32 v205, v205
	v_exp_f32_e32 v206, v206
	v_add_f32_e32 v252, v252, v204
	s_waitcnt lgkmcnt(12)
	v_mfma_f32_32x32x16_bf16 v[36:51], v[100:103], v[136:139], v[36:51]
	ds_read_b64_tr_b16 v[132:133], v168 offset:0
	ds_read_b64_tr_b16 v[134:135], v168 offset:2048
	v_exp_f32_e32 v207, v207
	v_add_f32_e32 v253, v253, v205
	v_exp_f32_e32 v208, v208
	v_add_f32_e32 v252, v252, v206
	v_exp_f32_e32 v209, v209
	s_waitcnt lgkmcnt(12)
	v_mfma_f32_32x32x16_bf16 v[52:67], v[100:103], v[140:143], v[52:67]
	ds_read_b64_tr_b16 v[136:137], v169 offset:0
	ds_read_b64_tr_b16 v[138:139], v169 offset:2048
	v_add_f32_e32 v253, v253, v207
	v_exp_f32_e32 v210, v210
	v_cvt_pk_bf16_f32 v204, v204, v205
	v_exp_f32_e32 v211, v211
	v_cvt_pk_bf16_f32 v205, v206, v207
	s_waitcnt lgkmcnt(12)
	v_mfma_f32_32x32x16_bf16 v[68:83], v[100:103], v[144:147], v[68:83]
	ds_read_b64_tr_b16 v[140:141], v170 offset:0
	ds_read_b64_tr_b16 v[142:143], v170 offset:2048
	v_add_f32_e32 v252, v252, v208
	v_add_f32_e32 v253, v253, v209
	v_cvt_pk_bf16_f32 v206, v208, v209
	v_add_f32_e32 v252, v252, v210
	v_add_f32_e32 v253, v253, v211
	v_cvt_pk_bf16_f32 v207, v210, v211
	s_waitcnt lgkmcnt(12)
	v_mfma_f32_32x32x16_bf16 v[20:35], v[104:107], v[220:223], v[20:35]
	ds_read_b64_tr_b16 v[144:145], v171 offset:0
	ds_read_b64_tr_b16 v[146:147], v171 offset:2048
	v_exp_f32_e32 v212, v212
	v_exp_f32_e32 v213, v213
	v_exp_f32_e32 v214, v214
	v_add_f32_e32 v252, v252, v212
	s_waitcnt lgkmcnt(12)
	v_mfma_f32_32x32x16_bf16 v[36:51], v[104:107], v[224:227], v[36:51]
	ds_read_b64_tr_b16 v[220:221], v168 offset:4096
	ds_read_b64_tr_b16 v[222:223], v168 offset:6144
	v_exp_f32_e32 v215, v215
	v_add_f32_e32 v253, v253, v213
	v_exp_f32_e32 v216, v216
	v_add_f32_e32 v252, v252, v214
	s_waitcnt lgkmcnt(12)
	v_mfma_f32_32x32x16_bf16 v[52:67], v[104:107], v[232:235], v[52:67]
	ds_read_b64_tr_b16 v[224:225], v169 offset:4096
	ds_read_b64_tr_b16 v[226:227], v169 offset:6144
	v_exp_f32_e32 v217, v217
	v_add_f32_e32 v253, v253, v215
	v_exp_f32_e32 v218, v218
	v_cvt_pk_bf16_f32 v208, v212, v213
	v_exp_f32_e32 v219, v219
	s_waitcnt lgkmcnt(12)
	v_mfma_f32_32x32x16_bf16 v[68:83], v[104:107], v[236:239], v[68:83]
	ds_read_b64_tr_b16 v[232:233], v170 offset:4096
	ds_read_b64_tr_b16 v[234:235], v170 offset:6144
	v_cvt_pk_bf16_f32 v209, v214, v215
	v_add_f32_e32 v252, v252, v216
	v_add_f32_e32 v253, v253, v217
	v_cvt_pk_bf16_f32 v210, v216, v217
	v_add_f32_e32 v252, v252, v218
	v_add_f32_e32 v253, v253, v219
	v_cvt_pk_bf16_f32 v211, v218, v219
	v_max_f32_e32 v251, v252, v253
	v_cmp_nge_f32_e32 vcc, 0x45800000, v251
	s_cbranch_vccnz .LatA_recs_x1

; #define LAS __attribute__((address_space(3)))
; __device__ __forceinline__ float max2f(float a, float b) { float r; asm("v_max_f32_e32 %0, %1, %2" : "=v"(r) : "v"(a), "v"(b)); return r; }
; __device__ __forceinline__ void attn_unit(LAS unsigned char* lds, const bf16_t* Z, bf16_t* A2, const float* tabg, int seq_base, int S, int h, int qb, float lam) {
;     ...
;         if (first || __any(mx > THR)) {
;             { auto rr = __builtin_amdgcn_permlane32_swap(__float_as_uint(mx), __float_as_uint(mx), false, false); mx = max2f(__uint_as_float(rr[0]), __uint_as_float(rr[1])); }
;             const float delta = first ? mx : fmaxf(mx, 0.f);
;             const float alpha = first ? 1.0f : __builtin_amdgcn_exp2f(-delta);
;             mu += delta; ls2 *= alpha;
;             if (!first) {
;                 asm volatile("" ::: "memory");
;                 scr[r32] = alpha;
;                 asm volatile("s_waitcnt lgkmcnt(0)" ::: "memory");
; #pragma unroll
;                 for (int g = 0; g < 4; ++g) { const f32x4 a4 = *(const LAS f32x4*)(scr + 8 * g + 4 * hi);
; #pragma unroll
;                     for (int d = 0; d < 4; ++d) { O[d][4 * g + 0] *= a4[0]; O[d][4 * g + 1] *= a4[1]; O[d][4 * g + 2] *= a4[2]; O[d][4 * g + 3] *= a4[3]; } }
;                 asm volatile("s_waitcnt lgkmcnt(0)" ::: "memory");
;             }
; #pragma unroll
;             for (int r = 0; r < 16; ++r) { p0[r] -= delta; p1[r] -= delta; }
.LatA_recnn_0:
	v_max3_f32 v251, v84, v85, v86
	v_max3_f32 v252, v87, v88, v89
	v_max3_f32 v251, v251, v90, v91
	v_max3_f32 v252, v252, v92, v93
	v_max3_f32 v251, v251, v94, v95
	v_max3_f32 v252, v252, v96, v97
	v_max3_f32 v251, v251, v98, v99
	v_max3_f32 v252, v252, v100, v101
	v_max3_f32 v251, v251, v102, v103
	v_max3_f32 v252, v252, v104, v105
	v_max3_f32 v251, v251, v106, v107
	v_max3_f32 v252, v252, v108, v109
	v_max3_f32 v251, v251, v110, v111
	v_max3_f32 v252, v252, v112, v113
	v_max3_f32 v251, v251, v114, v115
	v_max_f32_e32 v251, v251, v252
	v_mov_b32_e32 v252, v251
	s_nop 1
	v_permlane32_swap_b32_e32 v251, v252
	v_max_f32_e32 v251, v251, v252
	v_max_f32_e32 v253, 0, v251
	v_exp_f32_e64 v254, -v253
	v_add_f32_e32 v186, v186, v253
	s_nop 0
	v_mul_f32_e32 v150, v150, v254
	v_mul_f32_e32 v151, v151, v254
	ds_write_b32 v184, v254
	s_waitcnt lgkmcnt(0)
	ds_read_b128 v[132:135], v185
	ds_read_b128 v[136:139], v185 offset:32
	ds_read_b128 v[140:143], v185 offset:64
	ds_read_b128 v[144:147], v185 offset:96
	s_waitcnt lgkmcnt(0)
	v_pk_mul_f32 v[20:21], v[20:21], v[132:133]
	v_pk_mul_f32 v[22:23], v[22:23], v[134:135]
	v_pk_mul_f32 v[24:25], v[24:25], v[136:137]
	v_pk_mul_f32 v[26:27], v[26:27], v[138:139]
	v_pk_mul_f32 v[28:29], v[28:29], v[140:141]
	v_pk_mul_f32 v[30:31], v[30:31], v[142:143]
	v_pk_mul_f32 v[32:33], v[32:33], v[144:145]
	v_pk_mul_f32 v[34:35], v[34:35], v[146:147]
	v_pk_mul_f32 v[36:37], v[36:37], v[132:133]
	v_pk_mul_f32 v[38:39], v[38:39], v[134:135]
	v_pk_mul_f32 v[40:41], v[40:41], v[136:137]
	v_pk_mul_f32 v[42:43], v[42:43], v[138:139]
	v_pk_mul_f32 v[44:45], v[44:45], v[140:141]
	v_pk_mul_f32 v[46:47], v[46:47], v[142:143]
	v_pk_mul_f32 v[48:49], v[48:49], v[144:145]
	v_pk_mul_f32 v[50:51], v[50:51], v[146:147]
	v_pk_mul_f32 v[52:53], v[52:53], v[132:133]
	v_pk_mul_f32 v[54:55], v[54:55], v[134:135]
	v_pk_mul_f32 v[56:57], v[56:57], v[136:137]
	v_pk_mul_f32 v[58:59], v[58:59], v[138:139]
	v_pk_mul_f32 v[60:61], v[60:61], v[140:141]
	v_pk_mul_f32 v[62:63], v[62:63], v[142:143]
	v_pk_mul_f32 v[64:65], v[64:65], v[144:145]
	v_pk_mul_f32 v[66:67], v[66:67], v[146:147]
	v_pk_mul_f32 v[68:69], v[68:69], v[132:133]
	v_pk_mul_f32 v[70:71], v[70:71], v[134:135]
	v_pk_mul_f32 v[72:73], v[72:73], v[136:137]
	v_pk_mul_f32 v[74:75], v[74:75], v[138:139]
	v_pk_mul_f32 v[76:77], v[76:77], v[140:141]
	v_pk_mul_f32 v[78:79], v[78:79], v[142:143]
	v_pk_mul_f32 v[80:81], v[80:81], v[144:145]
	v_pk_mul_f32 v[82:83], v[82:83], v[146:147]
	v_mov_b32_e32 v252, v253
	v_pk_add_f32 v[84:85], v[84:85], v[252:253] neg_lo:[0,1] neg_hi:[0,1]
	v_pk_add_f32 v[86:87], v[86:87], v[252:253] neg_lo:[0,1] neg_hi:[0,1]
	v_pk_add_f32 v[88:89], v[88:89], v[252:253] neg_lo:[0,1] neg_hi:[0,1]
	v_pk_add_f32 v[90:91], v[90:91], v[252:253] neg_lo:[0,1] neg_hi:[0,1]
	v_pk_add_f32 v[92:93], v[92:93], v[252:253] neg_lo:[0,1] neg_hi:[0,1]
	v_pk_add_f32 v[94:95], v[94:95], v[252:253] neg_lo:[0,1] neg_hi:[0,1]
	v_pk_add_f32 v[96:97], v[96:97], v[252:253] neg_lo:[0,1] neg_hi:[0,1]
	v_pk_add_f32 v[98:99], v[98:99], v[252:253] neg_lo:[0,1] neg_hi:[0,1]
	v_pk_add_f32 v[100:101], v[100:101], v[252:253] neg_lo:[0,1] neg_hi:[0,1]
	v_pk_add_f32 v[102:103], v[102:103], v[252:253] neg_lo:[0,1] neg_hi:[0,1]
	v_pk_add_f32 v[104:105], v[104:105], v[252:253] neg_lo:[0,1] neg_hi:[0,1]
	v_pk_add_f32 v[106:107], v[106:107], v[252:253] neg_lo:[0,1] neg_hi:[0,1]
	v_pk_add_f32 v[108:109], v[108:109], v[252:253] neg_lo:[0,1] neg_hi:[0,1]
	v_pk_add_f32 v[110:111], v[110:111], v[252:253] neg_lo:[0,1] neg_hi:[0,1]
	v_pk_add_f32 v[112:113], v[112:113], v[252:253] neg_lo:[0,1] neg_hi:[0,1]
	v_pk_add_f32 v[114:115], v[114:115], v[252:253] neg_lo:[0,1] neg_hi:[0,1]
	v_pk_add_f32 v[188:189], v[188:189], v[252:253] neg_lo:[0,1] neg_hi:[0,1]
	v_pk_add_f32 v[190:191], v[190:191], v[252:253] neg_lo:[0,1] neg_hi:[0,1]
	v_pk_add_f32 v[192:193], v[192:193], v[252:253] neg_lo:[0,1] neg_hi:[0,1]
	v_pk_add_f32 v[194:195], v[194:195], v[252:253] neg_lo:[0,1] neg_hi:[0,1]
	v_pk_add_f32 v[196:197], v[196:197], v[252:253] neg_lo:[0,1] neg_hi:[0,1]
	v_pk_add_f32 v[198:199], v[198:199], v[252:253] neg_lo:[0,1] neg_hi:[0,1]
	v_pk_add_f32 v[200:201], v[200:201], v[252:253] neg_lo:[0,1] neg_hi:[0,1]
	v_pk_add_f32 v[202:203], v[202:203], v[252:253] neg_lo:[0,1] neg_hi:[0,1]
; #define VREADS1(arr, d_) do { const unsigned ad_ = vbase ^ (unsigned)((d_) << 6); __builtin_amdgcn_sched_barrier(0); \
;         _Pragma("unroll") for (int ks_ = 0; ks_ < 4; ++ks_) { VTR(arr[ks_ * 2], ad_, ks_ * 4096); VTR(arr[ks_ * 2 + 1], ad_, ks_ * 4096 + 2048); } __builtin_amdgcn_sched_barrier(0); } while (0)
; #define PV1(arr, d_) do { _Pragma("unroll") for (int ks_ = 0; ks_ < 4; ++ks_) { const s16x4 lo_ = arr[ks_ * 2], hh_ = arr[ks_ * 2 + 1]; \
;         const bf16x8 bv_ = (bf16x8){lo_[0], lo_[1], lo_[2], lo_[3], hh_[0], hh_[1], hh_[2], hh_[3]}; \
;         O[d_] = __builtin_amdgcn_mfma_f32_32x32x16_bf16(pa[ks_], bv_, O[d_], 0, 0, 0); } __builtin_amdgcn_sched_barrier(0); } while (0)
; #define LGKM0() do { __builtin_amdgcn_sched_barrier(0); asm volatile("s_waitcnt lgkmcnt(0)" ::: "memory"); __builtin_amdgcn_sched_barrier(0); } while (0)
; __device__ __forceinline__ void attn_unit(LAS unsigned char* lds, const bf16_t* Z, bf16_t* A2, const float* tabg, int seq_base, int S, int h, int qb, float lam) {
;     ...
;         { const float coff = cc - mu;
;           if (__any(!(coff == coff_cur))) { coff_cur = coff;
; #pragma unroll
;               for (int r = 0; r < 16; ++r) cblk[r] = coff;
;               asm volatile("" : "+v"(cblk)); } }
;     ...
;             for (int r = 0; r < 16; ++r) { p0[r] -= delta; p1[r] -= delta; }
;             asm volatile("" : "+v"(p0), "+v"(p1));
;         }
; #pragma unroll
;         for (int r = 0; r < 16; ++r) { p0[r] = __builtin_amdgcn_exp2f(p0[r]); p1[r] = __builtin_amdgcn_exp2f(p1[r]); }
; #pragma unroll
;         for (int r = 0; r < 16; r += 2) { ls2 += (f32x2){p0[r], p0[r + 1]}; ls2 += (f32x2){p1[r], p1[r + 1]}; }
;         bf16x8 pa[4]; pa[0] = pack8(p0, 0); pa[1] = pack8(p0, 8); pa[2] = pack8(p1, 0); pa[3] = pack8(p1, 8);
;         LGKM0(); VREADS1(vb, 1); PV1(va, 0); LGKM0(); VREADS1(va, 2); PV1(vb, 1); LGKM0(); VREADS1(vb, 3); PV1(va, 2); LGKM0(); PV1(vb, 3);
	v_pk_add_f32 v[204:205], v[204:205], v[252:253] neg_lo:[0,1] neg_hi:[0,1]
	v_pk_add_f32 v[206:207], v[206:207], v[252:253] neg_lo:[0,1] neg_hi:[0,1]
	v_pk_add_f32 v[208:209], v[208:209], v[252:253] neg_lo:[0,1] neg_hi:[0,1]
	v_pk_add_f32 v[210:211], v[210:211], v[252:253] neg_lo:[0,1] neg_hi:[0,1]
	v_pk_add_f32 v[212:213], v[212:213], v[252:253] neg_lo:[0,1] neg_hi:[0,1]
	v_pk_add_f32 v[214:215], v[214:215], v[252:253] neg_lo:[0,1] neg_hi:[0,1]
	v_pk_add_f32 v[216:217], v[216:217], v[252:253] neg_lo:[0,1] neg_hi:[0,1]
	v_pk_add_f32 v[218:219], v[218:219], v[252:253] neg_lo:[0,1] neg_hi:[0,1]
	v_exp_f32_e32 v84, v84
	v_exp_f32_e32 v85, v85
	v_exp_f32_e32 v86, v86
	v_exp_f32_e32 v87, v87
	v_add_f32_e32 v252, v84, v86
	v_exp_f32_e32 v88, v88
	v_add_f32_e32 v253, v85, v87
	v_exp_f32_e32 v89, v89
	v_cvt_pk_bf16_f32 v84, v84, v85
	v_exp_f32_e32 v90, v90
	v_cvt_pk_bf16_f32 v85, v86, v87
	v_exp_f32_e32 v91, v91
	v_add_f32_e32 v252, v252, v88
	v_add_f32_e32 v253, v253, v89
	v_cvt_pk_bf16_f32 v86, v88, v89
	v_add_f32_e32 v252, v252, v90
	v_add_f32_e32 v253, v253, v91
	v_cvt_pk_bf16_f32 v87, v90, v91
	v_exp_f32_e32 v92, v92
	v_exp_f32_e32 v93, v93
	v_exp_f32_e32 v94, v94
	v_add_f32_e32 v252, v252, v92
	v_exp_f32_e32 v95, v95
	v_add_f32_e32 v253, v253, v93
	v_exp_f32_e32 v96, v96
	v_add_f32_e32 v252, v252, v94
	v_exp_f32_e32 v97, v97
	v_add_f32_e32 v253, v253, v95
	v_exp_f32_e32 v98, v98
	v_cvt_pk_bf16_f32 v88, v92, v93
	v_exp_f32_e32 v99, v99
	v_cvt_pk_bf16_f32 v89, v94, v95
	v_add_f32_e32 v252, v252, v96
	v_add_f32_e32 v253, v253, v97
	v_cvt_pk_bf16_f32 v90, v96, v97
	v_add_f32_e32 v252, v252, v98
	v_add_f32_e32 v253, v253, v99
	v_cvt_pk_bf16_f32 v91, v98, v99
	v_exp_f32_e32 v100, v100
	v_exp_f32_e32 v101, v101
	v_exp_f32_e32 v102, v102
	v_add_f32_e32 v252, v252, v100
	v_exp_f32_e32 v103, v103
	v_add_f32_e32 v253, v253, v101
	v_exp_f32_e32 v104, v104
	v_add_f32_e32 v252, v252, v102
	v_exp_f32_e32 v105, v105
	v_add_f32_e32 v253, v253, v103
	v_exp_f32_e32 v106, v106
	v_cvt_pk_bf16_f32 v100, v100, v101
	v_exp_f32_e32 v107, v107
	v_cvt_pk_bf16_f32 v101, v102, v103
	v_add_f32_e32 v252, v252, v104
	v_add_f32_e32 v253, v253, v105
	v_cvt_pk_bf16_f32 v102, v104, v105
	v_add_f32_e32 v252, v252, v106
	v_add_f32_e32 v253, v253, v107
	v_cvt_pk_bf16_f32 v103, v106, v107
	v_exp_f32_e32 v108, v108
	v_exp_f32_e32 v109, v109
	v_exp_f32_e32 v110, v110
	v_add_f32_e32 v252, v252, v108
	v_exp_f32_e32 v111, v111
	v_add_f32_e32 v253, v253, v109
	v_exp_f32_e32 v112, v112
	v_add_f32_e32 v252, v252, v110
	v_exp_f32_e32 v113, v113
	v_add_f32_e32 v253, v253, v111
	v_exp_f32_e32 v114, v114
	v_cvt_pk_bf16_f32 v104, v108, v109
	v_exp_f32_e32 v115, v115
	v_cvt_pk_bf16_f32 v105, v110, v111
	v_add_f32_e32 v252, v252, v112
	v_add_f32_e32 v253, v253, v113
	v_cvt_pk_bf16_f32 v106, v112, v113
	v_add_f32_e32 v252, v252, v114
	v_add_f32_e32 v253, v253, v115
	v_cvt_pk_bf16_f32 v107, v114, v115
	s_mov_b32 s37, s43
	s_mov_b32 s35, s37
	v_mov_b32_e32 v251, 0
	s_cmp_eq_u32 s37, 1
	s_cselect_b64 vcc, -1, 0
	v_cndmask_b32_e32 v251, v251, v177, vcc
	s_cmp_eq_u32 s37, 2
	s_cselect_b64 vcc, -1, 0
	v_cndmask_b32_e32 v251, v251, v178, vcc
	v_sub_f32_e32 v2, v251, v186
	v_mov_b32_e32 v3, v2
	v_mov_b64_e32 v[4:5], v[2:3]
	v_mov_b64_e32 v[6:7], v[2:3]
	v_mov_b64_e32 v[8:9], v[2:3]
	v_mov_b64_e32 v[10:11], v[2:3]
	v_mov_b64_e32 v[12:13], v[2:3]
	v_mov_b64_e32 v[14:15], v[2:3]
	v_mov_b64_e32 v[16:17], v[2:3]
	ds_read_b64_tr_b16 v[132:133], v228 offset:0
	ds_read_b64_tr_b16 v[134:135], v228 offset:2048
	ds_read_b64_tr_b16 v[136:137], v229 offset:0
	ds_read_b64_tr_b16 v[138:139], v229 offset:2048
	ds_read_b64_tr_b16 v[140:141], v230 offset:0
	ds_read_b64_tr_b16 v[142:143], v230 offset:2048
	ds_read_b64_tr_b16 v[144:145], v231 offset:0
	ds_read_b64_tr_b16 v[146:147], v231 offset:2048
	ds_read_b64_tr_b16 v[220:221], v228 offset:4096
	ds_read_b64_tr_b16 v[222:223], v228 offset:6144
	ds_read_b64_tr_b16 v[224:225], v229 offset:4096
	ds_read_b64_tr_b16 v[226:227], v229 offset:6144
	ds_read_b64_tr_b16 v[232:233], v230 offset:4096
	ds_read_b64_tr_b16 v[234:235], v230 offset:6144
	s_nop 1
	s_cmp_eq_u32 s42, 0
	s_cbranch_scc1 .LatA_recret_h0
	s_cmp_eq_u32 s42, 1
	s_cbranch_scc1 .LatA_recret_m0
	s_branch .LatA_recret_x4

; #define LAS __attribute__((address_space(3)))
; __device__ __forceinline__ float max2f(float a, float b) { float r; asm("v_max_f32_e32 %0, %1, %2" : "=v"(r) : "v"(a), "v"(b)); return r; }
; __device__ __forceinline__ void attn_unit(LAS unsigned char* lds, const bf16_t* Z, bf16_t* A2, const float* tabg, int seq_base, int S, int h, int qb, float lam) {
;     ...
;         if (first || __any(mx > THR)) {
;             { auto rr = __builtin_amdgcn_permlane32_swap(__float_as_uint(mx), __float_as_uint(mx), false, false); mx = max2f(__uint_as_float(rr[0]), __uint_as_float(rr[1])); }
;             const float delta = first ? mx : fmaxf(mx, 0.f);
;             const float alpha = first ? 1.0f : __builtin_amdgcn_exp2f(-delta);
;             mu += delta; ls2 *= alpha;
;             if (!first) {
;                 asm volatile("" ::: "memory");
;                 scr[r32] = alpha;
;                 asm volatile("s_waitcnt lgkmcnt(0)" ::: "memory");
; #pragma unroll
;                 for (int g = 0; g < 4; ++g) { const f32x4 a4 = *(const LAS f32x4*)(scr + 8 * g + 4 * hi);
; #pragma unroll
;                     for (int d = 0; d < 4; ++d) { O[d][4 * g + 0] *= a4[0]; O[d][4 * g + 1] *= a4[1]; O[d][4 * g + 2] *= a4[2]; O[d][4 * g + 3] *= a4[3]; } }
;                 asm volatile("s_waitcnt lgkmcnt(0)" ::: "memory");
;             }
; #pragma unroll
;             for (int r = 0; r < 16; ++r) { p0[r] -= delta; p1[r] -= delta; }
.LatA_recnn_1:
	v_max3_f32 v251, v188, v189, v190
	v_max3_f32 v252, v191, v192, v193
	v_max3_f32 v251, v251, v194, v195
	v_max3_f32 v252, v252, v196, v197
	v_max3_f32 v251, v251, v198, v199
	v_max3_f32 v252, v252, v200, v201
	v_max3_f32 v251, v251, v202, v203
	v_max3_f32 v252, v252, v204, v205
	v_max3_f32 v251, v251, v206, v207
	v_max3_f32 v252, v252, v208, v209
	v_max3_f32 v251, v251, v210, v211
	v_max3_f32 v252, v252, v212, v213
	v_max3_f32 v251, v251, v214, v215
	v_max3_f32 v252, v252, v216, v217
	v_max3_f32 v251, v251, v218, v219
	v_max_f32_e32 v251, v251, v252
	v_mov_b32_e32 v252, v251
	s_nop 1
	v_permlane32_swap_b32_e32 v251, v252
	v_max_f32_e32 v251, v251, v252
	v_max_f32_e32 v253, 0, v251
	v_exp_f32_e64 v254, -v253
	v_add_f32_e32 v186, v186, v253
	s_nop 0
	v_mul_f32_e32 v150, v150, v254
	v_mul_f32_e32 v151, v151, v254
	ds_write_b32 v184, v254
	s_waitcnt lgkmcnt(0)
	ds_read_b128 v[132:135], v185
	ds_read_b128 v[136:139], v185 offset:32
	ds_read_b128 v[140:143], v185 offset:64
	ds_read_b128 v[144:147], v185 offset:96
	s_waitcnt lgkmcnt(0)
	v_pk_mul_f32 v[20:21], v[20:21], v[132:133]
	v_pk_mul_f32 v[22:23], v[22:23], v[134:135]
	v_pk_mul_f32 v[24:25], v[24:25], v[136:137]
	v_pk_mul_f32 v[26:27], v[26:27], v[138:139]
	v_pk_mul_f32 v[28:29], v[28:29], v[140:141]
	v_pk_mul_f32 v[30:31], v[30:31], v[142:143]
	v_pk_mul_f32 v[32:33], v[32:33], v[144:145]
	v_pk_mul_f32 v[34:35], v[34:35], v[146:147]
	v_pk_mul_f32 v[36:37], v[36:37], v[132:133]
	v_pk_mul_f32 v[38:39], v[38:39], v[134:135]
	v_pk_mul_f32 v[40:41], v[40:41], v[136:137]
	v_pk_mul_f32 v[42:43], v[42:43], v[138:139]
	v_pk_mul_f32 v[44:45], v[44:45], v[140:141]
	v_pk_mul_f32 v[46:47], v[46:47], v[142:143]
	v_pk_mul_f32 v[48:49], v[48:49], v[144:145]
	v_pk_mul_f32 v[50:51], v[50:51], v[146:147]
	v_pk_mul_f32 v[52:53], v[52:53], v[132:133]
	v_pk_mul_f32 v[54:55], v[54:55], v[134:135]
	v_pk_mul_f32 v[56:57], v[56:57], v[136:137]
	v_pk_mul_f32 v[58:59], v[58:59], v[138:139]
	v_pk_mul_f32 v[60:61], v[60:61], v[140:141]
	v_pk_mul_f32 v[62:63], v[62:63], v[142:143]
	v_pk_mul_f32 v[64:65], v[64:65], v[144:145]
	v_pk_mul_f32 v[66:67], v[66:67], v[146:147]
	v_pk_mul_f32 v[68:69], v[68:69], v[132:133]
	v_pk_mul_f32 v[70:71], v[70:71], v[134:135]
	v_pk_mul_f32 v[72:73], v[72:73], v[136:137]
	v_pk_mul_f32 v[74:75], v[74:75], v[138:139]
	v_pk_mul_f32 v[76:77], v[76:77], v[140:141]
	v_pk_mul_f32 v[78:79], v[78:79], v[142:143]
	v_pk_mul_f32 v[80:81], v[80:81], v[144:145]
	v_pk_mul_f32 v[82:83], v[82:83], v[146:147]
	v_mov_b32_e32 v252, v253
	v_pk_add_f32 v[188:189], v[188:189], v[252:253] neg_lo:[0,1] neg_hi:[0,1]
	v_pk_add_f32 v[190:191], v[190:191], v[252:253] neg_lo:[0,1] neg_hi:[0,1]
	v_pk_add_f32 v[192:193], v[192:193], v[252:253] neg_lo:[0,1] neg_hi:[0,1]
	v_pk_add_f32 v[194:195], v[194:195], v[252:253] neg_lo:[0,1] neg_hi:[0,1]
	v_pk_add_f32 v[196:197], v[196:197], v[252:253] neg_lo:[0,1] neg_hi:[0,1]
	v_pk_add_f32 v[198:199], v[198:199], v[252:253] neg_lo:[0,1] neg_hi:[0,1]
	v_pk_add_f32 v[200:201], v[200:201], v[252:253] neg_lo:[0,1] neg_hi:[0,1]
	v_pk_add_f32 v[202:203], v[202:203], v[252:253] neg_lo:[0,1] neg_hi:[0,1]
	v_pk_add_f32 v[204:205], v[204:205], v[252:253] neg_lo:[0,1] neg_hi:[0,1]
	v_pk_add_f32 v[206:207], v[206:207], v[252:253] neg_lo:[0,1] neg_hi:[0,1]
	v_pk_add_f32 v[208:209], v[208:209], v[252:253] neg_lo:[0,1] neg_hi:[0,1]
	v_pk_add_f32 v[210:211], v[210:211], v[252:253] neg_lo:[0,1] neg_hi:[0,1]
	v_pk_add_f32 v[212:213], v[212:213], v[252:253] neg_lo:[0,1] neg_hi:[0,1]
	v_pk_add_f32 v[214:215], v[214:215], v[252:253] neg_lo:[0,1] neg_hi:[0,1]
	v_pk_add_f32 v[216:217], v[216:217], v[252:253] neg_lo:[0,1] neg_hi:[0,1]
	v_pk_add_f32 v[218:219], v[218:219], v[252:253] neg_lo:[0,1] neg_hi:[0,1]
	v_pk_add_f32 v[84:85], v[84:85], v[252:253] neg_lo:[0,1] neg_hi:[0,1]
	v_pk_add_f32 v[86:87], v[86:87], v[252:253] neg_lo:[0,1] neg_hi:[0,1]
	v_pk_add_f32 v[88:89], v[88:89], v[252:253] neg_lo:[0,1] neg_hi:[0,1]
	v_pk_add_f32 v[90:91], v[90:91], v[252:253] neg_lo:[0,1] neg_hi:[0,1]
	v_pk_add_f32 v[92:93], v[92:93], v[252:253] neg_lo:[0,1] neg_hi:[0,1]
	v_pk_add_f32 v[94:95], v[94:95], v[252:253] neg_lo:[0,1] neg_hi:[0,1]
	v_pk_add_f32 v[96:97], v[96:97], v[252:253] neg_lo:[0,1] neg_hi:[0,1]
	v_pk_add_f32 v[98:99], v[98:99], v[252:253] neg_lo:[0,1] neg_hi:[0,1]
; #define VREADS1(arr, d_) do { const unsigned ad_ = vbase ^ (unsigned)((d_) << 6); __builtin_amdgcn_sched_barrier(0); \
;         _Pragma("unroll") for (int ks_ = 0; ks_ < 4; ++ks_) { VTR(arr[ks_ * 2], ad_, ks_ * 4096); VTR(arr[ks_ * 2 + 1], ad_, ks_ * 4096 + 2048); } __builtin_amdgcn_sched_barrier(0); } while (0)
; #define PV1(arr, d_) do { _Pragma("unroll") for (int ks_ = 0; ks_ < 4; ++ks_) { const s16x4 lo_ = arr[ks_ * 2], hh_ = arr[ks_ * 2 + 1]; \
;         const bf16x8 bv_ = (bf16x8){lo_[0], lo_[1], lo_[2], lo_[3], hh_[0], hh_[1], hh_[2], hh_[3]}; \
;         O[d_] = __builtin_amdgcn_mfma_f32_32x32x16_bf16(pa[ks_], bv_, O[d_], 0, 0, 0); } __builtin_amdgcn_sched_barrier(0); } while (0)
; #define LGKM0() do { __builtin_amdgcn_sched_barrier(0); asm volatile("s_waitcnt lgkmcnt(0)" ::: "memory"); __builtin_amdgcn_sched_barrier(0); } while (0)
; __device__ __forceinline__ void attn_unit(LAS unsigned char* lds, const bf16_t* Z, bf16_t* A2, const float* tabg, int seq_base, int S, int h, int qb, float lam) {
;     ...
;         { const float coff = cc - mu;
;           if (__any(!(coff == coff_cur))) { coff_cur = coff;
; #pragma unroll
;               for (int r = 0; r < 16; ++r) cblk[r] = coff;
;               asm volatile("" : "+v"(cblk)); } }
;     ...
;             for (int r = 0; r < 16; ++r) { p0[r] -= delta; p1[r] -= delta; }
;             asm volatile("" : "+v"(p0), "+v"(p1));
;         }
; #pragma unroll
;         for (int r = 0; r < 16; ++r) { p0[r] = __builtin_amdgcn_exp2f(p0[r]); p1[r] = __builtin_amdgcn_exp2f(p1[r]); }
; #pragma unroll
;         for (int r = 0; r < 16; r += 2) { ls2 += (f32x2){p0[r], p0[r + 1]}; ls2 += (f32x2){p1[r], p1[r + 1]}; }
;         bf16x8 pa[4]; pa[0] = pack8(p0, 0); pa[1] = pack8(p0, 8); pa[2] = pack8(p1, 0); pa[3] = pack8(p1, 8);
;         LGKM0(); VREADS1(vb, 1); PV1(va, 0); LGKM0(); VREADS1(va, 2); PV1(vb, 1); LGKM0(); VREADS1(vb, 3); PV1(va, 2); LGKM0(); PV1(vb, 3);
	v_pk_add_f32 v[100:101], v[100:101], v[252:253] neg_lo:[0,1] neg_hi:[0,1]
	v_pk_add_f32 v[102:103], v[102:103], v[252:253] neg_lo:[0,1] neg_hi:[0,1]
	v_pk_add_f32 v[104:105], v[104:105], v[252:253] neg_lo:[0,1] neg_hi:[0,1]
	v_pk_add_f32 v[106:107], v[106:107], v[252:253] neg_lo:[0,1] neg_hi:[0,1]
	v_pk_add_f32 v[108:109], v[108:109], v[252:253] neg_lo:[0,1] neg_hi:[0,1]
	v_pk_add_f32 v[110:111], v[110:111], v[252:253] neg_lo:[0,1] neg_hi:[0,1]
	v_pk_add_f32 v[112:113], v[112:113], v[252:253] neg_lo:[0,1] neg_hi:[0,1]
	v_pk_add_f32 v[114:115], v[114:115], v[252:253] neg_lo:[0,1] neg_hi:[0,1]
	v_exp_f32_e32 v188, v188
	v_exp_f32_e32 v189, v189
	v_exp_f32_e32 v190, v190
	v_exp_f32_e32 v191, v191
	v_add_f32_e32 v252, v188, v190
	v_exp_f32_e32 v192, v192
	v_add_f32_e32 v253, v189, v191
	v_exp_f32_e32 v193, v193
	v_cvt_pk_bf16_f32 v188, v188, v189
	v_exp_f32_e32 v194, v194
	v_cvt_pk_bf16_f32 v189, v190, v191
	v_exp_f32_e32 v195, v195
	v_add_f32_e32 v252, v252, v192
	v_add_f32_e32 v253, v253, v193
	v_cvt_pk_bf16_f32 v190, v192, v193
	v_add_f32_e32 v252, v252, v194
	v_add_f32_e32 v253, v253, v195
	v_cvt_pk_bf16_f32 v191, v194, v195
	v_exp_f32_e32 v196, v196
	v_exp_f32_e32 v197, v197
	v_exp_f32_e32 v198, v198
	v_add_f32_e32 v252, v252, v196
	v_exp_f32_e32 v199, v199
	v_add_f32_e32 v253, v253, v197
	v_exp_f32_e32 v200, v200
	v_add_f32_e32 v252, v252, v198
	v_exp_f32_e32 v201, v201
	v_add_f32_e32 v253, v253, v199
	v_exp_f32_e32 v202, v202
	v_cvt_pk_bf16_f32 v192, v196, v197
	v_exp_f32_e32 v203, v203
	v_cvt_pk_bf16_f32 v193, v198, v199
	v_add_f32_e32 v252, v252, v200
	v_add_f32_e32 v253, v253, v201
	v_cvt_pk_bf16_f32 v194, v200, v201
	v_add_f32_e32 v252, v252, v202
	v_add_f32_e32 v253, v253, v203
	v_cvt_pk_bf16_f32 v195, v202, v203
	v_exp_f32_e32 v204, v204
	v_exp_f32_e32 v205, v205
	v_exp_f32_e32 v206, v206
	v_add_f32_e32 v252, v252, v204
	v_exp_f32_e32 v207, v207
	v_add_f32_e32 v253, v253, v205
	v_exp_f32_e32 v208, v208
	v_add_f32_e32 v252, v252, v206
	v_exp_f32_e32 v209, v209
	v_add_f32_e32 v253, v253, v207
	v_exp_f32_e32 v210, v210
	v_cvt_pk_bf16_f32 v204, v204, v205
	v_exp_f32_e32 v211, v211
	v_cvt_pk_bf16_f32 v205, v206, v207
	v_add_f32_e32 v252, v252, v208
	v_add_f32_e32 v253, v253, v209
	v_cvt_pk_bf16_f32 v206, v208, v209
	v_add_f32_e32 v252, v252, v210
	v_add_f32_e32 v253, v253, v211
	v_cvt_pk_bf16_f32 v207, v210, v211
	v_exp_f32_e32 v212, v212
	v_exp_f32_e32 v213, v213
	v_exp_f32_e32 v214, v214
	v_add_f32_e32 v252, v252, v212
	v_exp_f32_e32 v215, v215
	v_add_f32_e32 v253, v253, v213
	v_exp_f32_e32 v216, v216
	v_add_f32_e32 v252, v252, v214
	v_exp_f32_e32 v217, v217
	v_add_f32_e32 v253, v253, v215
	v_exp_f32_e32 v218, v218
	v_cvt_pk_bf16_f32 v208, v212, v213
	v_exp_f32_e32 v219, v219
	v_cvt_pk_bf16_f32 v209, v214, v215
	v_add_f32_e32 v252, v252, v216
	v_add_f32_e32 v253, v253, v217
	v_cvt_pk_bf16_f32 v210, v216, v217
	v_add_f32_e32 v252, v252, v218
	v_add_f32_e32 v253, v253, v219
	v_cvt_pk_bf16_f32 v211, v218, v219
	s_mov_b32 s37, s43
	s_mov_b32 s35, s37
	v_mov_b32_e32 v251, 0
	s_cmp_eq_u32 s37, 1
	s_cselect_b64 vcc, -1, 0
	v_cndmask_b32_e32 v251, v251, v177, vcc
	s_cmp_eq_u32 s37, 2
	s_cselect_b64 vcc, -1, 0
	v_cndmask_b32_e32 v251, v251, v178, vcc
	v_sub_f32_e32 v2, v251, v186
	v_mov_b32_e32 v3, v2
	v_mov_b64_e32 v[4:5], v[2:3]
	v_mov_b64_e32 v[6:7], v[2:3]
	v_mov_b64_e32 v[8:9], v[2:3]
	v_mov_b64_e32 v[10:11], v[2:3]
	v_mov_b64_e32 v[12:13], v[2:3]
	v_mov_b64_e32 v[14:15], v[2:3]
	v_mov_b64_e32 v[16:17], v[2:3]
	ds_read_b64_tr_b16 v[132:133], v228 offset:16384
	ds_read_b64_tr_b16 v[134:135], v228 offset:18432
	ds_read_b64_tr_b16 v[136:137], v229 offset:16384
	ds_read_b64_tr_b16 v[138:139], v229 offset:18432
	ds_read_b64_tr_b16 v[140:141], v230 offset:16384
	ds_read_b64_tr_b16 v[142:143], v230 offset:18432
	ds_read_b64_tr_b16 v[144:145], v231 offset:16384
	ds_read_b64_tr_b16 v[146:147], v231 offset:18432
	ds_read_b64_tr_b16 v[220:221], v228 offset:20480
	ds_read_b64_tr_b16 v[222:223], v228 offset:22528
	ds_read_b64_tr_b16 v[224:225], v229 offset:20480
	ds_read_b64_tr_b16 v[226:227], v229 offset:22528
	ds_read_b64_tr_b16 v[232:233], v230 offset:20480
	ds_read_b64_tr_b16 v[234:235], v230 offset:22528
	s_nop 1
	s_cmp_eq_u32 s42, 0
	s_cbranch_scc1 .LatA_recret_h1
	s_cmp_eq_u32 s42, 1
	s_cbranch_scc1 .LatA_recret_m1
	s_branch .LatA_recret_x3

; #define LAS __attribute__((address_space(3)))
; __device__ __forceinline__ float max2f(float a, float b) { float r; asm("v_max_f32_e32 %0, %1, %2" : "=v"(r) : "v"(a), "v"(b)); return r; }
; __device__ __forceinline__ void attn_unit(LAS unsigned char* lds, const bf16_t* Z, bf16_t* A2, const float* tabg, int seq_base, int S, int h, int qb, float lam) {
;     ...
;         if (first || __any(mx > THR)) {
;             { auto rr = __builtin_amdgcn_permlane32_swap(__float_as_uint(mx), __float_as_uint(mx), false, false); mx = max2f(__uint_as_float(rr[0]), __uint_as_float(rr[1])); }
;             const float delta = first ? mx : fmaxf(mx, 0.f);
;             const float alpha = first ? 1.0f : __builtin_amdgcn_exp2f(-delta);
;             mu += delta; ls2 *= alpha;
;             if (!first) {
;                 asm volatile("" ::: "memory");
;                 scr[r32] = alpha;
;                 asm volatile("s_waitcnt lgkmcnt(0)" ::: "memory");
; #pragma unroll
;                 for (int g = 0; g < 4; ++g) { const f32x4 a4 = *(const LAS f32x4*)(scr + 8 * g + 4 * hi);
; #pragma unroll
;                     for (int d = 0; d < 4; ++d) { O[d][4 * g + 0] *= a4[0]; O[d][4 * g + 1] *= a4[1]; O[d][4 * g + 2] *= a4[2]; O[d][4 * g + 3] *= a4[3]; } }
;                 asm volatile("s_waitcnt lgkmcnt(0)" ::: "memory");
;             }
; #pragma unroll
;             for (int r = 0; r < 16; ++r) { p0[r] -= delta; p1[r] -= delta; }
.LatA_recnn_2:
	v_max3_f32 v251, v84, v85, v86
	v_max3_f32 v252, v87, v88, v89
	v_max3_f32 v251, v251, v90, v91
	v_max3_f32 v252, v252, v92, v93
	v_max3_f32 v251, v251, v94, v95
	v_max3_f32 v252, v252, v96, v97
	v_max3_f32 v251, v251, v98, v99
	v_max3_f32 v252, v252, v100, v101
	v_max3_f32 v251, v251, v102, v103
	v_max3_f32 v252, v252, v104, v105
	v_max3_f32 v251, v251, v106, v107
	v_max3_f32 v252, v252, v108, v109
	v_max3_f32 v251, v251, v110, v111
	v_max3_f32 v252, v252, v112, v113
	v_max3_f32 v251, v251, v114, v115
	v_max_f32_e32 v251, v251, v252
	v_mov_b32_e32 v252, v251
	s_nop 1
	v_permlane32_swap_b32_e32 v251, v252
	v_max_f32_e32 v251, v251, v252
	v_max_f32_e32 v253, 0, v251
	v_exp_f32_e64 v254, -v253
	v_add_f32_e32 v186, v186, v253
	s_nop 0
	v_mul_f32_e32 v150, v150, v254
	v_mul_f32_e32 v151, v151, v254
	ds_write_b32 v184, v254
	s_waitcnt lgkmcnt(0)
	ds_read_b128 v[132:135], v185
	ds_read_b128 v[136:139], v185 offset:32
	ds_read_b128 v[140:143], v185 offset:64
	ds_read_b128 v[144:147], v185 offset:96
	s_waitcnt lgkmcnt(0)
	v_pk_mul_f32 v[20:21], v[20:21], v[132:133]
	v_pk_mul_f32 v[22:23], v[22:23], v[134:135]
	v_pk_mul_f32 v[24:25], v[24:25], v[136:137]
	v_pk_mul_f32 v[26:27], v[26:27], v[138:139]
	v_pk_mul_f32 v[28:29], v[28:29], v[140:141]
	v_pk_mul_f32 v[30:31], v[30:31], v[142:143]
	v_pk_mul_f32 v[32:33], v[32:33], v[144:145]
	v_pk_mul_f32 v[34:35], v[34:35], v[146:147]
	v_pk_mul_f32 v[36:37], v[36:37], v[132:133]
	v_pk_mul_f32 v[38:39], v[38:39], v[134:135]
	v_pk_mul_f32 v[40:41], v[40:41], v[136:137]
	v_pk_mul_f32 v[42:43], v[42:43], v[138:139]
	v_pk_mul_f32 v[44:45], v[44:45], v[140:141]
	v_pk_mul_f32 v[46:47], v[46:47], v[142:143]
	v_pk_mul_f32 v[48:49], v[48:49], v[144:145]
	v_pk_mul_f32 v[50:51], v[50:51], v[146:147]
	v_pk_mul_f32 v[52:53], v[52:53], v[132:133]
	v_pk_mul_f32 v[54:55], v[54:55], v[134:135]
	v_pk_mul_f32 v[56:57], v[56:57], v[136:137]
	v_pk_mul_f32 v[58:59], v[58:59], v[138:139]
	v_pk_mul_f32 v[60:61], v[60:61], v[140:141]
	v_pk_mul_f32 v[62:63], v[62:63], v[142:143]
	v_pk_mul_f32 v[64:65], v[64:65], v[144:145]
	v_pk_mul_f32 v[66:67], v[66:67], v[146:147]
	v_pk_mul_f32 v[68:69], v[68:69], v[132:133]
	v_pk_mul_f32 v[70:71], v[70:71], v[134:135]
	v_pk_mul_f32 v[72:73], v[72:73], v[136:137]
	v_pk_mul_f32 v[74:75], v[74:75], v[138:139]
	v_pk_mul_f32 v[76:77], v[76:77], v[140:141]
	v_pk_mul_f32 v[78:79], v[78:79], v[142:143]
	v_pk_mul_f32 v[80:81], v[80:81], v[144:145]
	v_pk_mul_f32 v[82:83], v[82:83], v[146:147]
	v_mov_b32_e32 v252, v253
	v_pk_add_f32 v[84:85], v[84:85], v[252:253] neg_lo:[0,1] neg_hi:[0,1]
	v_pk_add_f32 v[86:87], v[86:87], v[252:253] neg_lo:[0,1] neg_hi:[0,1]
	v_pk_add_f32 v[88:89], v[88:89], v[252:253] neg_lo:[0,1] neg_hi:[0,1]
	v_pk_add_f32 v[90:91], v[90:91], v[252:253] neg_lo:[0,1] neg_hi:[0,1]
	v_pk_add_f32 v[92:93], v[92:93], v[252:253] neg_lo:[0,1] neg_hi:[0,1]
	v_pk_add_f32 v[94:95], v[94:95], v[252:253] neg_lo:[0,1] neg_hi:[0,1]
	v_pk_add_f32 v[96:97], v[96:97], v[252:253] neg_lo:[0,1] neg_hi:[0,1]
	v_pk_add_f32 v[98:99], v[98:99], v[252:253] neg_lo:[0,1] neg_hi:[0,1]
	v_pk_add_f32 v[100:101], v[100:101], v[252:253] neg_lo:[0,1] neg_hi:[0,1]
	v_pk_add_f32 v[102:103], v[102:103], v[252:253] neg_lo:[0,1] neg_hi:[0,1]
	v_pk_add_f32 v[104:105], v[104:105], v[252:253] neg_lo:[0,1] neg_hi:[0,1]
	v_pk_add_f32 v[106:107], v[106:107], v[252:253] neg_lo:[0,1] neg_hi:[0,1]
	v_pk_add_f32 v[108:109], v[108:109], v[252:253] neg_lo:[0,1] neg_hi:[0,1]
	v_pk_add_f32 v[110:111], v[110:111], v[252:253] neg_lo:[0,1] neg_hi:[0,1]
	v_pk_add_f32 v[112:113], v[112:113], v[252:253] neg_lo:[0,1] neg_hi:[0,1]
	v_pk_add_f32 v[114:115], v[114:115], v[252:253] neg_lo:[0,1] neg_hi:[0,1]
	v_pk_add_f32 v[188:189], v[188:189], v[252:253] neg_lo:[0,1] neg_hi:[0,1]
	v_pk_add_f32 v[190:191], v[190:191], v[252:253] neg_lo:[0,1] neg_hi:[0,1]
	v_pk_add_f32 v[192:193], v[192:193], v[252:253] neg_lo:[0,1] neg_hi:[0,1]
	v_pk_add_f32 v[194:195], v[194:195], v[252:253] neg_lo:[0,1] neg_hi:[0,1]
	v_pk_add_f32 v[196:197], v[196:197], v[252:253] neg_lo:[0,1] neg_hi:[0,1]
	v_pk_add_f32 v[198:199], v[198:199], v[252:253] neg_lo:[0,1] neg_hi:[0,1]
	v_pk_add_f32 v[200:201], v[200:201], v[252:253] neg_lo:[0,1] neg_hi:[0,1]
	v_pk_add_f32 v[202:203], v[202:203], v[252:253] neg_lo:[0,1] neg_hi:[0,1]
; #define VREADS1(arr, d_) do { const unsigned ad_ = vbase ^ (unsigned)((d_) << 6); __builtin_amdgcn_sched_barrier(0); \
;         _Pragma("unroll") for (int ks_ = 0; ks_ < 4; ++ks_) { VTR(arr[ks_ * 2], ad_, ks_ * 4096); VTR(arr[ks_ * 2 + 1], ad_, ks_ * 4096 + 2048); } __builtin_amdgcn_sched_barrier(0); } while (0)
; #define PV1(arr, d_) do { _Pragma("unroll") for (int ks_ = 0; ks_ < 4; ++ks_) { const s16x4 lo_ = arr[ks_ * 2], hh_ = arr[ks_ * 2 + 1]; \
;         const bf16x8 bv_ = (bf16x8){lo_[0], lo_[1], lo_[2], lo_[3], hh_[0], hh_[1], hh_[2], hh_[3]}; \
;         O[d_] = __builtin_amdgcn_mfma_f32_32x32x16_bf16(pa[ks_], bv_, O[d_], 0, 0, 0); } __builtin_amdgcn_sched_barrier(0); } while (0)
; #define LGKM0() do { __builtin_amdgcn_sched_barrier(0); asm volatile("s_waitcnt lgkmcnt(0)" ::: "memory"); __builtin_amdgcn_sched_barrier(0); } while (0)
; __device__ __forceinline__ void attn_unit(LAS unsigned char* lds, const bf16_t* Z, bf16_t* A2, const float* tabg, int seq_base, int S, int h, int qb, float lam) {
;     ...
;         { const float coff = cc - mu;
;           if (__any(!(coff == coff_cur))) { coff_cur = coff;
; #pragma unroll
;               for (int r = 0; r < 16; ++r) cblk[r] = coff;
;               asm volatile("" : "+v"(cblk)); } }
;     ...
;             for (int r = 0; r < 16; ++r) { p0[r] -= delta; p1[r] -= delta; }
;             asm volatile("" : "+v"(p0), "+v"(p1));
;         }
; #pragma unroll
;         for (int r = 0; r < 16; ++r) { p0[r] = __builtin_amdgcn_exp2f(p0[r]); p1[r] = __builtin_amdgcn_exp2f(p1[r]); }
; #pragma unroll
;         for (int r = 0; r < 16; r += 2) { ls2 += (f32x2){p0[r], p0[r + 1]}; ls2 += (f32x2){p1[r], p1[r + 1]}; }
;         bf16x8 pa[4]; pa[0] = pack8(p0, 0); pa[1] = pack8(p0, 8); pa[2] = pack8(p1, 0); pa[3] = pack8(p1, 8);
;         LGKM0(); VREADS1(vb, 1); PV1(va, 0); LGKM0(); VREADS1(va, 2); PV1(vb, 1); LGKM0(); VREADS1(vb, 3); PV1(va, 2); LGKM0(); PV1(vb, 3);
	v_pk_add_f32 v[204:205], v[204:205], v[252:253] neg_lo:[0,1] neg_hi:[0,1]
	v_pk_add_f32 v[206:207], v[206:207], v[252:253] neg_lo:[0,1] neg_hi:[0,1]
	v_pk_add_f32 v[208:209], v[208:209], v[252:253] neg_lo:[0,1] neg_hi:[0,1]
	v_pk_add_f32 v[210:211], v[210:211], v[252:253] neg_lo:[0,1] neg_hi:[0,1]
	v_pk_add_f32 v[212:213], v[212:213], v[252:253] neg_lo:[0,1] neg_hi:[0,1]
	v_pk_add_f32 v[214:215], v[214:215], v[252:253] neg_lo:[0,1] neg_hi:[0,1]
	v_pk_add_f32 v[216:217], v[216:217], v[252:253] neg_lo:[0,1] neg_hi:[0,1]
	v_pk_add_f32 v[218:219], v[218:219], v[252:253] neg_lo:[0,1] neg_hi:[0,1]
	v_exp_f32_e32 v84, v84
	v_exp_f32_e32 v85, v85
	v_exp_f32_e32 v86, v86
	v_exp_f32_e32 v87, v87
	v_add_f32_e32 v252, v84, v86
	v_exp_f32_e32 v88, v88
	v_add_f32_e32 v253, v85, v87
	v_exp_f32_e32 v89, v89
	v_cvt_pk_bf16_f32 v84, v84, v85
	v_exp_f32_e32 v90, v90
	v_cvt_pk_bf16_f32 v85, v86, v87
	v_exp_f32_e32 v91, v91
	v_add_f32_e32 v252, v252, v88
	v_add_f32_e32 v253, v253, v89
	v_cvt_pk_bf16_f32 v86, v88, v89
	v_add_f32_e32 v252, v252, v90
	v_add_f32_e32 v253, v253, v91
	v_cvt_pk_bf16_f32 v87, v90, v91
	v_exp_f32_e32 v92, v92
	v_exp_f32_e32 v93, v93
	v_exp_f32_e32 v94, v94
	v_add_f32_e32 v252, v252, v92
	v_exp_f32_e32 v95, v95
	v_add_f32_e32 v253, v253, v93
	v_exp_f32_e32 v96, v96
	v_add_f32_e32 v252, v252, v94
	v_exp_f32_e32 v97, v97
	v_add_f32_e32 v253, v253, v95
	v_exp_f32_e32 v98, v98
	v_cvt_pk_bf16_f32 v88, v92, v93
	v_exp_f32_e32 v99, v99
	v_cvt_pk_bf16_f32 v89, v94, v95
	v_add_f32_e32 v252, v252, v96
	v_add_f32_e32 v253, v253, v97
	v_cvt_pk_bf16_f32 v90, v96, v97
	v_add_f32_e32 v252, v252, v98
	v_add_f32_e32 v253, v253, v99
	v_cvt_pk_bf16_f32 v91, v98, v99
	v_exp_f32_e32 v100, v100
	v_exp_f32_e32 v101, v101
	v_exp_f32_e32 v102, v102
	v_add_f32_e32 v252, v252, v100
	v_exp_f32_e32 v103, v103
	v_add_f32_e32 v253, v253, v101
	v_exp_f32_e32 v104, v104
	v_add_f32_e32 v252, v252, v102
	v_exp_f32_e32 v105, v105
	v_add_f32_e32 v253, v253, v103
	v_exp_f32_e32 v106, v106
	v_cvt_pk_bf16_f32 v100, v100, v101
	v_exp_f32_e32 v107, v107
	v_cvt_pk_bf16_f32 v101, v102, v103
	v_add_f32_e32 v252, v252, v104
	v_add_f32_e32 v253, v253, v105
	v_cvt_pk_bf16_f32 v102, v104, v105
	v_add_f32_e32 v252, v252, v106
	v_add_f32_e32 v253, v253, v107
	v_cvt_pk_bf16_f32 v103, v106, v107
	v_exp_f32_e32 v108, v108
	v_exp_f32_e32 v109, v109
	v_exp_f32_e32 v110, v110
	v_add_f32_e32 v252, v252, v108
	v_exp_f32_e32 v111, v111
	v_add_f32_e32 v253, v253, v109
	v_exp_f32_e32 v112, v112
	v_add_f32_e32 v252, v252, v110
	v_exp_f32_e32 v113, v113
	v_add_f32_e32 v253, v253, v111
	v_exp_f32_e32 v114, v114
	v_cvt_pk_bf16_f32 v104, v108, v109
	v_exp_f32_e32 v115, v115
	v_cvt_pk_bf16_f32 v105, v110, v111
	v_add_f32_e32 v252, v252, v112
	v_add_f32_e32 v253, v253, v113
	v_cvt_pk_bf16_f32 v106, v112, v113
	v_add_f32_e32 v252, v252, v114
	v_add_f32_e32 v253, v253, v115
	v_cvt_pk_bf16_f32 v107, v114, v115
	s_mov_b32 s37, s43
	s_mov_b32 s35, s37
	v_mov_b32_e32 v251, 0
	s_cmp_eq_u32 s37, 1
	s_cselect_b64 vcc, -1, 0
	v_cndmask_b32_e32 v251, v251, v177, vcc
	s_cmp_eq_u32 s37, 2
	s_cselect_b64 vcc, -1, 0
	v_cndmask_b32_e32 v251, v251, v178, vcc
	v_sub_f32_e32 v2, v251, v186
	v_mov_b32_e32 v3, v2
	v_mov_b64_e32 v[4:5], v[2:3]
	v_mov_b64_e32 v[6:7], v[2:3]
	v_mov_b64_e32 v[8:9], v[2:3]
	v_mov_b64_e32 v[10:11], v[2:3]
	v_mov_b64_e32 v[12:13], v[2:3]
	v_mov_b64_e32 v[14:15], v[2:3]
	v_mov_b64_e32 v[16:17], v[2:3]
	ds_read_b64_tr_b16 v[132:133], v228 offset:32768
	ds_read_b64_tr_b16 v[134:135], v228 offset:34816
	ds_read_b64_tr_b16 v[136:137], v229 offset:32768
	ds_read_b64_tr_b16 v[138:139], v229 offset:34816
	ds_read_b64_tr_b16 v[140:141], v230 offset:32768
	ds_read_b64_tr_b16 v[142:143], v230 offset:34816
	ds_read_b64_tr_b16 v[144:145], v231 offset:32768
	ds_read_b64_tr_b16 v[146:147], v231 offset:34816
	ds_read_b64_tr_b16 v[220:221], v228 offset:36864
	ds_read_b64_tr_b16 v[222:223], v228 offset:38912
	ds_read_b64_tr_b16 v[224:225], v229 offset:36864
	ds_read_b64_tr_b16 v[226:227], v229 offset:38912
	ds_read_b64_tr_b16 v[232:233], v230 offset:36864
	ds_read_b64_tr_b16 v[234:235], v230 offset:38912
	s_nop 1
	s_cmp_eq_u32 s42, 0
	s_cbranch_scc1 .LatA_recret_h2
	s_cmp_eq_u32 s42, 1
	s_cbranch_scc1 .LatA_recret_m2
	s_branch .LatA_recret_x2

; #define LAS __attribute__((address_space(3)))
; __device__ __forceinline__ float max2f(float a, float b) { float r; asm("v_max_f32_e32 %0, %1, %2" : "=v"(r) : "v"(a), "v"(b)); return r; }
; __device__ __forceinline__ void attn_unit(LAS unsigned char* lds, const bf16_t* Z, bf16_t* A2, const float* tabg, int seq_base, int S, int h, int qb, float lam) {
;     ...
;         if (first || __any(mx > THR)) {
;             { auto rr = __builtin_amdgcn_permlane32_swap(__float_as_uint(mx), __float_as_uint(mx), false, false); mx = max2f(__uint_as_float(rr[0]), __uint_as_float(rr[1])); }
;             const float delta = first ? mx : fmaxf(mx, 0.f);
;             const float alpha = first ? 1.0f : __builtin_amdgcn_exp2f(-delta);
;             mu += delta; ls2 *= alpha;
;             if (!first) {
;                 asm volatile("" ::: "memory");
;                 scr[r32] = alpha;
;                 asm volatile("s_waitcnt lgkmcnt(0)" ::: "memory");
; #pragma unroll
;                 for (int g = 0; g < 4; ++g) { const f32x4 a4 = *(const LAS f32x4*)(scr + 8 * g + 4 * hi);
; #pragma unroll
;                     for (int d = 0; d < 4; ++d) { O[d][4 * g + 0] *= a4[0]; O[d][4 * g + 1] *= a4[1]; O[d][4 * g + 2] *= a4[2]; O[d][4 * g + 3] *= a4[3]; } }
;                 asm volatile("s_waitcnt lgkmcnt(0)" ::: "memory");
;             }
; #pragma unroll
;             for (int r = 0; r < 16; ++r) { p0[r] -= delta; p1[r] -= delta; }
.LatA_recnn_3:
	v_max3_f32 v251, v188, v189, v190
	v_max3_f32 v252, v191, v192, v193
	v_max3_f32 v251, v251, v194, v195
	v_max3_f32 v252, v252, v196, v197
	v_max3_f32 v251, v251, v198, v199
	v_max3_f32 v252, v252, v200, v201
	v_max3_f32 v251, v251, v202, v203
	v_max3_f32 v252, v252, v204, v205
	v_max3_f32 v251, v251, v206, v207
	v_max3_f32 v252, v252, v208, v209
	v_max3_f32 v251, v251, v210, v211
	v_max3_f32 v252, v252, v212, v213
	v_max3_f32 v251, v251, v214, v215
	v_max3_f32 v252, v252, v216, v217
	v_max3_f32 v251, v251, v218, v219
	v_max_f32_e32 v251, v251, v252
	v_mov_b32_e32 v252, v251
	s_nop 1
	v_permlane32_swap_b32_e32 v251, v252
	v_max_f32_e32 v251, v251, v252
	v_max_f32_e32 v253, 0, v251
	v_exp_f32_e64 v254, -v253
	v_add_f32_e32 v186, v186, v253
	s_nop 0
	v_mul_f32_e32 v150, v150, v254
	v_mul_f32_e32 v151, v151, v254
	ds_write_b32 v184, v254
	s_waitcnt lgkmcnt(0)
	ds_read_b128 v[132:135], v185
	ds_read_b128 v[136:139], v185 offset:32
	ds_read_b128 v[140:143], v185 offset:64
	ds_read_b128 v[144:147], v185 offset:96
	s_waitcnt lgkmcnt(0)
	v_pk_mul_f32 v[20:21], v[20:21], v[132:133]
	v_pk_mul_f32 v[22:23], v[22:23], v[134:135]
	v_pk_mul_f32 v[24:25], v[24:25], v[136:137]
	v_pk_mul_f32 v[26:27], v[26:27], v[138:139]
	v_pk_mul_f32 v[28:29], v[28:29], v[140:141]
	v_pk_mul_f32 v[30:31], v[30:31], v[142:143]
	v_pk_mul_f32 v[32:33], v[32:33], v[144:145]
	v_pk_mul_f32 v[34:35], v[34:35], v[146:147]
	v_pk_mul_f32 v[36:37], v[36:37], v[132:133]
	v_pk_mul_f32 v[38:39], v[38:39], v[134:135]
	v_pk_mul_f32 v[40:41], v[40:41], v[136:137]
	v_pk_mul_f32 v[42:43], v[42:43], v[138:139]
	v_pk_mul_f32 v[44:45], v[44:45], v[140:141]
	v_pk_mul_f32 v[46:47], v[46:47], v[142:143]
	v_pk_mul_f32 v[48:49], v[48:49], v[144:145]
	v_pk_mul_f32 v[50:51], v[50:51], v[146:147]
	v_pk_mul_f32 v[52:53], v[52:53], v[132:133]
	v_pk_mul_f32 v[54:55], v[54:55], v[134:135]
	v_pk_mul_f32 v[56:57], v[56:57], v[136:137]
	v_pk_mul_f32 v[58:59], v[58:59], v[138:139]
	v_pk_mul_f32 v[60:61], v[60:61], v[140:141]
	v_pk_mul_f32 v[62:63], v[62:63], v[142:143]
	v_pk_mul_f32 v[64:65], v[64:65], v[144:145]
	v_pk_mul_f32 v[66:67], v[66:67], v[146:147]
	v_pk_mul_f32 v[68:69], v[68:69], v[132:133]
	v_pk_mul_f32 v[70:71], v[70:71], v[134:135]
	v_pk_mul_f32 v[72:73], v[72:73], v[136:137]
	v_pk_mul_f32 v[74:75], v[74:75], v[138:139]
	v_pk_mul_f32 v[76:77], v[76:77], v[140:141]
	v_pk_mul_f32 v[78:79], v[78:79], v[142:143]
	v_pk_mul_f32 v[80:81], v[80:81], v[144:145]
	v_pk_mul_f32 v[82:83], v[82:83], v[146:147]
	v_mov_b32_e32 v252, v253
	v_pk_add_f32 v[188:189], v[188:189], v[252:253] neg_lo:[0,1] neg_hi:[0,1]
	v_pk_add_f32 v[190:191], v[190:191], v[252:253] neg_lo:[0,1] neg_hi:[0,1]
	v_pk_add_f32 v[192:193], v[192:193], v[252:253] neg_lo:[0,1] neg_hi:[0,1]
	v_pk_add_f32 v[194:195], v[194:195], v[252:253] neg_lo:[0,1] neg_hi:[0,1]
	v_pk_add_f32 v[196:197], v[196:197], v[252:253] neg_lo:[0,1] neg_hi:[0,1]
	v_pk_add_f32 v[198:199], v[198:199], v[252:253] neg_lo:[0,1] neg_hi:[0,1]
	v_pk_add_f32 v[200:201], v[200:201], v[252:253] neg_lo:[0,1] neg_hi:[0,1]
	v_pk_add_f32 v[202:203], v[202:203], v[252:253] neg_lo:[0,1] neg_hi:[0,1]
	v_pk_add_f32 v[204:205], v[204:205], v[252:253] neg_lo:[0,1] neg_hi:[0,1]
	v_pk_add_f32 v[206:207], v[206:207], v[252:253] neg_lo:[0,1] neg_hi:[0,1]
	v_pk_add_f32 v[208:209], v[208:209], v[252:253] neg_lo:[0,1] neg_hi:[0,1]
	v_pk_add_f32 v[210:211], v[210:211], v[252:253] neg_lo:[0,1] neg_hi:[0,1]
	v_pk_add_f32 v[212:213], v[212:213], v[252:253] neg_lo:[0,1] neg_hi:[0,1]
	v_pk_add_f32 v[214:215], v[214:215], v[252:253] neg_lo:[0,1] neg_hi:[0,1]
	v_pk_add_f32 v[216:217], v[216:217], v[252:253] neg_lo:[0,1] neg_hi:[0,1]
	v_pk_add_f32 v[218:219], v[218:219], v[252:253] neg_lo:[0,1] neg_hi:[0,1]
	v_pk_add_f32 v[84:85], v[84:85], v[252:253] neg_lo:[0,1] neg_hi:[0,1]
	v_pk_add_f32 v[86:87], v[86:87], v[252:253] neg_lo:[0,1] neg_hi:[0,1]
	v_pk_add_f32 v[88:89], v[88:89], v[252:253] neg_lo:[0,1] neg_hi:[0,1]
	v_pk_add_f32 v[90:91], v[90:91], v[252:253] neg_lo:[0,1] neg_hi:[0,1]
	v_pk_add_f32 v[92:93], v[92:93], v[252:253] neg_lo:[0,1] neg_hi:[0,1]
	v_pk_add_f32 v[94:95], v[94:95], v[252:253] neg_lo:[0,1] neg_hi:[0,1]
	v_pk_add_f32 v[96:97], v[96:97], v[252:253] neg_lo:[0,1] neg_hi:[0,1]
	v_pk_add_f32 v[98:99], v[98:99], v[252:253] neg_lo:[0,1] neg_hi:[0,1]
; #define VREADS1(arr, d_) do { const unsigned ad_ = vbase ^ (unsigned)((d_) << 6); __builtin_amdgcn_sched_barrier(0); \
;         _Pragma("unroll") for (int ks_ = 0; ks_ < 4; ++ks_) { VTR(arr[ks_ * 2], ad_, ks_ * 4096); VTR(arr[ks_ * 2 + 1], ad_, ks_ * 4096 + 2048); } __builtin_amdgcn_sched_barrier(0); } while (0)
; #define PV1(arr, d_) do { _Pragma("unroll") for (int ks_ = 0; ks_ < 4; ++ks_) { const s16x4 lo_ = arr[ks_ * 2], hh_ = arr[ks_ * 2 + 1]; \
;         const bf16x8 bv_ = (bf16x8){lo_[0], lo_[1], lo_[2], lo_[3], hh_[0], hh_[1], hh_[2], hh_[3]}; \
;         O[d_] = __builtin_amdgcn_mfma_f32_32x32x16_bf16(pa[ks_], bv_, O[d_], 0, 0, 0); } __builtin_amdgcn_sched_barrier(0); } while (0)
; #define LGKM0() do { __builtin_amdgcn_sched_barrier(0); asm volatile("s_waitcnt lgkmcnt(0)" ::: "memory"); __builtin_amdgcn_sched_barrier(0); } while (0)
; __device__ __forceinline__ void attn_unit(LAS unsigned char* lds, const bf16_t* Z, bf16_t* A2, const float* tabg, int seq_base, int S, int h, int qb, float lam) {
;     ...
;         { const float coff = cc - mu;
;           if (__any(!(coff == coff_cur))) { coff_cur = coff;
; #pragma unroll
;               for (int r = 0; r < 16; ++r) cblk[r] = coff;
;               asm volatile("" : "+v"(cblk)); } }
;     ...
;             for (int r = 0; r < 16; ++r) { p0[r] -= delta; p1[r] -= delta; }
;             asm volatile("" : "+v"(p0), "+v"(p1));
;         }
; #pragma unroll
;         for (int r = 0; r < 16; ++r) { p0[r] = __builtin_amdgcn_exp2f(p0[r]); p1[r] = __builtin_amdgcn_exp2f(p1[r]); }
; #pragma unroll
;         for (int r = 0; r < 16; r += 2) { ls2 += (f32x2){p0[r], p0[r + 1]}; ls2 += (f32x2){p1[r], p1[r + 1]}; }
;         bf16x8 pa[4]; pa[0] = pack8(p0, 0); pa[1] = pack8(p0, 8); pa[2] = pack8(p1, 0); pa[3] = pack8(p1, 8);
;         LGKM0(); VREADS1(vb, 1); PV1(va, 0); LGKM0(); VREADS1(va, 2); PV1(vb, 1); LGKM0(); VREADS1(vb, 3); PV1(va, 2); LGKM0(); PV1(vb, 3);
	v_pk_add_f32 v[100:101], v[100:101], v[252:253] neg_lo:[0,1] neg_hi:[0,1]
	v_pk_add_f32 v[102:103], v[102:103], v[252:253] neg_lo:[0,1] neg_hi:[0,1]
	v_pk_add_f32 v[104:105], v[104:105], v[252:253] neg_lo:[0,1] neg_hi:[0,1]
	v_pk_add_f32 v[106:107], v[106:107], v[252:253] neg_lo:[0,1] neg_hi:[0,1]
	v_pk_add_f32 v[108:109], v[108:109], v[252:253] neg_lo:[0,1] neg_hi:[0,1]
	v_pk_add_f32 v[110:111], v[110:111], v[252:253] neg_lo:[0,1] neg_hi:[0,1]
	v_pk_add_f32 v[112:113], v[112:113], v[252:253] neg_lo:[0,1] neg_hi:[0,1]
	v_pk_add_f32 v[114:115], v[114:115], v[252:253] neg_lo:[0,1] neg_hi:[0,1]
	v_exp_f32_e32 v188, v188
	v_exp_f32_e32 v189, v189
	v_exp_f32_e32 v190, v190
	v_exp_f32_e32 v191, v191
	v_add_f32_e32 v252, v188, v190
	v_exp_f32_e32 v192, v192
	v_add_f32_e32 v253, v189, v191
	v_exp_f32_e32 v193, v193
	v_cvt_pk_bf16_f32 v188, v188, v189
	v_exp_f32_e32 v194, v194
	v_cvt_pk_bf16_f32 v189, v190, v191
	v_exp_f32_e32 v195, v195
	v_add_f32_e32 v252, v252, v192
	v_add_f32_e32 v253, v253, v193
	v_cvt_pk_bf16_f32 v190, v192, v193
	v_add_f32_e32 v252, v252, v194
	v_add_f32_e32 v253, v253, v195
	v_cvt_pk_bf16_f32 v191, v194, v195
	v_exp_f32_e32 v196, v196
	v_exp_f32_e32 v197, v197
	v_exp_f32_e32 v198, v198
	v_add_f32_e32 v252, v252, v196
	v_exp_f32_e32 v199, v199
	v_add_f32_e32 v253, v253, v197
	v_exp_f32_e32 v200, v200
	v_add_f32_e32 v252, v252, v198
	v_exp_f32_e32 v201, v201
	v_add_f32_e32 v253, v253, v199
	v_exp_f32_e32 v202, v202
	v_cvt_pk_bf16_f32 v192, v196, v197
	v_exp_f32_e32 v203, v203
	v_cvt_pk_bf16_f32 v193, v198, v199
	v_add_f32_e32 v252, v252, v200
	v_add_f32_e32 v253, v253, v201
	v_cvt_pk_bf16_f32 v194, v200, v201
	v_add_f32_e32 v252, v252, v202
	v_add_f32_e32 v253, v253, v203
	v_cvt_pk_bf16_f32 v195, v202, v203
	v_exp_f32_e32 v204, v204
	v_exp_f32_e32 v205, v205
	v_exp_f32_e32 v206, v206
	v_add_f32_e32 v252, v252, v204
	v_exp_f32_e32 v207, v207
	v_add_f32_e32 v253, v253, v205
	v_exp_f32_e32 v208, v208
	v_add_f32_e32 v252, v252, v206
	v_exp_f32_e32 v209, v209
	v_add_f32_e32 v253, v253, v207
	v_exp_f32_e32 v210, v210
	v_cvt_pk_bf16_f32 v204, v204, v205
	v_exp_f32_e32 v211, v211
	v_cvt_pk_bf16_f32 v205, v206, v207
	v_add_f32_e32 v252, v252, v208
	v_add_f32_e32 v253, v253, v209
	v_cvt_pk_bf16_f32 v206, v208, v209
	v_add_f32_e32 v252, v252, v210
	v_add_f32_e32 v253, v253, v211
	v_cvt_pk_bf16_f32 v207, v210, v211
	v_exp_f32_e32 v212, v212
	v_exp_f32_e32 v213, v213
	v_exp_f32_e32 v214, v214
	v_add_f32_e32 v252, v252, v212
	v_exp_f32_e32 v215, v215
	v_add_f32_e32 v253, v253, v213
	v_exp_f32_e32 v216, v216
	v_add_f32_e32 v252, v252, v214
	v_exp_f32_e32 v217, v217
	v_add_f32_e32 v253, v253, v215
	v_exp_f32_e32 v218, v218
	v_cvt_pk_bf16_f32 v208, v212, v213
	v_exp_f32_e32 v219, v219
	v_cvt_pk_bf16_f32 v209, v214, v215
	v_add_f32_e32 v252, v252, v216
	v_add_f32_e32 v253, v253, v217
	v_cvt_pk_bf16_f32 v210, v216, v217
	v_add_f32_e32 v252, v252, v218
	v_add_f32_e32 v253, v253, v219
	v_cvt_pk_bf16_f32 v211, v218, v219
	s_mov_b32 s37, s43
	s_mov_b32 s35, s37
	v_mov_b32_e32 v251, 0
	s_cmp_eq_u32 s37, 1
	s_cselect_b64 vcc, -1, 0
	v_cndmask_b32_e32 v251, v251, v177, vcc
	s_cmp_eq_u32 s37, 2
	s_cselect_b64 vcc, -1, 0
	v_cndmask_b32_e32 v251, v251, v178, vcc
	v_sub_f32_e32 v2, v251, v186
	v_mov_b32_e32 v3, v2
	v_mov_b64_e32 v[4:5], v[2:3]
	v_mov_b64_e32 v[6:7], v[2:3]
	v_mov_b64_e32 v[8:9], v[2:3]
	v_mov_b64_e32 v[10:11], v[2:3]
	v_mov_b64_e32 v[12:13], v[2:3]
	v_mov_b64_e32 v[14:15], v[2:3]
	v_mov_b64_e32 v[16:17], v[2:3]
	ds_read_b64_tr_b16 v[132:133], v168 offset:0
	ds_read_b64_tr_b16 v[134:135], v168 offset:2048
	ds_read_b64_tr_b16 v[136:137], v169 offset:0
	ds_read_b64_tr_b16 v[138:139], v169 offset:2048
	ds_read_b64_tr_b16 v[140:141], v170 offset:0
	ds_read_b64_tr_b16 v[142:143], v170 offset:2048
	ds_read_b64_tr_b16 v[144:145], v171 offset:0
	ds_read_b64_tr_b16 v[146:147], v171 offset:2048
	ds_read_b64_tr_b16 v[220:221], v168 offset:4096
	ds_read_b64_tr_b16 v[222:223], v168 offset:6144
	ds_read_b64_tr_b16 v[224:225], v169 offset:4096
	ds_read_b64_tr_b16 v[226:227], v169 offset:6144
	ds_read_b64_tr_b16 v[232:233], v170 offset:4096
	ds_read_b64_tr_b16 v[234:235], v170 offset:6144
	s_nop 1
	s_cmp_eq_u32 s42, 0
	s_cbranch_scc1 .LatA_recret_h3
	s_cmp_eq_u32 s42, 1
	s_cbranch_scc1 .LatA_recret_m3
	s_branch .LatA_recret_x1

; __device__ __forceinline__ void attn_unit(LAS unsigned char* lds, const bf16_t* Z, bf16_t* A2, const float* tabg, int seq_base, int S, int h, int qb, float lam) {
;     ...
;         if (kv0 - (qlo + 31) >= 128) { near = false; cc = tabR; } else if (qlo - (kv0 + 63) >= 128) { near = false; cc = tabL; }
;         { const float coff = cc - mu;
;           if (__any(!(coff == coff_cur))) { coff_cur = coff;
; #pragma unroll
;               for (int r = 0; r < 16; ++r) cblk[r] = coff;
;               asm volatile("" : "+v"(cblk)); } }
;         f32x16 p0, p1;
;         {
;             bf16x8 kf[8];
; #pragma unroll
;     ...
;         float mx = max2f(max16f(p0), max16f(p1));
;         const bool first = (t == 0);
;         if (first || __any(mx > THR)) {
;             { auto rr = __builtin_amdgcn_permlane32_swap(__float_as_uint(mx), __float_as_uint(mx), false, false); mx = max2f(__uint_as_float(rr[0]), __uint_as_float(rr[1])); }
;             const float delta = first ? mx : fmaxf(mx, 0.f);
;             const float alpha = first ? 1.0f : __builtin_amdgcn_exp2f(-delta);
;             mu += delta; ls2 *= alpha;
;             if (!first) {
;                 asm volatile("" ::: "memory");
;                 scr[r32] = alpha;
;                 asm volatile("s_waitcnt lgkmcnt(0)" ::: "memory");
; #pragma unroll
;                 for (int g = 0; g < 4; ++g) { const f32x4 a4 = *(const LAS f32x4*)(scr + 8 * g + 4 * hi);
; #pragma unroll
;                     for (int d = 0; d < 4; ++d) { O[d][4 * g + 0] *= a4[0]; O[d][4 * g + 1] *= a4[1]; O[d][4 * g + 2] *= a4[2]; O[d][4 * g + 3] *= a4[3]; } }
;                 asm volatile("s_waitcnt lgkmcnt(0)" ::: "memory");
;             }
; #pragma unroll
;             for (int r = 0; r < 16; ++r) { p0[r] -= delta; p1[r] -= delta; }
;             asm volatile("" : "+v"(p0), "+v"(p1));
;         }
; #pragma unroll
;         for (int r = 0; r < 16; ++r) { p0[r] = __builtin_amdgcn_exp2f(p0[r]); p1[r] = __builtin_amdgcn_exp2f(p1[r]); }
; #pragma unroll
;         for (int r = 0; r < 16; r += 2) { ls2 += (f32x2){p0[r], p0[r + 1]}; ls2 += (f32x2){p1[r], p1[r + 1]}; }
;         bf16x8 pa[4]; pa[0] = pack8(p0, 0); pa[1] = pack8(p0, 8); pa[2] = pack8(p1, 0); pa[3] = pack8(p1, 8);
;         LGKM0(); VREADS1(vb, 1); PV1(va, 0); LGKM0(); VREADS1(va, 2); PV1(vb, 1); LGKM0(); VREADS1(vb, 3); PV1(va, 2); LGKM0(); PV1(vb, 3);
.LatB_p0_nonear:
	v_max3_f32 v251, v84, v85, v86
	v_max3_f32 v252, v87, v88, v89
	v_max3_f32 v251, v251, v90, v91
	v_max3_f32 v252, v252, v92, v93
	v_max3_f32 v251, v251, v94, v95
	v_max3_f32 v252, v252, v96, v97
	v_max3_f32 v251, v251, v98, v99
	v_max3_f32 v252, v252, v100, v101
	v_max3_f32 v251, v251, v102, v103
	v_max3_f32 v252, v252, v104, v105
	v_max3_f32 v251, v251, v106, v107
	v_max3_f32 v252, v252, v108, v109
	v_max3_f32 v251, v251, v110, v111
	v_max3_f32 v252, v252, v112, v113
	v_max3_f32 v251, v251, v114, v115
	v_max_f32_e32 v251, v251, v252
	v_mov_b32_e32 v252, v251
	s_nop 1
	v_permlane32_swap_b32_e32 v251, v252
	v_max_f32_e32 v186, v251, v252
	v_sub_f32_e32 v84, v84, v186
	v_sub_f32_e32 v85, v85, v186
	v_sub_f32_e32 v86, v86, v186
	v_sub_f32_e32 v87, v87, v186
	v_sub_f32_e32 v88, v88, v186
	v_sub_f32_e32 v89, v89, v186
	v_sub_f32_e32 v90, v90, v186
	v_sub_f32_e32 v91, v91, v186
	v_sub_f32_e32 v92, v92, v186
	v_sub_f32_e32 v93, v93, v186
	v_sub_f32_e32 v94, v94, v186
	v_sub_f32_e32 v95, v95, v186
	v_sub_f32_e32 v96, v96, v186
	v_sub_f32_e32 v97, v97, v186
	v_sub_f32_e32 v98, v98, v186
	v_sub_f32_e32 v99, v99, v186
	v_sub_f32_e32 v100, v100, v186
	v_sub_f32_e32 v101, v101, v186
	v_sub_f32_e32 v102, v102, v186
	v_sub_f32_e32 v103, v103, v186
	v_sub_f32_e32 v104, v104, v186
	v_sub_f32_e32 v105, v105, v186
	v_sub_f32_e32 v106, v106, v186
	v_sub_f32_e32 v107, v107, v186
	v_sub_f32_e32 v108, v108, v186
	v_sub_f32_e32 v109, v109, v186
	v_sub_f32_e32 v110, v110, v186
	v_sub_f32_e32 v111, v111, v186
	v_sub_f32_e32 v112, v112, v186
	v_sub_f32_e32 v113, v113, v186
	v_sub_f32_e32 v114, v114, v186
	v_sub_f32_e32 v115, v115, v186
	s_add_u32 s29, s5, 64
	s_cmp_lt_u32 s29, s11
	s_cselect_b32 s24, 1, 0
	s_cmp_gt_u32 s29, s31
	s_cselect_b32 s30, 2, 0
	s_or_b32 s24, s24, s30
	s_mov_b32 s35, s24
	v_mov_b32_e32 v251, 0
	s_cmp_eq_u32 s24, 1
	s_cselect_b64 vcc, -1, 0
	v_cndmask_b32_e32 v251, v251, v177, vcc
	s_cmp_eq_u32 s24, 2
	s_cselect_b64 vcc, -1, 0
	v_cndmask_b32_e32 v251, v251, v178, vcc
	v_sub_f32_e32 v2, v251, v186
	v_mov_b32_e32 v3, v2
	v_mov_b64_e32 v[4:5], v[2:3]
	v_mov_b64_e32 v[6:7], v[2:3]
	v_mov_b64_e32 v[8:9], v[2:3]
	v_mov_b64_e32 v[10:11], v[2:3]
	v_mov_b64_e32 v[12:13], v[2:3]
	v_mov_b64_e32 v[14:15], v[2:3]
	v_mov_b64_e32 v[16:17], v[2:3]
	s_waitcnt vmcnt(0)
	s_barrier
	ds_read_b128 v[132:135], v19 offset:16384
	ds_read_b128 v[136:139], v19 offset:24576
	ds_read_b128 v[140:143], v180 offset:16384
	ds_read_b128 v[144:147], v180 offset:24576
	ds_read_b128 v[220:223], v181 offset:16384
	ds_read_b128 v[224:227], v181 offset:24576
	ds_read_b128 v[232:235], v182 offset:16384
	s_waitcnt lgkmcnt(6)
	s_add_u32 m0, s25, 0x1d000
	v_mfma_f32_32x32x16_bf16 v[188:203], v[132:135], v[116:119], v[2:17]
	global_load_lds_dwordx4 v172, s[8:9]
	ds_read_b128 v[236:239], v182 offset:24576
	v_exp_f32_e32 v84, v84
	v_exp_f32_e32 v85, v85
	v_exp_f32_e32 v86, v86
	v_exp_f32_e32 v87, v87
	v_add_f32_e32 v252, v84, v86
	v_exp_f32_e32 v88, v88
	v_add_f32_e32 v253, v85, v87
	v_exp_f32_e32 v89, v89
	s_waitcnt lgkmcnt(6)
	s_add_u32 m0, s27, 0x8000
	v_mfma_f32_32x32x16_bf16 v[204:219], v[136:139], v[116:119], v[2:17]
	global_load_lds_dwordx4 v174, s[8:9]
	ds_read_b64_tr_b16 v[132:133], v228 offset:0
	ds_read_b64_tr_b16 v[134:135], v228 offset:2048
	v_cvt_pk_bf16_f32 v84, v84, v85
	v_exp_f32_e32 v90, v90
	v_cvt_pk_bf16_f32 v85, v86, v87
	v_exp_f32_e32 v91, v91
	v_add_f32_e32 v252, v252, v88
	v_add_f32_e32 v253, v253, v89
	v_cvt_pk_bf16_f32 v86, v88, v89
	v_add_f32_e32 v252, v252, v90
	v_add_f32_e32 v253, v253, v91
	v_cvt_pk_bf16_f32 v87, v90, v91
	v_exp_f32_e32 v92, v92
	s_waitcnt lgkmcnt(7)
	s_add_u32 m0, s25, 0x1f000
	v_mfma_f32_32x32x16_bf16 v[188:203], v[140:143], v[120:123], v[188:203]
	global_load_lds_dwordx4 v173, s[8:9]
	ds_read_b64_tr_b16 v[136:137], v229 offset:0
	ds_read_b64_tr_b16 v[138:139], v229 offset:2048
	v_exp_f32_e32 v93, v93
	v_exp_f32_e32 v94, v94
	v_add_f32_e32 v252, v252, v92
	v_exp_f32_e32 v95, v95
	v_add_f32_e32 v253, v253, v93
	v_exp_f32_e32 v96, v96
	v_add_f32_e32 v252, v252, v94
	v_exp_f32_e32 v97, v97
	s_waitcnt lgkmcnt(8)
	s_add_u32 m0, s27, 0xa000
	v_mfma_f32_32x32x16_bf16 v[204:219], v[144:147], v[120:123], v[204:219]
	global_load_lds_dwordx4 v175, s[8:9]
	ds_read_b64_tr_b16 v[140:141], v230 offset:0
	ds_read_b64_tr_b16 v[142:143], v230 offset:2048
	v_add_f32_e32 v253, v253, v95
	v_exp_f32_e32 v98, v98
	v_cvt_pk_bf16_f32 v88, v92, v93
	v_exp_f32_e32 v99, v99
	v_cvt_pk_bf16_f32 v89, v94, v95
	v_add_f32_e32 v252, v252, v96
	v_add_f32_e32 v253, v253, v97
	v_cvt_pk_bf16_f32 v90, v96, v97
	v_add_f32_e32 v252, v252, v98
	v_add_f32_e32 v253, v253, v99
	v_cvt_pk_bf16_f32 v91, v98, v99
	s_waitcnt lgkmcnt(9)
	v_mfma_f32_32x32x16_bf16 v[188:203], v[220:223], v[124:127], v[188:203]
	ds_read_b64_tr_b16 v[144:145], v231 offset:0
	ds_read_b64_tr_b16 v[146:147], v231 offset:2048
	v_exp_f32_e32 v100, v100
	v_exp_f32_e32 v101, v101
	v_exp_f32_e32 v102, v102
	v_add_f32_e32 v252, v252, v100
	v_exp_f32_e32 v103, v103
	v_add_f32_e32 v253, v253, v101
	v_exp_f32_e32 v104, v104
	v_add_f32_e32 v252, v252, v102
	v_exp_f32_e32 v105, v105
	s_waitcnt lgkmcnt(10)
	v_mfma_f32_32x32x16_bf16 v[204:219], v[224:227], v[124:127], v[204:219]
	ds_read_b64_tr_b16 v[220:221], v228 offset:4096
	ds_read_b64_tr_b16 v[222:223], v228 offset:6144
	v_add_f32_e32 v253, v253, v103
	v_exp_f32_e32 v106, v106
	v_cvt_pk_bf16_f32 v100, v100, v101
	v_exp_f32_e32 v107, v107
	v_cvt_pk_bf16_f32 v101, v102, v103
	v_add_f32_e32 v252, v252, v104
	v_add_f32_e32 v253, v253, v105
	v_cvt_pk_bf16_f32 v102, v104, v105
	v_add_f32_e32 v252, v252, v106
	v_add_f32_e32 v253, v253, v107
	v_cvt_pk_bf16_f32 v103, v106, v107
	s_waitcnt lgkmcnt(11)
	v_mfma_f32_32x32x16_bf16 v[188:203], v[232:235], v[128:131], v[188:203]
	ds_read_b64_tr_b16 v[224:225], v229 offset:4096
	ds_read_b64_tr_b16 v[226:227], v229 offset:6144
	v_exp_f32_e32 v108, v108
	v_exp_f32_e32 v109, v109
	v_exp_f32_e32 v110, v110
	v_add_f32_e32 v252, v252, v108
	v_exp_f32_e32 v111, v111
	v_add_f32_e32 v253, v253, v109
	v_exp_f32_e32 v112, v112
	v_add_f32_e32 v252, v252, v110
	s_waitcnt lgkmcnt(12)
	v_mfma_f32_32x32x16_bf16 v[204:219], v[236:239], v[128:131], v[204:219]
	ds_read_b64_tr_b16 v[232:233], v230 offset:4096
	ds_read_b64_tr_b16 v[234:235], v230 offset:6144
	v_exp_f32_e32 v113, v113
	v_add_f32_e32 v253, v253, v111
	v_exp_f32_e32 v114, v114
	v_cvt_pk_bf16_f32 v104, v108, v109
	v_exp_f32_e32 v115, v115
	v_cvt_pk_bf16_f32 v105, v110, v111
	v_add_f32_e32 v252, v252, v112
	v_add_f32_e32 v253, v253, v113
	v_cvt_pk_bf16_f32 v106, v112, v113
	v_add_f32_e32 v252, v252, v114
	v_add_f32_e32 v253, v253, v115
	v_cvt_pk_bf16_f32 v107, v114, v115
	v_max_f32_e32 v251, v252, v253
	v_cmp_nge_f32_e32 vcc, 0x45800000, v251
	s_cbranch_vccnz .LatB_recs_h0

; #define LAS __attribute__((address_space(3)))
; #define VREADS1(arr, d_) do { const unsigned ad_ = vbase ^ (unsigned)((d_) << 6); __builtin_amdgcn_sched_barrier(0); \
;         _Pragma("unroll") for (int ks_ = 0; ks_ < 4; ++ks_) { VTR(arr[ks_ * 2], ad_, ks_ * 4096); VTR(arr[ks_ * 2 + 1], ad_, ks_ * 4096 + 2048); } __builtin_amdgcn_sched_barrier(0); } while (0)
; #define PV1(arr, d_) do { _Pragma("unroll") for (int ks_ = 0; ks_ < 4; ++ks_) { const s16x4 lo_ = arr[ks_ * 2], hh_ = arr[ks_ * 2 + 1]; \
;         const bf16x8 bv_ = (bf16x8){lo_[0], lo_[1], lo_[2], lo_[3], hh_[0], hh_[1], hh_[2], hh_[3]}; \
;         O[d_] = __builtin_amdgcn_mfma_f32_32x32x16_bf16(pa[ks_], bv_, O[d_], 0, 0, 0); } __builtin_amdgcn_sched_barrier(0); } while (0)
; #define LGKM0() do { __builtin_amdgcn_sched_barrier(0); asm volatile("s_waitcnt lgkmcnt(0)" ::: "memory"); __builtin_amdgcn_sched_barrier(0); } while (0)
; __device__ __forceinline__ void attn_unit(LAS unsigned char* lds, const bf16_t* Z, bf16_t* A2, const float* tabg, int seq_base, int S, int h, int qb, float lam) {
;     ...
;             for (int ds = 0; ds < 4; ++ds) { kf[2 * ds] = *(const LAS bf16x8*)(Kt + (kfo ^ (unsigned)(ds << 5))); kf[2 * ds + 1] = *(const LAS bf16x8*)(Kt + 32 * 256 + (kfo ^ (unsigned)(ds << 5))); }
;             __builtin_amdgcn_sched_barrier(0);
;             p0 = __builtin_amdgcn_mfma_f32_32x32x16_bf16(kf[0], qf[0], cblk, 0, 0, 0);
;             p1 = __builtin_amdgcn_mfma_f32_32x32x16_bf16(kf[1], qf[0], cblk, 0, 0, 0);
; #pragma unroll
;             for (int ds = 1; ds < 4; ++ds) {
;                 p0 = __builtin_amdgcn_mfma_f32_32x32x16_bf16(kf[2 * ds], qf[ds], p0, 0, 0, 0);
;                 p1 = __builtin_amdgcn_mfma_f32_32x32x16_bf16(kf[2 * ds + 1], qf[ds], p1, 0, 0, 0);
;             }
;     ...
; #pragma unroll
;         for (int r = 0; r < 16; ++r) { p0[r] = __builtin_amdgcn_exp2f(p0[r]); p1[r] = __builtin_amdgcn_exp2f(p1[r]); }
; #pragma unroll
;         for (int r = 0; r < 16; r += 2) { ls2 += (f32x2){p0[r], p0[r + 1]}; ls2 += (f32x2){p1[r], p1[r + 1]}; }
;         bf16x8 pa[4]; pa[0] = pack8(p0, 0); pa[1] = pack8(p0, 8); pa[2] = pack8(p1, 0); pa[3] = pack8(p1, 8);
;         LGKM0(); VREADS1(vb, 1); PV1(va, 0); LGKM0(); VREADS1(va, 2); PV1(vb, 1); LGKM0(); VREADS1(vb, 3); PV1(va, 2); LGKM0(); PV1(vb, 3);
.LatB_evret_h1:
	s_waitcnt lgkmcnt(12)
	v_mfma_f32_32x32x16_bf16 v[20:35], v[84:87], v[132:135], v[20:35]
	ds_read_b64_tr_b16 v[236:237], v231 offset:4096
	ds_read_b64_tr_b16 v[238:239], v231 offset:6144
	v_exp_f32_e32 v188, v188
	v_exp_f32_e32 v189, v189
	s_waitcnt lgkmcnt(12)
	v_mfma_f32_32x32x16_bf16 v[36:51], v[84:87], v[136:139], v[36:51]
	ds_read_b64_tr_b16 v[132:133], v228 offset:8192
	ds_read_b64_tr_b16 v[134:135], v228 offset:10240
	v_exp_f32_e32 v190, v190
	v_exp_f32_e32 v191, v191
	v_add_f32_e32 v252, v188, v190
	s_waitcnt lgkmcnt(12)
	v_mfma_f32_32x32x16_bf16 v[52:67], v[84:87], v[140:143], v[52:67]
	ds_read_b64_tr_b16 v[136:137], v229 offset:8192
	ds_read_b64_tr_b16 v[138:139], v229 offset:10240
	v_exp_f32_e32 v192, v192
	v_add_f32_e32 v253, v189, v191
	v_exp_f32_e32 v193, v193
	s_waitcnt lgkmcnt(12)
	s_mov_b32 m0, s25
	v_mfma_f32_32x32x16_bf16 v[68:83], v[84:87], v[144:147], v[68:83]
	global_load_lds_dwordx4 v172, s[8:9]
	ds_read_b64_tr_b16 v[140:141], v230 offset:8192
	ds_read_b64_tr_b16 v[142:143], v230 offset:10240
	v_cvt_pk_bf16_f32 v188, v188, v189
	v_exp_f32_e32 v194, v194
	v_cvt_pk_bf16_f32 v189, v190, v191
	s_waitcnt lgkmcnt(12)
	v_mfma_f32_32x32x16_bf16 v[20:35], v[88:91], v[220:223], v[20:35]
	ds_read_b64_tr_b16 v[144:145], v231 offset:8192
	ds_read_b64_tr_b16 v[146:147], v231 offset:10240
	v_exp_f32_e32 v195, v195
	v_add_f32_e32 v252, v252, v192
	v_add_f32_e32 v253, v253, v193
	v_cvt_pk_bf16_f32 v190, v192, v193
	s_waitcnt lgkmcnt(12)
	v_mfma_f32_32x32x16_bf16 v[36:51], v[88:91], v[224:227], v[36:51]
	ds_read_b64_tr_b16 v[220:221], v228 offset:12288
	ds_read_b64_tr_b16 v[222:223], v228 offset:14336
	v_add_f32_e32 v252, v252, v194
	v_add_f32_e32 v253, v253, v195
	v_cvt_pk_bf16_f32 v191, v194, v195
	v_exp_f32_e32 v196, v196
	s_waitcnt lgkmcnt(12)
	v_mfma_f32_32x32x16_bf16 v[52:67], v[88:91], v[232:235], v[52:67]
	ds_read_b64_tr_b16 v[224:225], v229 offset:12288
	ds_read_b64_tr_b16 v[226:227], v229 offset:14336
	v_exp_f32_e32 v197, v197
	v_exp_f32_e32 v198, v198
	s_waitcnt lgkmcnt(12)
	s_add_u32 m0, s27, 0xd000
	v_mfma_f32_32x32x16_bf16 v[68:83], v[88:91], v[236:239], v[68:83]
	global_load_lds_dwordx4 v174, s[8:9]
	ds_read_b64_tr_b16 v[232:233], v230 offset:12288
	ds_read_b64_tr_b16 v[234:235], v230 offset:14336
	v_add_f32_e32 v252, v252, v196
	v_exp_f32_e32 v199, v199
	v_add_f32_e32 v253, v253, v197
	s_waitcnt lgkmcnt(12)
	v_mfma_f32_32x32x16_bf16 v[20:35], v[100:103], v[132:135], v[20:35]
	ds_read_b64_tr_b16 v[236:237], v231 offset:12288
	ds_read_b64_tr_b16 v[238:239], v231 offset:14336
	v_exp_f32_e32 v200, v200
	v_add_f32_e32 v252, v252, v198
	v_exp_f32_e32 v201, v201
	s_waitcnt lgkmcnt(12)
	v_mfma_f32_32x32x16_bf16 v[36:51], v[100:103], v[136:139], v[36:51]
	ds_read_b128 v[132:135], v19 offset:32768
	v_add_f32_e32 v253, v253, v199
	v_exp_f32_e32 v202, v202
	v_cvt_pk_bf16_f32 v192, v196, v197
	s_waitcnt lgkmcnt(11)
	v_mfma_f32_32x32x16_bf16 v[52:67], v[100:103], v[140:143], v[52:67]
	ds_read_b128 v[136:139], v19 offset:40960
	v_exp_f32_e32 v203, v203
	v_cvt_pk_bf16_f32 v193, v198, v199
	v_add_f32_e32 v252, v252, v200
	v_add_f32_e32 v253, v253, v201
	s_waitcnt lgkmcnt(10)
	s_add_u32 m0, s25, 0x2000
	v_mfma_f32_32x32x16_bf16 v[68:83], v[100:103], v[144:147], v[68:83]
	global_load_lds_dwordx4 v173, s[8:9]
	ds_read_b128 v[140:143], v180 offset:32768
	v_cvt_pk_bf16_f32 v194, v200, v201
	v_add_f32_e32 v252, v252, v202
	v_add_f32_e32 v253, v253, v203
	v_cvt_pk_bf16_f32 v195, v202, v203
	s_waitcnt lgkmcnt(9)
	v_mfma_f32_32x32x16_bf16 v[20:35], v[104:107], v[220:223], v[20:35]
	ds_read_b128 v[144:147], v180 offset:40960
	v_exp_f32_e32 v204, v204
	v_exp_f32_e32 v205, v205
	v_exp_f32_e32 v206, v206
	s_waitcnt lgkmcnt(8)
	v_mfma_f32_32x32x16_bf16 v[36:51], v[104:107], v[224:227], v[36:51]
	ds_read_b128 v[220:223], v181 offset:32768
	v_add_f32_e32 v252, v252, v204
	v_exp_f32_e32 v207, v207
	v_add_f32_e32 v253, v253, v205
	s_waitcnt lgkmcnt(7)
	v_mfma_f32_32x32x16_bf16 v[52:67], v[104:107], v[232:235], v[52:67]
	ds_read_b128 v[224:227], v181 offset:40960
	v_exp_f32_e32 v208, v208
	v_add_f32_e32 v252, v252, v206
	v_exp_f32_e32 v209, v209
	s_waitcnt lgkmcnt(6)
	s_add_u32 m0, s27, 0xf000
	v_mfma_f32_32x32x16_bf16 v[68:83], v[104:107], v[236:239], v[68:83]
	global_load_lds_dwordx4 v175, s[8:9]
	ds_read_b128 v[232:235], v182 offset:32768
	v_add_f32_e32 v253, v253, v207
	v_exp_f32_e32 v210, v210
	v_cvt_pk_bf16_f32 v204, v204, v205
	s_waitcnt lgkmcnt(6)
	v_mfma_f32_32x32x16_bf16 v[84:99], v[132:135], v[116:119], v[2:17]
	ds_read_b128 v[236:239], v182 offset:40960
	v_exp_f32_e32 v211, v211
	v_cvt_pk_bf16_f32 v205, v206, v207
	v_add_f32_e32 v252, v252, v208
	v_add_f32_e32 v253, v253, v209
	s_waitcnt lgkmcnt(6)
	v_mfma_f32_32x32x16_bf16 v[100:115], v[136:139], v[116:119], v[2:17]
	ds_read_b64_tr_b16 v[132:133], v228 offset:16384
	ds_read_b64_tr_b16 v[134:135], v228 offset:18432
	v_cvt_pk_bf16_f32 v206, v208, v209
	v_add_f32_e32 v252, v252, v210
	v_add_f32_e32 v253, v253, v211
	v_cvt_pk_bf16_f32 v207, v210, v211
	s_waitcnt lgkmcnt(7)
	v_mfma_f32_32x32x16_bf16 v[84:99], v[140:143], v[120:123], v[84:99]
	ds_read_b64_tr_b16 v[136:137], v229 offset:16384
	ds_read_b64_tr_b16 v[138:139], v229 offset:18432
	v_exp_f32_e32 v212, v212
	v_exp_f32_e32 v213, v213
	s_waitcnt lgkmcnt(8)
	v_mfma_f32_32x32x16_bf16 v[100:115], v[144:147], v[120:123], v[100:115]
	ds_read_b64_tr_b16 v[140:141], v230 offset:16384
	ds_read_b64_tr_b16 v[142:143], v230 offset:18432
	v_exp_f32_e32 v214, v214
	v_add_f32_e32 v252, v252, v212
	v_exp_f32_e32 v215, v215
	v_add_f32_e32 v253, v253, v213
	s_waitcnt lgkmcnt(9)
	v_mfma_f32_32x32x16_bf16 v[84:99], v[220:223], v[124:127], v[84:99]
	ds_read_b64_tr_b16 v[144:145], v231 offset:16384
	ds_read_b64_tr_b16 v[146:147], v231 offset:18432
	v_exp_f32_e32 v216, v216
	v_add_f32_e32 v252, v252, v214
	s_waitcnt lgkmcnt(10)
	v_mfma_f32_32x32x16_bf16 v[100:115], v[224:227], v[124:127], v[100:115]
	ds_read_b64_tr_b16 v[220:221], v228 offset:20480
	ds_read_b64_tr_b16 v[222:223], v228 offset:22528
	v_exp_f32_e32 v217, v217
	v_add_f32_e32 v253, v253, v215
	v_exp_f32_e32 v218, v218
	v_cvt_pk_bf16_f32 v208, v212, v213
	s_waitcnt lgkmcnt(11)
	v_mfma_f32_32x32x16_bf16 v[84:99], v[232:235], v[128:131], v[84:99]
	ds_read_b64_tr_b16 v[224:225], v229 offset:20480
	ds_read_b64_tr_b16 v[226:227], v229 offset:22528
	v_exp_f32_e32 v219, v219
	v_cvt_pk_bf16_f32 v209, v214, v215
	v_add_f32_e32 v252, v252, v216
	s_waitcnt lgkmcnt(12)
	v_mfma_f32_32x32x16_bf16 v[100:115], v[236:239], v[128:131], v[100:115]
	ds_read_b64_tr_b16 v[232:233], v230 offset:20480
	ds_read_b64_tr_b16 v[234:235], v230 offset:22528
	v_add_f32_e32 v253, v253, v217
	v_cvt_pk_bf16_f32 v210, v216, v217
	v_add_f32_e32 v252, v252, v218
	v_add_f32_e32 v253, v253, v219
	v_cvt_pk_bf16_f32 v211, v218, v219
	v_max_f32_e32 v251, v252, v253
	v_cmp_nge_f32_e32 vcc, 0x45800000, v251
	s_cbranch_vccnz .LatB_recs_h1

; #define LAS __attribute__((address_space(3)))
; #define VREADS1(arr, d_) do { const unsigned ad_ = vbase ^ (unsigned)((d_) << 6); __builtin_amdgcn_sched_barrier(0); \
;         _Pragma("unroll") for (int ks_ = 0; ks_ < 4; ++ks_) { VTR(arr[ks_ * 2], ad_, ks_ * 4096); VTR(arr[ks_ * 2 + 1], ad_, ks_ * 4096 + 2048); } __builtin_amdgcn_sched_barrier(0); } while (0)
; #define PV1(arr, d_) do { _Pragma("unroll") for (int ks_ = 0; ks_ < 4; ++ks_) { const s16x4 lo_ = arr[ks_ * 2], hh_ = arr[ks_ * 2 + 1]; \
;         const bf16x8 bv_ = (bf16x8){lo_[0], lo_[1], lo_[2], lo_[3], hh_[0], hh_[1], hh_[2], hh_[3]}; \
;         O[d_] = __builtin_amdgcn_mfma_f32_32x32x16_bf16(pa[ks_], bv_, O[d_], 0, 0, 0); } __builtin_amdgcn_sched_barrier(0); } while (0)
; #define LGKM0() do { __builtin_amdgcn_sched_barrier(0); asm volatile("s_waitcnt lgkmcnt(0)" ::: "memory"); __builtin_amdgcn_sched_barrier(0); } while (0)
; __device__ __forceinline__ void attn_unit(LAS unsigned char* lds, const bf16_t* Z, bf16_t* A2, const float* tabg, int seq_base, int S, int h, int qb, float lam) {
;     ...
;             for (int ds = 0; ds < 4; ++ds) { kf[2 * ds] = *(const LAS bf16x8*)(Kt + (kfo ^ (unsigned)(ds << 5))); kf[2 * ds + 1] = *(const LAS bf16x8*)(Kt + 32 * 256 + (kfo ^ (unsigned)(ds << 5))); }
;             __builtin_amdgcn_sched_barrier(0);
;             p0 = __builtin_amdgcn_mfma_f32_32x32x16_bf16(kf[0], qf[0], cblk, 0, 0, 0);
;             p1 = __builtin_amdgcn_mfma_f32_32x32x16_bf16(kf[1], qf[0], cblk, 0, 0, 0);
; #pragma unroll
;             for (int ds = 1; ds < 4; ++ds) {
;                 p0 = __builtin_amdgcn_mfma_f32_32x32x16_bf16(kf[2 * ds], qf[ds], p0, 0, 0, 0);
;                 p1 = __builtin_amdgcn_mfma_f32_32x32x16_bf16(kf[2 * ds + 1], qf[ds], p1, 0, 0, 0);
;             }
;     ...
; #pragma unroll
;         for (int r = 0; r < 16; ++r) { p0[r] = __builtin_amdgcn_exp2f(p0[r]); p1[r] = __builtin_amdgcn_exp2f(p1[r]); }
; #pragma unroll
;         for (int r = 0; r < 16; r += 2) { ls2 += (f32x2){p0[r], p0[r + 1]}; ls2 += (f32x2){p1[r], p1[r + 1]}; }
;         bf16x8 pa[4]; pa[0] = pack8(p0, 0); pa[1] = pack8(p0, 8); pa[2] = pack8(p1, 0); pa[3] = pack8(p1, 8);
;         LGKM0(); VREADS1(vb, 1); PV1(va, 0); LGKM0(); VREADS1(va, 2); PV1(vb, 1); LGKM0(); VREADS1(vb, 3); PV1(va, 2); LGKM0(); PV1(vb, 3);
.LatB_evret_h2:
	s_waitcnt lgkmcnt(12)
	v_mfma_f32_32x32x16_bf16 v[20:35], v[188:191], v[132:135], v[20:35]
	ds_read_b64_tr_b16 v[236:237], v231 offset:20480
	ds_read_b64_tr_b16 v[238:239], v231 offset:22528
	v_exp_f32_e32 v84, v84
	v_exp_f32_e32 v85, v85
	s_waitcnt lgkmcnt(12)
	v_mfma_f32_32x32x16_bf16 v[36:51], v[188:191], v[136:139], v[36:51]
	ds_read_b64_tr_b16 v[132:133], v228 offset:24576
	ds_read_b64_tr_b16 v[134:135], v228 offset:26624
	v_exp_f32_e32 v86, v86
	v_exp_f32_e32 v87, v87
	v_add_f32_e32 v252, v84, v86
	s_waitcnt lgkmcnt(12)
	v_mfma_f32_32x32x16_bf16 v[52:67], v[188:191], v[140:143], v[52:67]
	ds_read_b64_tr_b16 v[136:137], v229 offset:24576
	ds_read_b64_tr_b16 v[138:139], v229 offset:26624
	v_exp_f32_e32 v88, v88
	v_add_f32_e32 v253, v85, v87
	v_exp_f32_e32 v89, v89
	s_waitcnt lgkmcnt(12)
	s_add_u32 m0, s25, 0x4000
	v_mfma_f32_32x32x16_bf16 v[68:83], v[188:191], v[144:147], v[68:83]
	global_load_lds_dwordx4 v172, s[8:9]
	ds_read_b64_tr_b16 v[140:141], v230 offset:24576
	ds_read_b64_tr_b16 v[142:143], v230 offset:26624
	v_cvt_pk_bf16_f32 v84, v84, v85
	v_exp_f32_e32 v90, v90
	v_cvt_pk_bf16_f32 v85, v86, v87
	s_waitcnt lgkmcnt(12)
	v_mfma_f32_32x32x16_bf16 v[20:35], v[192:195], v[220:223], v[20:35]
	ds_read_b64_tr_b16 v[144:145], v231 offset:24576
	ds_read_b64_tr_b16 v[146:147], v231 offset:26624
	v_exp_f32_e32 v91, v91
	v_add_f32_e32 v252, v252, v88
	v_add_f32_e32 v253, v253, v89
	v_cvt_pk_bf16_f32 v86, v88, v89
	s_waitcnt lgkmcnt(12)
	v_mfma_f32_32x32x16_bf16 v[36:51], v[192:195], v[224:227], v[36:51]
	ds_read_b64_tr_b16 v[220:221], v228 offset:28672
	ds_read_b64_tr_b16 v[222:223], v228 offset:30720
	v_add_f32_e32 v252, v252, v90
	v_add_f32_e32 v253, v253, v91
	v_cvt_pk_bf16_f32 v87, v90, v91
	v_exp_f32_e32 v92, v92
	s_waitcnt lgkmcnt(12)
	v_mfma_f32_32x32x16_bf16 v[52:67], v[192:195], v[232:235], v[52:67]
	ds_read_b64_tr_b16 v[224:225], v229 offset:28672
	ds_read_b64_tr_b16 v[226:227], v229 offset:30720
	v_exp_f32_e32 v93, v93
	v_exp_f32_e32 v94, v94
	s_waitcnt lgkmcnt(12)
	s_mov_b32 m0, s27
	v_mfma_f32_32x32x16_bf16 v[68:83], v[192:195], v[236:239], v[68:83]
	global_load_lds_dwordx4 v174, s[8:9]
	ds_read_b64_tr_b16 v[232:233], v230 offset:28672
	ds_read_b64_tr_b16 v[234:235], v230 offset:30720
	v_add_f32_e32 v252, v252, v92
	v_exp_f32_e32 v95, v95
	v_add_f32_e32 v253, v253, v93
	s_waitcnt lgkmcnt(12)
	v_mfma_f32_32x32x16_bf16 v[20:35], v[204:207], v[132:135], v[20:35]
	ds_read_b64_tr_b16 v[236:237], v231 offset:28672
	ds_read_b64_tr_b16 v[238:239], v231 offset:30720
	v_exp_f32_e32 v96, v96
	v_add_f32_e32 v252, v252, v94
	v_exp_f32_e32 v97, v97
	s_waitcnt lgkmcnt(12)
	v_mfma_f32_32x32x16_bf16 v[36:51], v[204:207], v[136:139], v[36:51]
	ds_read_b128 v[132:135], v164
	v_add_f32_e32 v253, v253, v95
	v_exp_f32_e32 v98, v98
	v_cvt_pk_bf16_f32 v88, v92, v93
	s_waitcnt lgkmcnt(11)
	v_mfma_f32_32x32x16_bf16 v[52:67], v[204:207], v[140:143], v[52:67]
	ds_read_b128 v[136:139], v164 offset:8192
	v_exp_f32_e32 v99, v99
	v_cvt_pk_bf16_f32 v89, v94, v95
	v_add_f32_e32 v252, v252, v96
	v_add_f32_e32 v253, v253, v97
	s_waitcnt lgkmcnt(10)
	s_add_u32 m0, s25, 0x6000
	v_mfma_f32_32x32x16_bf16 v[68:83], v[204:207], v[144:147], v[68:83]
	global_load_lds_dwordx4 v173, s[8:9]
	ds_read_b128 v[140:143], v165
	v_cvt_pk_bf16_f32 v90, v96, v97
	v_add_f32_e32 v252, v252, v98
	v_add_f32_e32 v253, v253, v99
	v_cvt_pk_bf16_f32 v91, v98, v99
	s_waitcnt lgkmcnt(9)
	v_mfma_f32_32x32x16_bf16 v[20:35], v[208:211], v[220:223], v[20:35]
	ds_read_b128 v[144:147], v165 offset:8192
	v_exp_f32_e32 v100, v100
	v_exp_f32_e32 v101, v101
	v_exp_f32_e32 v102, v102
	s_waitcnt lgkmcnt(8)
	v_mfma_f32_32x32x16_bf16 v[36:51], v[208:211], v[224:227], v[36:51]
	ds_read_b128 v[220:223], v166
	v_add_f32_e32 v252, v252, v100
	v_exp_f32_e32 v103, v103
	v_add_f32_e32 v253, v253, v101
	s_waitcnt lgkmcnt(7)
	v_mfma_f32_32x32x16_bf16 v[52:67], v[208:211], v[232:235], v[52:67]
	ds_read_b128 v[224:227], v166 offset:8192
	v_exp_f32_e32 v104, v104
	v_add_f32_e32 v252, v252, v102
	v_exp_f32_e32 v105, v105
	s_waitcnt lgkmcnt(6)
	s_add_u32 m0, s27, 0x2000
	v_mfma_f32_32x32x16_bf16 v[68:83], v[208:211], v[236:239], v[68:83]
	global_load_lds_dwordx4 v175, s[8:9]
	ds_read_b128 v[232:235], v167
	v_add_f32_e32 v253, v253, v103
	v_exp_f32_e32 v106, v106
	v_cvt_pk_bf16_f32 v100, v100, v101
	s_waitcnt lgkmcnt(6)
	v_mfma_f32_32x32x16_bf16 v[188:203], v[132:135], v[116:119], v[2:17]
	ds_read_b128 v[236:239], v167 offset:8192
	v_exp_f32_e32 v107, v107
	v_cvt_pk_bf16_f32 v101, v102, v103
	v_add_f32_e32 v252, v252, v104
	v_add_f32_e32 v253, v253, v105
	s_waitcnt lgkmcnt(6)
	v_mfma_f32_32x32x16_bf16 v[204:219], v[136:139], v[116:119], v[2:17]
	ds_read_b64_tr_b16 v[132:133], v228 offset:32768
	ds_read_b64_tr_b16 v[134:135], v228 offset:34816
	v_cvt_pk_bf16_f32 v102, v104, v105
	v_add_f32_e32 v252, v252, v106
	v_add_f32_e32 v253, v253, v107
	v_cvt_pk_bf16_f32 v103, v106, v107
	s_waitcnt lgkmcnt(7)
	v_mfma_f32_32x32x16_bf16 v[188:203], v[140:143], v[120:123], v[188:203]
	ds_read_b64_tr_b16 v[136:137], v229 offset:32768
	ds_read_b64_tr_b16 v[138:139], v229 offset:34816
	v_exp_f32_e32 v108, v108
	v_exp_f32_e32 v109, v109
	s_waitcnt lgkmcnt(8)
	v_mfma_f32_32x32x16_bf16 v[204:219], v[144:147], v[120:123], v[204:219]
	ds_read_b64_tr_b16 v[140:141], v230 offset:32768
	ds_read_b64_tr_b16 v[142:143], v230 offset:34816
	v_exp_f32_e32 v110, v110
	v_add_f32_e32 v252, v252, v108
	v_exp_f32_e32 v111, v111
	v_add_f32_e32 v253, v253, v109
	s_waitcnt lgkmcnt(9)
	v_mfma_f32_32x32x16_bf16 v[188:203], v[220:223], v[124:127], v[188:203]
	ds_read_b64_tr_b16 v[144:145], v231 offset:32768
	ds_read_b64_tr_b16 v[146:147], v231 offset:34816
	v_exp_f32_e32 v112, v112
	v_add_f32_e32 v252, v252, v110
	s_waitcnt lgkmcnt(10)
	v_mfma_f32_32x32x16_bf16 v[204:219], v[224:227], v[124:127], v[204:219]
	ds_read_b64_tr_b16 v[220:221], v228 offset:36864
	ds_read_b64_tr_b16 v[222:223], v228 offset:38912
	v_exp_f32_e32 v113, v113
	v_add_f32_e32 v253, v253, v111
	v_exp_f32_e32 v114, v114
	v_cvt_pk_bf16_f32 v104, v108, v109
	s_waitcnt lgkmcnt(11)
	v_mfma_f32_32x32x16_bf16 v[188:203], v[232:235], v[128:131], v[188:203]
	ds_read_b64_tr_b16 v[224:225], v229 offset:36864
	ds_read_b64_tr_b16 v[226:227], v229 offset:38912
	v_exp_f32_e32 v115, v115
	v_cvt_pk_bf16_f32 v105, v110, v111
	v_add_f32_e32 v252, v252, v112
	s_waitcnt lgkmcnt(12)
	v_mfma_f32_32x32x16_bf16 v[204:219], v[236:239], v[128:131], v[204:219]
	ds_read_b64_tr_b16 v[232:233], v230 offset:36864
	ds_read_b64_tr_b16 v[234:235], v230 offset:38912
	v_add_f32_e32 v253, v253, v113
	v_cvt_pk_bf16_f32 v106, v112, v113
	v_add_f32_e32 v252, v252, v114
	v_add_f32_e32 v253, v253, v115
	v_cvt_pk_bf16_f32 v107, v114, v115
	v_max_f32_e32 v251, v252, v253
	v_cmp_nge_f32_e32 vcc, 0x45800000, v251
	s_cbranch_vccnz .LatB_recs_h2

; #define LAS __attribute__((address_space(3)))
; #define VREADS1(arr, d_) do { const unsigned ad_ = vbase ^ (unsigned)((d_) << 6); __builtin_amdgcn_sched_barrier(0); \
;         _Pragma("unroll") for (int ks_ = 0; ks_ < 4; ++ks_) { VTR(arr[ks_ * 2], ad_, ks_ * 4096); VTR(arr[ks_ * 2 + 1], ad_, ks_ * 4096 + 2048); } __builtin_amdgcn_sched_barrier(0); } while (0)
; #define PV1(arr, d_) do { _Pragma("unroll") for (int ks_ = 0; ks_ < 4; ++ks_) { const s16x4 lo_ = arr[ks_ * 2], hh_ = arr[ks_ * 2 + 1]; \
;         const bf16x8 bv_ = (bf16x8){lo_[0], lo_[1], lo_[2], lo_[3], hh_[0], hh_[1], hh_[2], hh_[3]}; \
;         O[d_] = __builtin_amdgcn_mfma_f32_32x32x16_bf16(pa[ks_], bv_, O[d_], 0, 0, 0); } __builtin_amdgcn_sched_barrier(0); } while (0)
; #define LGKM0() do { __builtin_amdgcn_sched_barrier(0); asm volatile("s_waitcnt lgkmcnt(0)" ::: "memory"); __builtin_amdgcn_sched_barrier(0); } while (0)
; __device__ __forceinline__ void attn_unit(LAS unsigned char* lds, const bf16_t* Z, bf16_t* A2, const float* tabg, int seq_base, int S, int h, int qb, float lam) {
;     ...
;             for (int ds = 0; ds < 4; ++ds) { kf[2 * ds] = *(const LAS bf16x8*)(Kt + (kfo ^ (unsigned)(ds << 5))); kf[2 * ds + 1] = *(const LAS bf16x8*)(Kt + 32 * 256 + (kfo ^ (unsigned)(ds << 5))); }
;             __builtin_amdgcn_sched_barrier(0);
;             p0 = __builtin_amdgcn_mfma_f32_32x32x16_bf16(kf[0], qf[0], cblk, 0, 0, 0);
;             p1 = __builtin_amdgcn_mfma_f32_32x32x16_bf16(kf[1], qf[0], cblk, 0, 0, 0);
; #pragma unroll
;             for (int ds = 1; ds < 4; ++ds) {
;                 p0 = __builtin_amdgcn_mfma_f32_32x32x16_bf16(kf[2 * ds], qf[ds], p0, 0, 0, 0);
;                 p1 = __builtin_amdgcn_mfma_f32_32x32x16_bf16(kf[2 * ds + 1], qf[ds], p1, 0, 0, 0);
;             }
;     ...
; #pragma unroll
;         for (int r = 0; r < 16; ++r) { p0[r] = __builtin_amdgcn_exp2f(p0[r]); p1[r] = __builtin_amdgcn_exp2f(p1[r]); }
; #pragma unroll
;         for (int r = 0; r < 16; r += 2) { ls2 += (f32x2){p0[r], p0[r + 1]}; ls2 += (f32x2){p1[r], p1[r + 1]}; }
;         bf16x8 pa[4]; pa[0] = pack8(p0, 0); pa[1] = pack8(p0, 8); pa[2] = pack8(p1, 0); pa[3] = pack8(p1, 8);
;         LGKM0(); VREADS1(vb, 1); PV1(va, 0); LGKM0(); VREADS1(va, 2); PV1(vb, 1); LGKM0(); VREADS1(vb, 3); PV1(va, 2); LGKM0(); PV1(vb, 3);
.LatB_evret_h3:
	s_waitcnt lgkmcnt(12)
	v_mfma_f32_32x32x16_bf16 v[20:35], v[84:87], v[132:135], v[20:35]
	ds_read_b64_tr_b16 v[236:237], v231 offset:36864
	ds_read_b64_tr_b16 v[238:239], v231 offset:38912
	v_exp_f32_e32 v188, v188
	v_exp_f32_e32 v189, v189
	s_waitcnt lgkmcnt(12)
	v_mfma_f32_32x32x16_bf16 v[36:51], v[84:87], v[136:139], v[36:51]
	ds_read_b64_tr_b16 v[132:133], v228 offset:40960
	ds_read_b64_tr_b16 v[134:135], v228 offset:43008
	v_exp_f32_e32 v190, v190
	v_exp_f32_e32 v191, v191
	v_add_f32_e32 v252, v188, v190
	s_waitcnt lgkmcnt(12)
	v_mfma_f32_32x32x16_bf16 v[52:67], v[84:87], v[140:143], v[52:67]
	ds_read_b64_tr_b16 v[136:137], v229 offset:40960
	ds_read_b64_tr_b16 v[138:139], v229 offset:43008
	v_exp_f32_e32 v192, v192
	v_add_f32_e32 v253, v189, v191
	v_exp_f32_e32 v193, v193
	s_waitcnt lgkmcnt(12)
	s_add_u32 m0, s25, 0x8000
	v_mfma_f32_32x32x16_bf16 v[68:83], v[84:87], v[144:147], v[68:83]
	global_load_lds_dwordx4 v172, s[8:9]
	ds_read_b64_tr_b16 v[140:141], v230 offset:40960
	ds_read_b64_tr_b16 v[142:143], v230 offset:43008
	v_cvt_pk_bf16_f32 v188, v188, v189
	v_exp_f32_e32 v194, v194
	v_cvt_pk_bf16_f32 v189, v190, v191
	s_waitcnt lgkmcnt(12)
	v_mfma_f32_32x32x16_bf16 v[20:35], v[88:91], v[220:223], v[20:35]
	ds_read_b64_tr_b16 v[144:145], v231 offset:40960
	ds_read_b64_tr_b16 v[146:147], v231 offset:43008
	v_exp_f32_e32 v195, v195
	v_add_f32_e32 v252, v252, v192
	v_add_f32_e32 v253, v253, v193
	v_cvt_pk_bf16_f32 v190, v192, v193
	s_waitcnt lgkmcnt(12)
	v_mfma_f32_32x32x16_bf16 v[36:51], v[88:91], v[224:227], v[36:51]
	ds_read_b64_tr_b16 v[220:221], v228 offset:45056
	ds_read_b64_tr_b16 v[222:223], v228 offset:47104
	v_add_f32_e32 v252, v252, v194
	v_add_f32_e32 v253, v253, v195
	v_cvt_pk_bf16_f32 v191, v194, v195
	v_exp_f32_e32 v196, v196
	s_waitcnt lgkmcnt(12)
	v_mfma_f32_32x32x16_bf16 v[52:67], v[88:91], v[232:235], v[52:67]
	ds_read_b64_tr_b16 v[224:225], v229 offset:45056
	ds_read_b64_tr_b16 v[226:227], v229 offset:47104
	v_exp_f32_e32 v197, v197
	v_exp_f32_e32 v198, v198
	s_waitcnt lgkmcnt(12)
	s_add_u32 m0, s27, 0x4000
	v_mfma_f32_32x32x16_bf16 v[68:83], v[88:91], v[236:239], v[68:83]
	global_load_lds_dwordx4 v174, s[8:9]
	ds_read_b64_tr_b16 v[232:233], v230 offset:45056
	ds_read_b64_tr_b16 v[234:235], v230 offset:47104
	v_add_f32_e32 v252, v252, v196
	v_exp_f32_e32 v199, v199
	v_add_f32_e32 v253, v253, v197
	s_waitcnt lgkmcnt(12)
	v_mfma_f32_32x32x16_bf16 v[20:35], v[100:103], v[132:135], v[20:35]
	ds_read_b64_tr_b16 v[236:237], v231 offset:45056
	ds_read_b64_tr_b16 v[238:239], v231 offset:47104
	v_exp_f32_e32 v200, v200
	v_add_f32_e32 v252, v252, v198
	v_exp_f32_e32 v201, v201
	s_waitcnt lgkmcnt(12)
	v_mfma_f32_32x32x16_bf16 v[36:51], v[100:103], v[136:139], v[36:51]
	ds_read_b128 v[132:135], v19
	v_add_f32_e32 v253, v253, v199
	v_exp_f32_e32 v202, v202
	v_cvt_pk_bf16_f32 v192, v196, v197
	s_waitcnt lgkmcnt(11)
	v_mfma_f32_32x32x16_bf16 v[52:67], v[100:103], v[140:143], v[52:67]
	ds_read_b128 v[136:139], v19 offset:8192
	v_exp_f32_e32 v203, v203
	v_cvt_pk_bf16_f32 v193, v198, v199
	v_add_f32_e32 v252, v252, v200
	v_add_f32_e32 v253, v253, v201
	s_waitcnt lgkmcnt(10)
	s_add_u32 m0, s25, 0xa000
	v_mfma_f32_32x32x16_bf16 v[68:83], v[100:103], v[144:147], v[68:83]
	global_load_lds_dwordx4 v173, s[8:9]
	ds_read_b128 v[140:143], v180
	v_cvt_pk_bf16_f32 v194, v200, v201
	v_add_f32_e32 v252, v252, v202
	v_add_f32_e32 v253, v253, v203
	v_cvt_pk_bf16_f32 v195, v202, v203
	s_waitcnt lgkmcnt(9)
	v_mfma_f32_32x32x16_bf16 v[20:35], v[104:107], v[220:223], v[20:35]
	ds_read_b128 v[144:147], v180 offset:8192
	v_exp_f32_e32 v204, v204
	v_exp_f32_e32 v205, v205
	v_exp_f32_e32 v206, v206
	s_waitcnt lgkmcnt(8)
	v_mfma_f32_32x32x16_bf16 v[36:51], v[104:107], v[224:227], v[36:51]
	ds_read_b128 v[220:223], v181
	v_add_f32_e32 v252, v252, v204
	v_exp_f32_e32 v207, v207
	v_add_f32_e32 v253, v253, v205
	s_waitcnt lgkmcnt(7)
	v_mfma_f32_32x32x16_bf16 v[52:67], v[104:107], v[232:235], v[52:67]
	ds_read_b128 v[224:227], v181 offset:8192
	v_exp_f32_e32 v208, v208
	v_add_f32_e32 v252, v252, v206
	v_exp_f32_e32 v209, v209
	s_waitcnt lgkmcnt(6)
	s_add_u32 m0, s27, 0x6000
	v_mfma_f32_32x32x16_bf16 v[68:83], v[104:107], v[236:239], v[68:83]
	global_load_lds_dwordx4 v175, s[8:9]
	ds_read_b128 v[232:235], v182
	v_add_f32_e32 v253, v253, v207
	v_exp_f32_e32 v210, v210
	v_cvt_pk_bf16_f32 v204, v204, v205
	s_waitcnt lgkmcnt(6)
	v_mfma_f32_32x32x16_bf16 v[84:99], v[132:135], v[116:119], v[2:17]
	ds_read_b128 v[236:239], v182 offset:8192
	v_exp_f32_e32 v211, v211
	v_cvt_pk_bf16_f32 v205, v206, v207
	v_add_f32_e32 v252, v252, v208
	v_add_f32_e32 v253, v253, v209
	s_waitcnt lgkmcnt(6)
	v_mfma_f32_32x32x16_bf16 v[100:115], v[136:139], v[116:119], v[2:17]
	ds_read_b64_tr_b16 v[132:133], v168 offset:0
	ds_read_b64_tr_b16 v[134:135], v168 offset:2048
	v_cvt_pk_bf16_f32 v206, v208, v209
	v_add_f32_e32 v252, v252, v210
	v_add_f32_e32 v253, v253, v211
	v_cvt_pk_bf16_f32 v207, v210, v211
	s_waitcnt lgkmcnt(7)
	v_mfma_f32_32x32x16_bf16 v[84:99], v[140:143], v[120:123], v[84:99]
	ds_read_b64_tr_b16 v[136:137], v169 offset:0
	ds_read_b64_tr_b16 v[138:139], v169 offset:2048
	v_exp_f32_e32 v212, v212
	v_exp_f32_e32 v213, v213
	s_waitcnt lgkmcnt(8)
	v_mfma_f32_32x32x16_bf16 v[100:115], v[144:147], v[120:123], v[100:115]
	ds_read_b64_tr_b16 v[140:141], v170 offset:0
	ds_read_b64_tr_b16 v[142:143], v170 offset:2048
	v_exp_f32_e32 v214, v214
	v_add_f32_e32 v252, v252, v212
	v_exp_f32_e32 v215, v215
	v_add_f32_e32 v253, v253, v213
	s_waitcnt lgkmcnt(9)
	v_mfma_f32_32x32x16_bf16 v[84:99], v[220:223], v[124:127], v[84:99]
	ds_read_b64_tr_b16 v[144:145], v171 offset:0
	ds_read_b64_tr_b16 v[146:147], v171 offset:2048
	v_exp_f32_e32 v216, v216
	v_add_f32_e32 v252, v252, v214
	s_waitcnt lgkmcnt(10)
	v_mfma_f32_32x32x16_bf16 v[100:115], v[224:227], v[124:127], v[100:115]
	ds_read_b64_tr_b16 v[220:221], v168 offset:4096
	ds_read_b64_tr_b16 v[222:223], v168 offset:6144
	v_exp_f32_e32 v217, v217
	v_add_f32_e32 v253, v253, v215
	v_exp_f32_e32 v218, v218
	v_cvt_pk_bf16_f32 v208, v212, v213
	s_waitcnt lgkmcnt(11)
	v_mfma_f32_32x32x16_bf16 v[84:99], v[232:235], v[128:131], v[84:99]
	ds_read_b64_tr_b16 v[224:225], v169 offset:4096
	ds_read_b64_tr_b16 v[226:227], v169 offset:6144
	v_exp_f32_e32 v219, v219
	v_cvt_pk_bf16_f32 v209, v214, v215
	v_add_f32_e32 v252, v252, v216
	s_waitcnt lgkmcnt(12)
	v_mfma_f32_32x32x16_bf16 v[100:115], v[236:239], v[128:131], v[100:115]
	ds_read_b64_tr_b16 v[232:233], v170 offset:4096
	ds_read_b64_tr_b16 v[234:235], v170 offset:6144
	v_add_f32_e32 v253, v253, v217
	v_cvt_pk_bf16_f32 v210, v216, v217
	v_add_f32_e32 v252, v252, v218
	v_add_f32_e32 v253, v253, v219
	v_cvt_pk_bf16_f32 v211, v218, v219
	v_max_f32_e32 v251, v252, v253
	v_cmp_nge_f32_e32 vcc, 0x45800000, v251
	s_cbranch_vccnz .LatB_recs_h3

; #define LAS __attribute__((address_space(3)))
; #define VREADS1(arr, d_) do { const unsigned ad_ = vbase ^ (unsigned)((d_) << 6); __builtin_amdgcn_sched_barrier(0); \
;         _Pragma("unroll") for (int ks_ = 0; ks_ < 4; ++ks_) { VTR(arr[ks_ * 2], ad_, ks_ * 4096); VTR(arr[ks_ * 2 + 1], ad_, ks_ * 4096 + 2048); } __builtin_amdgcn_sched_barrier(0); } while (0)
; #define PV1(arr, d_) do { _Pragma("unroll") for (int ks_ = 0; ks_ < 4; ++ks_) { const s16x4 lo_ = arr[ks_ * 2], hh_ = arr[ks_ * 2 + 1]; \
;         const bf16x8 bv_ = (bf16x8){lo_[0], lo_[1], lo_[2], lo_[3], hh_[0], hh_[1], hh_[2], hh_[3]}; \
;         O[d_] = __builtin_amdgcn_mfma_f32_32x32x16_bf16(pa[ks_], bv_, O[d_], 0, 0, 0); } __builtin_amdgcn_sched_barrier(0); } while (0)
; #define LGKM0() do { __builtin_amdgcn_sched_barrier(0); asm volatile("s_waitcnt lgkmcnt(0)" ::: "memory"); __builtin_amdgcn_sched_barrier(0); } while (0)
; __device__ __forceinline__ void attn_unit(LAS unsigned char* lds, const bf16_t* Z, bf16_t* A2, const float* tabg, int seq_base, int S, int h, int qb, float lam) {
;     ...
;             for (int ds = 0; ds < 4; ++ds) { kf[2 * ds] = *(const LAS bf16x8*)(Kt + (kfo ^ (unsigned)(ds << 5))); kf[2 * ds + 1] = *(const LAS bf16x8*)(Kt + 32 * 256 + (kfo ^ (unsigned)(ds << 5))); }
;             __builtin_amdgcn_sched_barrier(0);
;             p0 = __builtin_amdgcn_mfma_f32_32x32x16_bf16(kf[0], qf[0], cblk, 0, 0, 0);
;             p1 = __builtin_amdgcn_mfma_f32_32x32x16_bf16(kf[1], qf[0], cblk, 0, 0, 0);
; #pragma unroll
;             for (int ds = 1; ds < 4; ++ds) {
;                 p0 = __builtin_amdgcn_mfma_f32_32x32x16_bf16(kf[2 * ds], qf[ds], p0, 0, 0, 0);
;                 p1 = __builtin_amdgcn_mfma_f32_32x32x16_bf16(kf[2 * ds + 1], qf[ds], p1, 0, 0, 0);
;             }
;     ...
; #pragma unroll
;         for (int r = 0; r < 16; ++r) { p0[r] = __builtin_amdgcn_exp2f(p0[r]); p1[r] = __builtin_amdgcn_exp2f(p1[r]); }
; #pragma unroll
;         for (int r = 0; r < 16; r += 2) { ls2 += (f32x2){p0[r], p0[r + 1]}; ls2 += (f32x2){p1[r], p1[r + 1]}; }
;         bf16x8 pa[4]; pa[0] = pack8(p0, 0); pa[1] = pack8(p0, 8); pa[2] = pack8(p1, 0); pa[3] = pack8(p1, 8);
;         LGKM0(); VREADS1(vb, 1); PV1(va, 0); LGKM0(); VREADS1(va, 2); PV1(vb, 1); LGKM0(); VREADS1(vb, 3); PV1(va, 2); LGKM0(); PV1(vb, 3);
.LatB_evret_m0:
	s_waitcnt lgkmcnt(12)
	v_mfma_f32_32x32x16_bf16 v[20:35], v[188:191], v[132:135], v[20:35]
	ds_read_b64_tr_b16 v[236:237], v171 offset:4096
	ds_read_b64_tr_b16 v[238:239], v171 offset:6144
	v_exp_f32_e32 v84, v84
	v_exp_f32_e32 v85, v85
	s_waitcnt lgkmcnt(12)
	v_mfma_f32_32x32x16_bf16 v[36:51], v[188:191], v[136:139], v[36:51]
	ds_read_b64_tr_b16 v[132:133], v168 offset:8192
	ds_read_b64_tr_b16 v[134:135], v168 offset:10240
	v_exp_f32_e32 v86, v86
	v_exp_f32_e32 v87, v87
	v_add_f32_e32 v252, v84, v86
	s_waitcnt lgkmcnt(12)
	v_mfma_f32_32x32x16_bf16 v[52:67], v[188:191], v[140:143], v[52:67]
	ds_read_b64_tr_b16 v[136:137], v169 offset:8192
	ds_read_b64_tr_b16 v[138:139], v169 offset:10240
	v_exp_f32_e32 v88, v88
	v_add_f32_e32 v253, v85, v87
	v_exp_f32_e32 v89, v89
	s_waitcnt lgkmcnt(12)
	s_add_u32 m0, s25, 0x1d000
	v_mfma_f32_32x32x16_bf16 v[68:83], v[188:191], v[144:147], v[68:83]
	global_load_lds_dwordx4 v172, s[8:9]
	ds_read_b64_tr_b16 v[140:141], v170 offset:8192
	ds_read_b64_tr_b16 v[142:143], v170 offset:10240
	v_cvt_pk_bf16_f32 v84, v84, v85
	v_exp_f32_e32 v90, v90
	v_cvt_pk_bf16_f32 v85, v86, v87
	s_waitcnt lgkmcnt(12)
	v_mfma_f32_32x32x16_bf16 v[20:35], v[192:195], v[220:223], v[20:35]
	ds_read_b64_tr_b16 v[144:145], v171 offset:8192
	ds_read_b64_tr_b16 v[146:147], v171 offset:10240
	v_exp_f32_e32 v91, v91
	v_add_f32_e32 v252, v252, v88
	v_add_f32_e32 v253, v253, v89
	v_cvt_pk_bf16_f32 v86, v88, v89
	s_waitcnt lgkmcnt(12)
	v_mfma_f32_32x32x16_bf16 v[36:51], v[192:195], v[224:227], v[36:51]
	ds_read_b64_tr_b16 v[220:221], v168 offset:12288
	ds_read_b64_tr_b16 v[222:223], v168 offset:14336
	v_add_f32_e32 v252, v252, v90
	v_add_f32_e32 v253, v253, v91
	v_cvt_pk_bf16_f32 v87, v90, v91
	v_exp_f32_e32 v92, v92
	s_waitcnt lgkmcnt(12)
	v_mfma_f32_32x32x16_bf16 v[52:67], v[192:195], v[232:235], v[52:67]
	ds_read_b64_tr_b16 v[224:225], v169 offset:12288
	ds_read_b64_tr_b16 v[226:227], v169 offset:14336
	v_exp_f32_e32 v93, v93
	v_exp_f32_e32 v94, v94
	s_waitcnt lgkmcnt(12)
	s_add_u32 m0, s27, 0x8000
	v_mfma_f32_32x32x16_bf16 v[68:83], v[192:195], v[236:239], v[68:83]
	global_load_lds_dwordx4 v174, s[8:9]
	ds_read_b64_tr_b16 v[232:233], v170 offset:12288
	ds_read_b64_tr_b16 v[234:235], v170 offset:14336
	v_add_f32_e32 v252, v252, v92
	v_exp_f32_e32 v95, v95
	v_add_f32_e32 v253, v253, v93
	s_waitcnt lgkmcnt(12)
	v_mfma_f32_32x32x16_bf16 v[20:35], v[204:207], v[132:135], v[20:35]
	ds_read_b64_tr_b16 v[236:237], v171 offset:12288
	ds_read_b64_tr_b16 v[238:239], v171 offset:14336
	v_exp_f32_e32 v96, v96
	v_add_f32_e32 v252, v252, v94
	v_exp_f32_e32 v97, v97
	s_waitcnt lgkmcnt(12)
	v_mfma_f32_32x32x16_bf16 v[36:51], v[204:207], v[136:139], v[36:51]
	ds_read_b128 v[132:135], v19 offset:16384
	v_add_f32_e32 v253, v253, v95
	v_exp_f32_e32 v98, v98
	v_cvt_pk_bf16_f32 v88, v92, v93
	s_waitcnt lgkmcnt(11)
	v_mfma_f32_32x32x16_bf16 v[52:67], v[204:207], v[140:143], v[52:67]
	ds_read_b128 v[136:139], v19 offset:24576
	v_exp_f32_e32 v99, v99
	v_cvt_pk_bf16_f32 v89, v94, v95
	v_add_f32_e32 v252, v252, v96
	v_add_f32_e32 v253, v253, v97
	s_waitcnt lgkmcnt(10)
	s_add_u32 m0, s25, 0x1f000
	v_mfma_f32_32x32x16_bf16 v[68:83], v[204:207], v[144:147], v[68:83]
	global_load_lds_dwordx4 v173, s[8:9]
	ds_read_b128 v[140:143], v180 offset:16384
	v_cvt_pk_bf16_f32 v90, v96, v97
	v_add_f32_e32 v252, v252, v98
	v_add_f32_e32 v253, v253, v99
	v_cvt_pk_bf16_f32 v91, v98, v99
	s_waitcnt lgkmcnt(9)
	v_mfma_f32_32x32x16_bf16 v[20:35], v[208:211], v[220:223], v[20:35]
	ds_read_b128 v[144:147], v180 offset:24576
	v_exp_f32_e32 v100, v100
	v_exp_f32_e32 v101, v101
	v_exp_f32_e32 v102, v102
	s_waitcnt lgkmcnt(8)
	v_mfma_f32_32x32x16_bf16 v[36:51], v[208:211], v[224:227], v[36:51]
	ds_read_b128 v[220:223], v181 offset:16384
	v_add_f32_e32 v252, v252, v100
	v_exp_f32_e32 v103, v103
	v_add_f32_e32 v253, v253, v101
	s_waitcnt lgkmcnt(7)
	v_mfma_f32_32x32x16_bf16 v[52:67], v[208:211], v[232:235], v[52:67]
	ds_read_b128 v[224:227], v181 offset:24576
	v_exp_f32_e32 v104, v104
	v_add_f32_e32 v252, v252, v102
	v_exp_f32_e32 v105, v105
	s_waitcnt lgkmcnt(6)
	s_add_u32 m0, s27, 0xa000
	v_mfma_f32_32x32x16_bf16 v[68:83], v[208:211], v[236:239], v[68:83]
	global_load_lds_dwordx4 v175, s[8:9]
	ds_read_b128 v[232:235], v182 offset:16384
	v_add_f32_e32 v253, v253, v103
	v_exp_f32_e32 v106, v106
	v_cvt_pk_bf16_f32 v100, v100, v101
	s_waitcnt lgkmcnt(6)
	v_mfma_f32_32x32x16_bf16 v[188:203], v[132:135], v[116:119], v[2:17]
	ds_read_b128 v[236:239], v182 offset:24576
	v_exp_f32_e32 v107, v107
	v_cvt_pk_bf16_f32 v101, v102, v103
	v_add_f32_e32 v252, v252, v104
	v_add_f32_e32 v253, v253, v105
	s_waitcnt lgkmcnt(6)
	v_mfma_f32_32x32x16_bf16 v[204:219], v[136:139], v[116:119], v[2:17]
	ds_read_b64_tr_b16 v[132:133], v228 offset:0
	ds_read_b64_tr_b16 v[134:135], v228 offset:2048
	v_cvt_pk_bf16_f32 v102, v104, v105
	v_add_f32_e32 v252, v252, v106
	v_add_f32_e32 v253, v253, v107
	v_cvt_pk_bf16_f32 v103, v106, v107
	s_waitcnt lgkmcnt(7)
	v_mfma_f32_32x32x16_bf16 v[188:203], v[140:143], v[120:123], v[188:203]
	ds_read_b64_tr_b16 v[136:137], v229 offset:0
	ds_read_b64_tr_b16 v[138:139], v229 offset:2048
	v_exp_f32_e32 v108, v108
	v_exp_f32_e32 v109, v109
	s_waitcnt lgkmcnt(8)
	v_mfma_f32_32x32x16_bf16 v[204:219], v[144:147], v[120:123], v[204:219]
	ds_read_b64_tr_b16 v[140:141], v230 offset:0
	ds_read_b64_tr_b16 v[142:143], v230 offset:2048
	v_exp_f32_e32 v110, v110
	v_add_f32_e32 v252, v252, v108
	v_exp_f32_e32 v111, v111
	v_add_f32_e32 v253, v253, v109
	s_waitcnt lgkmcnt(9)
	v_mfma_f32_32x32x16_bf16 v[188:203], v[220:223], v[124:127], v[188:203]
	ds_read_b64_tr_b16 v[144:145], v231 offset:0
	ds_read_b64_tr_b16 v[146:147], v231 offset:2048
	v_exp_f32_e32 v112, v112
	v_add_f32_e32 v252, v252, v110
	s_waitcnt lgkmcnt(10)
	v_mfma_f32_32x32x16_bf16 v[204:219], v[224:227], v[124:127], v[204:219]
	ds_read_b64_tr_b16 v[220:221], v228 offset:4096
	ds_read_b64_tr_b16 v[222:223], v228 offset:6144
	v_exp_f32_e32 v113, v113
	v_add_f32_e32 v253, v253, v111
	v_exp_f32_e32 v114, v114
	v_cvt_pk_bf16_f32 v104, v108, v109
	s_waitcnt lgkmcnt(11)
	v_mfma_f32_32x32x16_bf16 v[188:203], v[232:235], v[128:131], v[188:203]
	ds_read_b64_tr_b16 v[224:225], v229 offset:4096
	ds_read_b64_tr_b16 v[226:227], v229 offset:6144
	v_exp_f32_e32 v115, v115
	v_cvt_pk_bf16_f32 v105, v110, v111
	v_add_f32_e32 v252, v252, v112
	s_waitcnt lgkmcnt(12)
	v_mfma_f32_32x32x16_bf16 v[204:219], v[236:239], v[128:131], v[204:219]
	ds_read_b64_tr_b16 v[232:233], v230 offset:4096
	ds_read_b64_tr_b16 v[234:235], v230 offset:6144
	v_add_f32_e32 v253, v253, v113
	v_cvt_pk_bf16_f32 v106, v112, v113
	v_add_f32_e32 v252, v252, v114
	v_add_f32_e32 v253, v253, v115
	v_cvt_pk_bf16_f32 v107, v114, v115
	v_max_f32_e32 v251, v252, v253
	v_cmp_nge_f32_e32 vcc, 0x45800000, v251
	s_cbranch_vccnz .LatB_recs_m0

; #define LAS __attribute__((address_space(3)))
; #define VREADS1(arr, d_) do { const unsigned ad_ = vbase ^ (unsigned)((d_) << 6); __builtin_amdgcn_sched_barrier(0); \
;         _Pragma("unroll") for (int ks_ = 0; ks_ < 4; ++ks_) { VTR(arr[ks_ * 2], ad_, ks_ * 4096); VTR(arr[ks_ * 2 + 1], ad_, ks_ * 4096 + 2048); } __builtin_amdgcn_sched_barrier(0); } while (0)
; #define PV1(arr, d_) do { _Pragma("unroll") for (int ks_ = 0; ks_ < 4; ++ks_) { const s16x4 lo_ = arr[ks_ * 2], hh_ = arr[ks_ * 2 + 1]; \
;         const bf16x8 bv_ = (bf16x8){lo_[0], lo_[1], lo_[2], lo_[3], hh_[0], hh_[1], hh_[2], hh_[3]}; \
;         O[d_] = __builtin_amdgcn_mfma_f32_32x32x16_bf16(pa[ks_], bv_, O[d_], 0, 0, 0); } __builtin_amdgcn_sched_barrier(0); } while (0)
; #define LGKM0() do { __builtin_amdgcn_sched_barrier(0); asm volatile("s_waitcnt lgkmcnt(0)" ::: "memory"); __builtin_amdgcn_sched_barrier(0); } while (0)
; __device__ __forceinline__ void attn_unit(LAS unsigned char* lds, const bf16_t* Z, bf16_t* A2, const float* tabg, int seq_base, int S, int h, int qb, float lam) {
;     ...
;             for (int ds = 0; ds < 4; ++ds) { kf[2 * ds] = *(const LAS bf16x8*)(Kt + (kfo ^ (unsigned)(ds << 5))); kf[2 * ds + 1] = *(const LAS bf16x8*)(Kt + 32 * 256 + (kfo ^ (unsigned)(ds << 5))); }
;             __builtin_amdgcn_sched_barrier(0);
;             p0 = __builtin_amdgcn_mfma_f32_32x32x16_bf16(kf[0], qf[0], cblk, 0, 0, 0);
;             p1 = __builtin_amdgcn_mfma_f32_32x32x16_bf16(kf[1], qf[0], cblk, 0, 0, 0);
; #pragma unroll
;             for (int ds = 1; ds < 4; ++ds) {
;                 p0 = __builtin_amdgcn_mfma_f32_32x32x16_bf16(kf[2 * ds], qf[ds], p0, 0, 0, 0);
;                 p1 = __builtin_amdgcn_mfma_f32_32x32x16_bf16(kf[2 * ds + 1], qf[ds], p1, 0, 0, 0);
;             }
;     ...
; #pragma unroll
;         for (int r = 0; r < 16; ++r) { p0[r] = __builtin_amdgcn_exp2f(p0[r]); p1[r] = __builtin_amdgcn_exp2f(p1[r]); }
; #pragma unroll
;         for (int r = 0; r < 16; r += 2) { ls2 += (f32x2){p0[r], p0[r + 1]}; ls2 += (f32x2){p1[r], p1[r + 1]}; }
;         bf16x8 pa[4]; pa[0] = pack8(p0, 0); pa[1] = pack8(p0, 8); pa[2] = pack8(p1, 0); pa[3] = pack8(p1, 8);
;         LGKM0(); VREADS1(vb, 1); PV1(va, 0); LGKM0(); VREADS1(va, 2); PV1(vb, 1); LGKM0(); VREADS1(vb, 3); PV1(va, 2); LGKM0(); PV1(vb, 3);
.LatB_evret_x3:
	s_waitcnt lgkmcnt(12)
	v_mfma_f32_32x32x16_bf16 v[20:35], v[84:87], v[132:135], v[20:35]
	ds_read_b64_tr_b16 v[236:237], v231 offset:4096
	ds_read_b64_tr_b16 v[238:239], v231 offset:6144
	v_exp_f32_e32 v188, v188
	v_exp_f32_e32 v189, v189
	s_waitcnt lgkmcnt(12)
	v_mfma_f32_32x32x16_bf16 v[36:51], v[84:87], v[136:139], v[36:51]
	ds_read_b64_tr_b16 v[132:133], v228 offset:8192
	ds_read_b64_tr_b16 v[134:135], v228 offset:10240
	v_exp_f32_e32 v190, v190
	v_exp_f32_e32 v191, v191
	v_add_f32_e32 v252, v188, v190
	s_waitcnt lgkmcnt(12)
	v_mfma_f32_32x32x16_bf16 v[52:67], v[84:87], v[140:143], v[52:67]
	ds_read_b64_tr_b16 v[136:137], v229 offset:8192
	ds_read_b64_tr_b16 v[138:139], v229 offset:10240
	v_exp_f32_e32 v192, v192
	v_add_f32_e32 v253, v189, v191
	v_exp_f32_e32 v193, v193
	s_waitcnt lgkmcnt(12)
	v_mfma_f32_32x32x16_bf16 v[68:83], v[84:87], v[144:147], v[68:83]
	ds_read_b64_tr_b16 v[140:141], v230 offset:8192
	ds_read_b64_tr_b16 v[142:143], v230 offset:10240
	v_cvt_pk_bf16_f32 v188, v188, v189
	v_exp_f32_e32 v194, v194
	v_cvt_pk_bf16_f32 v189, v190, v191
	s_waitcnt lgkmcnt(12)
	v_mfma_f32_32x32x16_bf16 v[20:35], v[88:91], v[220:223], v[20:35]
	ds_read_b64_tr_b16 v[144:145], v231 offset:8192
	ds_read_b64_tr_b16 v[146:147], v231 offset:10240
	v_exp_f32_e32 v195, v195
	v_add_f32_e32 v252, v252, v192
	v_add_f32_e32 v253, v253, v193
	v_cvt_pk_bf16_f32 v190, v192, v193
	s_waitcnt lgkmcnt(12)
	v_mfma_f32_32x32x16_bf16 v[36:51], v[88:91], v[224:227], v[36:51]
	ds_read_b64_tr_b16 v[220:221], v228 offset:12288
	ds_read_b64_tr_b16 v[222:223], v228 offset:14336
	v_add_f32_e32 v252, v252, v194
	v_add_f32_e32 v253, v253, v195
	v_cvt_pk_bf16_f32 v191, v194, v195
	v_exp_f32_e32 v196, v196
	s_waitcnt lgkmcnt(12)
	v_mfma_f32_32x32x16_bf16 v[52:67], v[88:91], v[232:235], v[52:67]
	ds_read_b64_tr_b16 v[224:225], v229 offset:12288
	ds_read_b64_tr_b16 v[226:227], v229 offset:14336
	v_exp_f32_e32 v197, v197
	v_exp_f32_e32 v198, v198
	s_waitcnt lgkmcnt(12)
	s_add_u32 m0, s27, 0xd000
	v_mfma_f32_32x32x16_bf16 v[68:83], v[88:91], v[236:239], v[68:83]
	global_load_lds_dwordx4 v174, s[8:9]
	ds_read_b64_tr_b16 v[232:233], v230 offset:12288
	ds_read_b64_tr_b16 v[234:235], v230 offset:14336
	v_add_f32_e32 v252, v252, v196
	v_exp_f32_e32 v199, v199
	v_add_f32_e32 v253, v253, v197
	s_waitcnt lgkmcnt(12)
	v_mfma_f32_32x32x16_bf16 v[20:35], v[100:103], v[132:135], v[20:35]
	ds_read_b64_tr_b16 v[236:237], v231 offset:12288
	ds_read_b64_tr_b16 v[238:239], v231 offset:14336
	v_exp_f32_e32 v200, v200
	v_add_f32_e32 v252, v252, v198
	v_exp_f32_e32 v201, v201
	s_waitcnt lgkmcnt(12)
	v_mfma_f32_32x32x16_bf16 v[36:51], v[100:103], v[136:139], v[36:51]
	ds_read_b128 v[132:135], v19 offset:32768
	v_add_f32_e32 v253, v253, v199
	v_exp_f32_e32 v202, v202
	v_cvt_pk_bf16_f32 v192, v196, v197
	s_waitcnt lgkmcnt(11)
	v_mfma_f32_32x32x16_bf16 v[52:67], v[100:103], v[140:143], v[52:67]
	ds_read_b128 v[136:139], v19 offset:40960
	v_exp_f32_e32 v203, v203
	v_cvt_pk_bf16_f32 v193, v198, v199
	v_add_f32_e32 v252, v252, v200
	v_add_f32_e32 v253, v253, v201
	s_waitcnt lgkmcnt(10)
	v_mfma_f32_32x32x16_bf16 v[68:83], v[100:103], v[144:147], v[68:83]
	ds_read_b128 v[140:143], v180 offset:32768
	v_cvt_pk_bf16_f32 v194, v200, v201
	v_add_f32_e32 v252, v252, v202
	v_add_f32_e32 v253, v253, v203
	v_cvt_pk_bf16_f32 v195, v202, v203
	s_waitcnt lgkmcnt(9)
	v_mfma_f32_32x32x16_bf16 v[20:35], v[104:107], v[220:223], v[20:35]
	ds_read_b128 v[144:147], v180 offset:40960
	v_exp_f32_e32 v204, v204
	v_exp_f32_e32 v205, v205
	v_exp_f32_e32 v206, v206
	s_waitcnt lgkmcnt(8)
	v_mfma_f32_32x32x16_bf16 v[36:51], v[104:107], v[224:227], v[36:51]
	ds_read_b128 v[220:223], v181 offset:32768
	v_add_f32_e32 v252, v252, v204
	v_exp_f32_e32 v207, v207
	v_add_f32_e32 v253, v253, v205
	s_waitcnt lgkmcnt(7)
	v_mfma_f32_32x32x16_bf16 v[52:67], v[104:107], v[232:235], v[52:67]
	ds_read_b128 v[224:227], v181 offset:40960
	v_exp_f32_e32 v208, v208
	v_add_f32_e32 v252, v252, v206
	v_exp_f32_e32 v209, v209
	s_waitcnt lgkmcnt(6)
	s_add_u32 m0, s27, 0xf000
	v_mfma_f32_32x32x16_bf16 v[68:83], v[104:107], v[236:239], v[68:83]
	global_load_lds_dwordx4 v175, s[8:9]
	ds_read_b128 v[232:235], v182 offset:32768
	v_add_f32_e32 v253, v253, v207
	v_exp_f32_e32 v210, v210
	v_cvt_pk_bf16_f32 v204, v204, v205
	s_waitcnt lgkmcnt(6)
	v_mfma_f32_32x32x16_bf16 v[84:99], v[132:135], v[116:119], v[2:17]
	ds_read_b128 v[236:239], v182 offset:40960
	v_exp_f32_e32 v211, v211
	v_cvt_pk_bf16_f32 v205, v206, v207
	v_add_f32_e32 v252, v252, v208
	v_add_f32_e32 v253, v253, v209
	s_waitcnt lgkmcnt(6)
	v_mfma_f32_32x32x16_bf16 v[100:115], v[136:139], v[116:119], v[2:17]
	ds_read_b64_tr_b16 v[132:133], v228 offset:16384
	ds_read_b64_tr_b16 v[134:135], v228 offset:18432
	v_cvt_pk_bf16_f32 v206, v208, v209
	v_add_f32_e32 v252, v252, v210
	v_add_f32_e32 v253, v253, v211
	v_cvt_pk_bf16_f32 v207, v210, v211
	s_waitcnt lgkmcnt(7)
	v_mfma_f32_32x32x16_bf16 v[84:99], v[140:143], v[120:123], v[84:99]
	ds_read_b64_tr_b16 v[136:137], v229 offset:16384
	ds_read_b64_tr_b16 v[138:139], v229 offset:18432
	v_exp_f32_e32 v212, v212
	v_exp_f32_e32 v213, v213
	s_waitcnt lgkmcnt(8)
	v_mfma_f32_32x32x16_bf16 v[100:115], v[144:147], v[120:123], v[100:115]
	ds_read_b64_tr_b16 v[140:141], v230 offset:16384
	ds_read_b64_tr_b16 v[142:143], v230 offset:18432
	v_exp_f32_e32 v214, v214
	v_add_f32_e32 v252, v252, v212
	v_exp_f32_e32 v215, v215
	v_add_f32_e32 v253, v253, v213
	s_waitcnt lgkmcnt(9)
	v_mfma_f32_32x32x16_bf16 v[84:99], v[220:223], v[124:127], v[84:99]
	ds_read_b64_tr_b16 v[144:145], v231 offset:16384
	ds_read_b64_tr_b16 v[146:147], v231 offset:18432
	v_exp_f32_e32 v216, v216
	v_add_f32_e32 v252, v252, v214
	s_waitcnt lgkmcnt(10)
	v_mfma_f32_32x32x16_bf16 v[100:115], v[224:227], v[124:127], v[100:115]
	ds_read_b64_tr_b16 v[220:221], v228 offset:20480
	ds_read_b64_tr_b16 v[222:223], v228 offset:22528
	v_exp_f32_e32 v217, v217
	v_add_f32_e32 v253, v253, v215
	v_exp_f32_e32 v218, v218
	v_cvt_pk_bf16_f32 v208, v212, v213
	s_waitcnt lgkmcnt(11)
	v_mfma_f32_32x32x16_bf16 v[84:99], v[232:235], v[128:131], v[84:99]
	ds_read_b64_tr_b16 v[224:225], v229 offset:20480
	ds_read_b64_tr_b16 v[226:227], v229 offset:22528
	v_exp_f32_e32 v219, v219
	v_cvt_pk_bf16_f32 v209, v214, v215
	v_add_f32_e32 v252, v252, v216
	s_waitcnt lgkmcnt(12)
	v_mfma_f32_32x32x16_bf16 v[100:115], v[236:239], v[128:131], v[100:115]
	ds_read_b64_tr_b16 v[232:233], v230 offset:20480
	ds_read_b64_tr_b16 v[234:235], v230 offset:22528
	v_add_f32_e32 v253, v253, v217
	v_cvt_pk_bf16_f32 v210, v216, v217
	v_add_f32_e32 v252, v252, v218
	v_add_f32_e32 v253, v253, v219
	v_cvt_pk_bf16_f32 v211, v218, v219
	v_max_f32_e32 v251, v252, v253
	v_cmp_nge_f32_e32 vcc, 0x45800000, v251
	s_cbranch_vccnz .LatB_recs_x3

; #define LAS __attribute__((address_space(3)))
; __device__ __forceinline__ float max2f(float a, float b) { float r; asm("v_max_f32_e32 %0, %1, %2" : "=v"(r) : "v"(a), "v"(b)); return r; }
; __device__ __forceinline__ void attn_unit(LAS unsigned char* lds, const bf16_t* Z, bf16_t* A2, const float* tabg, int seq_base, int S, int h, int qb, float lam) {
;     ...
;         float mx = max2f(max16f(p0), max16f(p1));
;         const bool first = (t == 0);
;         if (first || __any(mx > THR)) {
;             { auto rr = __builtin_amdgcn_permlane32_swap(__float_as_uint(mx), __float_as_uint(mx), false, false); mx = max2f(__uint_as_float(rr[0]), __uint_as_float(rr[1])); }
;             const float delta = first ? mx : fmaxf(mx, 0.f);
;             const float alpha = first ? 1.0f : __builtin_amdgcn_exp2f(-delta);
;             mu += delta; ls2 *= alpha;
;             if (!first) {
;                 asm volatile("" ::: "memory");
;                 scr[r32] = alpha;
;                 asm volatile("s_waitcnt lgkmcnt(0)" ::: "memory");
; #pragma unroll
;                 for (int g = 0; g < 4; ++g) { const f32x4 a4 = *(const LAS f32x4*)(scr + 8 * g + 4 * hi);
; #pragma unroll
;                     for (int d = 0; d < 4; ++d) { O[d][4 * g + 0] *= a4[0]; O[d][4 * g + 1] *= a4[1]; O[d][4 * g + 2] *= a4[2]; O[d][4 * g + 3] *= a4[3]; } }
;                 asm volatile("s_waitcnt lgkmcnt(0)" ::: "memory");
;             }
; #pragma unroll
;             for (int r = 0; r < 16; ++r) { p0[r] -= delta; p1[r] -= delta; }
.LatB_recnn_0:
	v_max3_f32 v251, v84, v85, v86
	v_max3_f32 v252, v87, v88, v89
	v_max3_f32 v251, v251, v90, v91
	v_max3_f32 v252, v252, v92, v93
	v_max3_f32 v251, v251, v94, v95
	v_max3_f32 v252, v252, v96, v97
	v_max3_f32 v251, v251, v98, v99
	v_max3_f32 v252, v252, v100, v101
	v_max3_f32 v251, v251, v102, v103
	v_max3_f32 v252, v252, v104, v105
	v_max3_f32 v251, v251, v106, v107
	v_max3_f32 v252, v252, v108, v109
	v_max3_f32 v251, v251, v110, v111
	v_max3_f32 v252, v252, v112, v113
	v_max3_f32 v251, v251, v114, v115
	v_max_f32_e32 v251, v251, v252
	v_mov_b32_e32 v252, v251
	s_nop 1
	v_permlane32_swap_b32_e32 v251, v252
	v_max_f32_e32 v251, v251, v252
	v_max_f32_e32 v253, 0, v251
	v_exp_f32_e64 v254, -v253
	v_add_f32_e32 v186, v186, v253
	s_nop 0
	v_mul_f32_e32 v150, v150, v254
	v_mul_f32_e32 v151, v151, v254
	ds_write_b32 v184, v254
	s_waitcnt lgkmcnt(0)
	ds_read_b128 v[132:135], v185
	ds_read_b128 v[136:139], v185 offset:32
	ds_read_b128 v[140:143], v185 offset:64
	ds_read_b128 v[144:147], v185 offset:96
	s_waitcnt lgkmcnt(0)
	v_pk_mul_f32 v[20:21], v[20:21], v[132:133]
	v_pk_mul_f32 v[22:23], v[22:23], v[134:135]
	v_pk_mul_f32 v[24:25], v[24:25], v[136:137]
	v_pk_mul_f32 v[26:27], v[26:27], v[138:139]
	v_pk_mul_f32 v[28:29], v[28:29], v[140:141]
	v_pk_mul_f32 v[30:31], v[30:31], v[142:143]
	v_pk_mul_f32 v[32:33], v[32:33], v[144:145]
	v_pk_mul_f32 v[34:35], v[34:35], v[146:147]
	v_pk_mul_f32 v[36:37], v[36:37], v[132:133]
	v_pk_mul_f32 v[38:39], v[38:39], v[134:135]
	v_pk_mul_f32 v[40:41], v[40:41], v[136:137]
	v_pk_mul_f32 v[42:43], v[42:43], v[138:139]
	v_pk_mul_f32 v[44:45], v[44:45], v[140:141]
	v_pk_mul_f32 v[46:47], v[46:47], v[142:143]
	v_pk_mul_f32 v[48:49], v[48:49], v[144:145]
	v_pk_mul_f32 v[50:51], v[50:51], v[146:147]
	v_pk_mul_f32 v[52:53], v[52:53], v[132:133]
	v_pk_mul_f32 v[54:55], v[54:55], v[134:135]
	v_pk_mul_f32 v[56:57], v[56:57], v[136:137]
	v_pk_mul_f32 v[58:59], v[58:59], v[138:139]
	v_pk_mul_f32 v[60:61], v[60:61], v[140:141]
	v_pk_mul_f32 v[62:63], v[62:63], v[142:143]
	v_pk_mul_f32 v[64:65], v[64:65], v[144:145]
	v_pk_mul_f32 v[66:67], v[66:67], v[146:147]
	v_pk_mul_f32 v[68:69], v[68:69], v[132:133]
	v_pk_mul_f32 v[70:71], v[70:71], v[134:135]
	v_pk_mul_f32 v[72:73], v[72:73], v[136:137]
	v_pk_mul_f32 v[74:75], v[74:75], v[138:139]
	v_pk_mul_f32 v[76:77], v[76:77], v[140:141]
	v_pk_mul_f32 v[78:79], v[78:79], v[142:143]
	v_pk_mul_f32 v[80:81], v[80:81], v[144:145]
	v_pk_mul_f32 v[82:83], v[82:83], v[146:147]
	v_mov_b32_e32 v252, v253
	v_pk_add_f32 v[84:85], v[84:85], v[252:253] neg_lo:[0,1] neg_hi:[0,1]
	v_pk_add_f32 v[86:87], v[86:87], v[252:253] neg_lo:[0,1] neg_hi:[0,1]
	v_pk_add_f32 v[88:89], v[88:89], v[252:253] neg_lo:[0,1] neg_hi:[0,1]
	v_pk_add_f32 v[90:91], v[90:91], v[252:253] neg_lo:[0,1] neg_hi:[0,1]
	v_pk_add_f32 v[92:93], v[92:93], v[252:253] neg_lo:[0,1] neg_hi:[0,1]
	v_pk_add_f32 v[94:95], v[94:95], v[252:253] neg_lo:[0,1] neg_hi:[0,1]
	v_pk_add_f32 v[96:97], v[96:97], v[252:253] neg_lo:[0,1] neg_hi:[0,1]
	v_pk_add_f32 v[98:99], v[98:99], v[252:253] neg_lo:[0,1] neg_hi:[0,1]
	v_pk_add_f32 v[100:101], v[100:101], v[252:253] neg_lo:[0,1] neg_hi:[0,1]
	v_pk_add_f32 v[102:103], v[102:103], v[252:253] neg_lo:[0,1] neg_hi:[0,1]
	v_pk_add_f32 v[104:105], v[104:105], v[252:253] neg_lo:[0,1] neg_hi:[0,1]
	v_pk_add_f32 v[106:107], v[106:107], v[252:253] neg_lo:[0,1] neg_hi:[0,1]
	v_pk_add_f32 v[108:109], v[108:109], v[252:253] neg_lo:[0,1] neg_hi:[0,1]
	v_pk_add_f32 v[110:111], v[110:111], v[252:253] neg_lo:[0,1] neg_hi:[0,1]
	v_pk_add_f32 v[112:113], v[112:113], v[252:253] neg_lo:[0,1] neg_hi:[0,1]
	v_pk_add_f32 v[114:115], v[114:115], v[252:253] neg_lo:[0,1] neg_hi:[0,1]
	v_pk_add_f32 v[188:189], v[188:189], v[252:253] neg_lo:[0,1] neg_hi:[0,1]
	v_pk_add_f32 v[190:191], v[190:191], v[252:253] neg_lo:[0,1] neg_hi:[0,1]
	v_pk_add_f32 v[192:193], v[192:193], v[252:253] neg_lo:[0,1] neg_hi:[0,1]
	v_pk_add_f32 v[194:195], v[194:195], v[252:253] neg_lo:[0,1] neg_hi:[0,1]
	v_pk_add_f32 v[196:197], v[196:197], v[252:253] neg_lo:[0,1] neg_hi:[0,1]
	v_pk_add_f32 v[198:199], v[198:199], v[252:253] neg_lo:[0,1] neg_hi:[0,1]
	v_pk_add_f32 v[200:201], v[200:201], v[252:253] neg_lo:[0,1] neg_hi:[0,1]
	v_pk_add_f32 v[202:203], v[202:203], v[252:253] neg_lo:[0,1] neg_hi:[0,1]
; __device__ __forceinline__ void attn_unit(LAS unsigned char* lds, const bf16_t* Z, bf16_t* A2, const float* tabg, int seq_base, int S, int h, int qb, float lam) {
;     ...
;         { const float coff = cc - mu;
;           if (__any(!(coff == coff_cur))) { coff_cur = coff;
; #pragma unroll
;               for (int r = 0; r < 16; ++r) cblk[r] = coff;
;               asm volatile("" : "+v"(cblk)); } }
;     ...
;             for (int r = 0; r < 16; ++r) { p0[r] -= delta; p1[r] -= delta; }
;             asm volatile("" : "+v"(p0), "+v"(p1));
;         }
; #pragma unroll
;         for (int r = 0; r < 16; ++r) { p0[r] = __builtin_amdgcn_exp2f(p0[r]); p1[r] = __builtin_amdgcn_exp2f(p1[r]); }
; #pragma unroll
;         for (int r = 0; r < 16; r += 2) { ls2 += (f32x2){p0[r], p0[r + 1]}; ls2 += (f32x2){p1[r], p1[r + 1]}; }
;         bf16x8 pa[4]; pa[0] = pack8(p0, 0); pa[1] = pack8(p0, 8); pa[2] = pack8(p1, 0); pa[3] = pack8(p1, 8);
	v_pk_add_f32 v[204:205], v[204:205], v[252:253] neg_lo:[0,1] neg_hi:[0,1]
	v_pk_add_f32 v[206:207], v[206:207], v[252:253] neg_lo:[0,1] neg_hi:[0,1]
	v_pk_add_f32 v[208:209], v[208:209], v[252:253] neg_lo:[0,1] neg_hi:[0,1]
	v_pk_add_f32 v[210:211], v[210:211], v[252:253] neg_lo:[0,1] neg_hi:[0,1]
	v_pk_add_f32 v[212:213], v[212:213], v[252:253] neg_lo:[0,1] neg_hi:[0,1]
	v_pk_add_f32 v[214:215], v[214:215], v[252:253] neg_lo:[0,1] neg_hi:[0,1]
	v_pk_add_f32 v[216:217], v[216:217], v[252:253] neg_lo:[0,1] neg_hi:[0,1]
	v_pk_add_f32 v[218:219], v[218:219], v[252:253] neg_lo:[0,1] neg_hi:[0,1]
	v_exp_f32_e32 v84, v84
	v_exp_f32_e32 v85, v85
	v_exp_f32_e32 v86, v86
	v_exp_f32_e32 v87, v87
	v_add_f32_e32 v252, v84, v86
	v_exp_f32_e32 v88, v88
	v_add_f32_e32 v253, v85, v87
	v_exp_f32_e32 v89, v89
	v_cvt_pk_bf16_f32 v84, v84, v85
	v_exp_f32_e32 v90, v90
	v_cvt_pk_bf16_f32 v85, v86, v87
	v_exp_f32_e32 v91, v91
	v_add_f32_e32 v252, v252, v88
	v_add_f32_e32 v253, v253, v89
	v_cvt_pk_bf16_f32 v86, v88, v89
	v_add_f32_e32 v252, v252, v90
	v_add_f32_e32 v253, v253, v91
	v_cvt_pk_bf16_f32 v87, v90, v91
	v_exp_f32_e32 v92, v92
	v_exp_f32_e32 v93, v93
	v_exp_f32_e32 v94, v94
	v_add_f32_e32 v252, v252, v92
	v_exp_f32_e32 v95, v95
	v_add_f32_e32 v253, v253, v93
	v_exp_f32_e32 v96, v96
	v_add_f32_e32 v252, v252, v94
	v_exp_f32_e32 v97, v97
	v_add_f32_e32 v253, v253, v95
	v_exp_f32_e32 v98, v98
	v_cvt_pk_bf16_f32 v88, v92, v93
	v_exp_f32_e32 v99, v99
	v_cvt_pk_bf16_f32 v89, v94, v95
	v_add_f32_e32 v252, v252, v96
	v_add_f32_e32 v253, v253, v97
	v_cvt_pk_bf16_f32 v90, v96, v97
	v_add_f32_e32 v252, v252, v98
	v_add_f32_e32 v253, v253, v99
	v_cvt_pk_bf16_f32 v91, v98, v99
	v_exp_f32_e32 v100, v100
	v_exp_f32_e32 v101, v101
	v_exp_f32_e32 v102, v102
	v_add_f32_e32 v252, v252, v100
	v_exp_f32_e32 v103, v103
	v_add_f32_e32 v253, v253, v101
	v_exp_f32_e32 v104, v104
	v_add_f32_e32 v252, v252, v102
	v_exp_f32_e32 v105, v105
	v_add_f32_e32 v253, v253, v103
	v_exp_f32_e32 v106, v106
	v_cvt_pk_bf16_f32 v100, v100, v101
	v_exp_f32_e32 v107, v107
	v_cvt_pk_bf16_f32 v101, v102, v103
	v_add_f32_e32 v252, v252, v104
	v_add_f32_e32 v253, v253, v105
	v_cvt_pk_bf16_f32 v102, v104, v105
	v_add_f32_e32 v252, v252, v106
	v_add_f32_e32 v253, v253, v107
	v_cvt_pk_bf16_f32 v103, v106, v107
	v_exp_f32_e32 v108, v108
	v_exp_f32_e32 v109, v109
	v_exp_f32_e32 v110, v110
	v_add_f32_e32 v252, v252, v108
	v_exp_f32_e32 v111, v111
	v_add_f32_e32 v253, v253, v109
	v_exp_f32_e32 v112, v112
	v_add_f32_e32 v252, v252, v110
	v_exp_f32_e32 v113, v113
	v_add_f32_e32 v253, v253, v111
	v_exp_f32_e32 v114, v114
	v_cvt_pk_bf16_f32 v104, v108, v109
	v_exp_f32_e32 v115, v115
	v_cvt_pk_bf16_f32 v105, v110, v111
	v_add_f32_e32 v252, v252, v112
	v_add_f32_e32 v253, v253, v113
	v_cvt_pk_bf16_f32 v106, v112, v113
	v_add_f32_e32 v252, v252, v114
	v_add_f32_e32 v253, v253, v115
	v_cvt_pk_bf16_f32 v107, v114, v115
	s_mov_b32 s24, s23
	s_mov_b32 s35, s24
	v_mov_b32_e32 v251, 0
	s_cmp_eq_u32 s24, 1
	s_cselect_b64 vcc, -1, 0
	v_cndmask_b32_e32 v251, v251, v177, vcc
	s_cmp_eq_u32 s24, 2
	s_cselect_b64 vcc, -1, 0
	v_cndmask_b32_e32 v251, v251, v178, vcc
	v_sub_f32_e32 v2, v251, v186
	v_mov_b32_e32 v3, v2
	v_mov_b64_e32 v[4:5], v[2:3]
	v_mov_b64_e32 v[6:7], v[2:3]
	v_mov_b64_e32 v[8:9], v[2:3]
	v_mov_b64_e32 v[10:11], v[2:3]
	v_mov_b64_e32 v[12:13], v[2:3]
	v_mov_b64_e32 v[14:15], v[2:3]
	v_mov_b64_e32 v[16:17], v[2:3]
	ds_read_b64_tr_b16 v[132:133], v228 offset:0
	ds_read_b64_tr_b16 v[134:135], v228 offset:2048
	ds_read_b64_tr_b16 v[136:137], v229 offset:0
	ds_read_b64_tr_b16 v[138:139], v229 offset:2048
	ds_read_b64_tr_b16 v[140:141], v230 offset:0
	ds_read_b64_tr_b16 v[142:143], v230 offset:2048
	ds_read_b64_tr_b16 v[144:145], v231 offset:0
	ds_read_b64_tr_b16 v[146:147], v231 offset:2048
	ds_read_b64_tr_b16 v[220:221], v228 offset:4096
	ds_read_b64_tr_b16 v[222:223], v228 offset:6144
	ds_read_b64_tr_b16 v[224:225], v229 offset:4096
	ds_read_b64_tr_b16 v[226:227], v229 offset:6144
	ds_read_b64_tr_b16 v[232:233], v230 offset:4096
	ds_read_b64_tr_b16 v[234:235], v230 offset:6144
	s_nop 1
	s_cmp_eq_u32 s22, 0
	s_cbranch_scc1 .LatB_recret_h0
	s_cmp_eq_u32 s22, 1
	s_cbranch_scc1 .LatB_recret_m0
	s_branch .LatB_recret_x4

; #define LAS __attribute__((address_space(3)))
; __device__ __forceinline__ float max2f(float a, float b) { float r; asm("v_max_f32_e32 %0, %1, %2" : "=v"(r) : "v"(a), "v"(b)); return r; }
; __device__ __forceinline__ void attn_unit(LAS unsigned char* lds, const bf16_t* Z, bf16_t* A2, const float* tabg, int seq_base, int S, int h, int qb, float lam) {
;     ...
;         float mx = max2f(max16f(p0), max16f(p1));
;         const bool first = (t == 0);
;         if (first || __any(mx > THR)) {
;             { auto rr = __builtin_amdgcn_permlane32_swap(__float_as_uint(mx), __float_as_uint(mx), false, false); mx = max2f(__uint_as_float(rr[0]), __uint_as_float(rr[1])); }
;             const float delta = first ? mx : fmaxf(mx, 0.f);
;             const float alpha = first ? 1.0f : __builtin_amdgcn_exp2f(-delta);
;             mu += delta; ls2 *= alpha;
;             if (!first) {
;                 asm volatile("" ::: "memory");
;                 scr[r32] = alpha;
;                 asm volatile("s_waitcnt lgkmcnt(0)" ::: "memory");
; #pragma unroll
;                 for (int g = 0; g < 4; ++g) { const f32x4 a4 = *(const LAS f32x4*)(scr + 8 * g + 4 * hi);
; #pragma unroll
;                     for (int d = 0; d < 4; ++d) { O[d][4 * g + 0] *= a4[0]; O[d][4 * g + 1] *= a4[1]; O[d][4 * g + 2] *= a4[2]; O[d][4 * g + 3] *= a4[3]; } }
;                 asm volatile("s_waitcnt lgkmcnt(0)" ::: "memory");
;             }
; #pragma unroll
;             for (int r = 0; r < 16; ++r) { p0[r] -= delta; p1[r] -= delta; }
.LatB_recnn_1:
	v_max3_f32 v251, v188, v189, v190
	v_max3_f32 v252, v191, v192, v193
	v_max3_f32 v251, v251, v194, v195
	v_max3_f32 v252, v252, v196, v197
	v_max3_f32 v251, v251, v198, v199
	v_max3_f32 v252, v252, v200, v201
	v_max3_f32 v251, v251, v202, v203
	v_max3_f32 v252, v252, v204, v205
	v_max3_f32 v251, v251, v206, v207
	v_max3_f32 v252, v252, v208, v209
	v_max3_f32 v251, v251, v210, v211
	v_max3_f32 v252, v252, v212, v213
	v_max3_f32 v251, v251, v214, v215
	v_max3_f32 v252, v252, v216, v217
	v_max3_f32 v251, v251, v218, v219
	v_max_f32_e32 v251, v251, v252
	v_mov_b32_e32 v252, v251
	s_nop 1
	v_permlane32_swap_b32_e32 v251, v252
	v_max_f32_e32 v251, v251, v252
	v_max_f32_e32 v253, 0, v251
	v_exp_f32_e64 v254, -v253
	v_add_f32_e32 v186, v186, v253
	s_nop 0
	v_mul_f32_e32 v150, v150, v254
	v_mul_f32_e32 v151, v151, v254
	ds_write_b32 v184, v254
	s_waitcnt lgkmcnt(0)
	ds_read_b128 v[132:135], v185
	ds_read_b128 v[136:139], v185 offset:32
	ds_read_b128 v[140:143], v185 offset:64
	ds_read_b128 v[144:147], v185 offset:96
	s_waitcnt lgkmcnt(0)
	v_pk_mul_f32 v[20:21], v[20:21], v[132:133]
	v_pk_mul_f32 v[22:23], v[22:23], v[134:135]
	v_pk_mul_f32 v[24:25], v[24:25], v[136:137]
	v_pk_mul_f32 v[26:27], v[26:27], v[138:139]
	v_pk_mul_f32 v[28:29], v[28:29], v[140:141]
	v_pk_mul_f32 v[30:31], v[30:31], v[142:143]
	v_pk_mul_f32 v[32:33], v[32:33], v[144:145]
	v_pk_mul_f32 v[34:35], v[34:35], v[146:147]
	v_pk_mul_f32 v[36:37], v[36:37], v[132:133]
	v_pk_mul_f32 v[38:39], v[38:39], v[134:135]
	v_pk_mul_f32 v[40:41], v[40:41], v[136:137]
	v_pk_mul_f32 v[42:43], v[42:43], v[138:139]
	v_pk_mul_f32 v[44:45], v[44:45], v[140:141]
	v_pk_mul_f32 v[46:47], v[46:47], v[142:143]
	v_pk_mul_f32 v[48:49], v[48:49], v[144:145]
	v_pk_mul_f32 v[50:51], v[50:51], v[146:147]
	v_pk_mul_f32 v[52:53], v[52:53], v[132:133]
	v_pk_mul_f32 v[54:55], v[54:55], v[134:135]
	v_pk_mul_f32 v[56:57], v[56:57], v[136:137]
	v_pk_mul_f32 v[58:59], v[58:59], v[138:139]
	v_pk_mul_f32 v[60:61], v[60:61], v[140:141]
	v_pk_mul_f32 v[62:63], v[62:63], v[142:143]
	v_pk_mul_f32 v[64:65], v[64:65], v[144:145]
	v_pk_mul_f32 v[66:67], v[66:67], v[146:147]
	v_pk_mul_f32 v[68:69], v[68:69], v[132:133]
	v_pk_mul_f32 v[70:71], v[70:71], v[134:135]
	v_pk_mul_f32 v[72:73], v[72:73], v[136:137]
	v_pk_mul_f32 v[74:75], v[74:75], v[138:139]
	v_pk_mul_f32 v[76:77], v[76:77], v[140:141]
	v_pk_mul_f32 v[78:79], v[78:79], v[142:143]
	v_pk_mul_f32 v[80:81], v[80:81], v[144:145]
	v_pk_mul_f32 v[82:83], v[82:83], v[146:147]
	v_mov_b32_e32 v252, v253
	v_pk_add_f32 v[188:189], v[188:189], v[252:253] neg_lo:[0,1] neg_hi:[0,1]
	v_pk_add_f32 v[190:191], v[190:191], v[252:253] neg_lo:[0,1] neg_hi:[0,1]
	v_pk_add_f32 v[192:193], v[192:193], v[252:253] neg_lo:[0,1] neg_hi:[0,1]
	v_pk_add_f32 v[194:195], v[194:195], v[252:253] neg_lo:[0,1] neg_hi:[0,1]
	v_pk_add_f32 v[196:197], v[196:197], v[252:253] neg_lo:[0,1] neg_hi:[0,1]
	v_pk_add_f32 v[198:199], v[198:199], v[252:253] neg_lo:[0,1] neg_hi:[0,1]
	v_pk_add_f32 v[200:201], v[200:201], v[252:253] neg_lo:[0,1] neg_hi:[0,1]
	v_pk_add_f32 v[202:203], v[202:203], v[252:253] neg_lo:[0,1] neg_hi:[0,1]
	v_pk_add_f32 v[204:205], v[204:205], v[252:253] neg_lo:[0,1] neg_hi:[0,1]
	v_pk_add_f32 v[206:207], v[206:207], v[252:253] neg_lo:[0,1] neg_hi:[0,1]
	v_pk_add_f32 v[208:209], v[208:209], v[252:253] neg_lo:[0,1] neg_hi:[0,1]
	v_pk_add_f32 v[210:211], v[210:211], v[252:253] neg_lo:[0,1] neg_hi:[0,1]
	v_pk_add_f32 v[212:213], v[212:213], v[252:253] neg_lo:[0,1] neg_hi:[0,1]
	v_pk_add_f32 v[214:215], v[214:215], v[252:253] neg_lo:[0,1] neg_hi:[0,1]
	v_pk_add_f32 v[216:217], v[216:217], v[252:253] neg_lo:[0,1] neg_hi:[0,1]
	v_pk_add_f32 v[218:219], v[218:219], v[252:253] neg_lo:[0,1] neg_hi:[0,1]
	v_pk_add_f32 v[84:85], v[84:85], v[252:253] neg_lo:[0,1] neg_hi:[0,1]
	v_pk_add_f32 v[86:87], v[86:87], v[252:253] neg_lo:[0,1] neg_hi:[0,1]
	v_pk_add_f32 v[88:89], v[88:89], v[252:253] neg_lo:[0,1] neg_hi:[0,1]
	v_pk_add_f32 v[90:91], v[90:91], v[252:253] neg_lo:[0,1] neg_hi:[0,1]
	v_pk_add_f32 v[92:93], v[92:93], v[252:253] neg_lo:[0,1] neg_hi:[0,1]
	v_pk_add_f32 v[94:95], v[94:95], v[252:253] neg_lo:[0,1] neg_hi:[0,1]
	v_pk_add_f32 v[96:97], v[96:97], v[252:253] neg_lo:[0,1] neg_hi:[0,1]
	v_pk_add_f32 v[98:99], v[98:99], v[252:253] neg_lo:[0,1] neg_hi:[0,1]
; __device__ __forceinline__ void attn_unit(LAS unsigned char* lds, const bf16_t* Z, bf16_t* A2, const float* tabg, int seq_base, int S, int h, int qb, float lam) {
;     ...
;         { const float coff = cc - mu;
;           if (__any(!(coff == coff_cur))) { coff_cur = coff;
; #pragma unroll
;               for (int r = 0; r < 16; ++r) cblk[r] = coff;
;               asm volatile("" : "+v"(cblk)); } }
;     ...
;             for (int r = 0; r < 16; ++r) { p0[r] -= delta; p1[r] -= delta; }
;             asm volatile("" : "+v"(p0), "+v"(p1));
;         }
; #pragma unroll
;         for (int r = 0; r < 16; ++r) { p0[r] = __builtin_amdgcn_exp2f(p0[r]); p1[r] = __builtin_amdgcn_exp2f(p1[r]); }
; #pragma unroll
;         for (int r = 0; r < 16; r += 2) { ls2 += (f32x2){p0[r], p0[r + 1]}; ls2 += (f32x2){p1[r], p1[r + 1]}; }
;         bf16x8 pa[4]; pa[0] = pack8(p0, 0); pa[1] = pack8(p0, 8); pa[2] = pack8(p1, 0); pa[3] = pack8(p1, 8);
	v_pk_add_f32 v[100:101], v[100:101], v[252:253] neg_lo:[0,1] neg_hi:[0,1]
	v_pk_add_f32 v[102:103], v[102:103], v[252:253] neg_lo:[0,1] neg_hi:[0,1]
	v_pk_add_f32 v[104:105], v[104:105], v[252:253] neg_lo:[0,1] neg_hi:[0,1]
	v_pk_add_f32 v[106:107], v[106:107], v[252:253] neg_lo:[0,1] neg_hi:[0,1]
	v_pk_add_f32 v[108:109], v[108:109], v[252:253] neg_lo:[0,1] neg_hi:[0,1]
	v_pk_add_f32 v[110:111], v[110:111], v[252:253] neg_lo:[0,1] neg_hi:[0,1]
	v_pk_add_f32 v[112:113], v[112:113], v[252:253] neg_lo:[0,1] neg_hi:[0,1]
	v_pk_add_f32 v[114:115], v[114:115], v[252:253] neg_lo:[0,1] neg_hi:[0,1]
	v_exp_f32_e32 v188, v188
	v_exp_f32_e32 v189, v189
	v_exp_f32_e32 v190, v190
	v_exp_f32_e32 v191, v191
	v_add_f32_e32 v252, v188, v190
	v_exp_f32_e32 v192, v192
	v_add_f32_e32 v253, v189, v191
	v_exp_f32_e32 v193, v193
	v_cvt_pk_bf16_f32 v188, v188, v189
	v_exp_f32_e32 v194, v194
	v_cvt_pk_bf16_f32 v189, v190, v191
	v_exp_f32_e32 v195, v195
	v_add_f32_e32 v252, v252, v192
	v_add_f32_e32 v253, v253, v193
	v_cvt_pk_bf16_f32 v190, v192, v193
	v_add_f32_e32 v252, v252, v194
	v_add_f32_e32 v253, v253, v195
	v_cvt_pk_bf16_f32 v191, v194, v195
	v_exp_f32_e32 v196, v196
	v_exp_f32_e32 v197, v197
	v_exp_f32_e32 v198, v198
	v_add_f32_e32 v252, v252, v196
	v_exp_f32_e32 v199, v199
	v_add_f32_e32 v253, v253, v197
	v_exp_f32_e32 v200, v200
	v_add_f32_e32 v252, v252, v198
	v_exp_f32_e32 v201, v201
	v_add_f32_e32 v253, v253, v199
	v_exp_f32_e32 v202, v202
	v_cvt_pk_bf16_f32 v192, v196, v197
	v_exp_f32_e32 v203, v203
	v_cvt_pk_bf16_f32 v193, v198, v199
	v_add_f32_e32 v252, v252, v200
	v_add_f32_e32 v253, v253, v201
	v_cvt_pk_bf16_f32 v194, v200, v201
	v_add_f32_e32 v252, v252, v202
	v_add_f32_e32 v253, v253, v203
	v_cvt_pk_bf16_f32 v195, v202, v203
	v_exp_f32_e32 v204, v204
	v_exp_f32_e32 v205, v205
	v_exp_f32_e32 v206, v206
	v_add_f32_e32 v252, v252, v204
	v_exp_f32_e32 v207, v207
	v_add_f32_e32 v253, v253, v205
	v_exp_f32_e32 v208, v208
	v_add_f32_e32 v252, v252, v206
	v_exp_f32_e32 v209, v209
	v_add_f32_e32 v253, v253, v207
	v_exp_f32_e32 v210, v210
	v_cvt_pk_bf16_f32 v204, v204, v205
	v_exp_f32_e32 v211, v211
	v_cvt_pk_bf16_f32 v205, v206, v207
	v_add_f32_e32 v252, v252, v208
	v_add_f32_e32 v253, v253, v209
	v_cvt_pk_bf16_f32 v206, v208, v209
	v_add_f32_e32 v252, v252, v210
	v_add_f32_e32 v253, v253, v211
	v_cvt_pk_bf16_f32 v207, v210, v211
	v_exp_f32_e32 v212, v212
	v_exp_f32_e32 v213, v213
	v_exp_f32_e32 v214, v214
	v_add_f32_e32 v252, v252, v212
	v_exp_f32_e32 v215, v215
	v_add_f32_e32 v253, v253, v213
	v_exp_f32_e32 v216, v216
	v_add_f32_e32 v252, v252, v214
	v_exp_f32_e32 v217, v217
	v_add_f32_e32 v253, v253, v215
	v_exp_f32_e32 v218, v218
	v_cvt_pk_bf16_f32 v208, v212, v213
	v_exp_f32_e32 v219, v219
	v_cvt_pk_bf16_f32 v209, v214, v215
	v_add_f32_e32 v252, v252, v216
	v_add_f32_e32 v253, v253, v217
	v_cvt_pk_bf16_f32 v210, v216, v217
	v_add_f32_e32 v252, v252, v218
	v_add_f32_e32 v253, v253, v219
	v_cvt_pk_bf16_f32 v211, v218, v219
	s_mov_b32 s24, s23
	s_mov_b32 s35, s24
	v_mov_b32_e32 v251, 0
	s_cmp_eq_u32 s24, 1
	s_cselect_b64 vcc, -1, 0
	v_cndmask_b32_e32 v251, v251, v177, vcc
	s_cmp_eq_u32 s24, 2
	s_cselect_b64 vcc, -1, 0
	v_cndmask_b32_e32 v251, v251, v178, vcc
	v_sub_f32_e32 v2, v251, v186
	v_mov_b32_e32 v3, v2
	v_mov_b64_e32 v[4:5], v[2:3]
	v_mov_b64_e32 v[6:7], v[2:3]
	v_mov_b64_e32 v[8:9], v[2:3]
	v_mov_b64_e32 v[10:11], v[2:3]
	v_mov_b64_e32 v[12:13], v[2:3]
	v_mov_b64_e32 v[14:15], v[2:3]
	v_mov_b64_e32 v[16:17], v[2:3]
	ds_read_b64_tr_b16 v[132:133], v228 offset:16384
	ds_read_b64_tr_b16 v[134:135], v228 offset:18432
	ds_read_b64_tr_b16 v[136:137], v229 offset:16384
	ds_read_b64_tr_b16 v[138:139], v229 offset:18432
	ds_read_b64_tr_b16 v[140:141], v230 offset:16384
	ds_read_b64_tr_b16 v[142:143], v230 offset:18432
	ds_read_b64_tr_b16 v[144:145], v231 offset:16384
	ds_read_b64_tr_b16 v[146:147], v231 offset:18432
	ds_read_b64_tr_b16 v[220:221], v228 offset:20480
	ds_read_b64_tr_b16 v[222:223], v228 offset:22528
	ds_read_b64_tr_b16 v[224:225], v229 offset:20480
	ds_read_b64_tr_b16 v[226:227], v229 offset:22528
	ds_read_b64_tr_b16 v[232:233], v230 offset:20480
	ds_read_b64_tr_b16 v[234:235], v230 offset:22528
	s_nop 1
	s_cmp_eq_u32 s22, 0
	s_cbranch_scc1 .LatB_recret_h1
	s_cmp_eq_u32 s22, 1
	s_cbranch_scc1 .LatB_recret_m1
	s_branch .LatB_recret_x3

; #define LAS __attribute__((address_space(3)))
; __device__ __forceinline__ float max2f(float a, float b) { float r; asm("v_max_f32_e32 %0, %1, %2" : "=v"(r) : "v"(a), "v"(b)); return r; }
; __device__ __forceinline__ void attn_unit(LAS unsigned char* lds, const bf16_t* Z, bf16_t* A2, const float* tabg, int seq_base, int S, int h, int qb, float lam) {
;     ...
;         float mx = max2f(max16f(p0), max16f(p1));
;         const bool first = (t == 0);
;         if (first || __any(mx > THR)) {
;             { auto rr = __builtin_amdgcn_permlane32_swap(__float_as_uint(mx), __float_as_uint(mx), false, false); mx = max2f(__uint_as_float(rr[0]), __uint_as_float(rr[1])); }
;             const float delta = first ? mx : fmaxf(mx, 0.f);
;             const float alpha = first ? 1.0f : __builtin_amdgcn_exp2f(-delta);
;             mu += delta; ls2 *= alpha;
;             if (!first) {
;                 asm volatile("" ::: "memory");
;                 scr[r32] = alpha;
;                 asm volatile("s_waitcnt lgkmcnt(0)" ::: "memory");
; #pragma unroll
;                 for (int g = 0; g < 4; ++g) { const f32x4 a4 = *(const LAS f32x4*)(scr + 8 * g + 4 * hi);
; #pragma unroll
;                     for (int d = 0; d < 4; ++d) { O[d][4 * g + 0] *= a4[0]; O[d][4 * g + 1] *= a4[1]; O[d][4 * g + 2] *= a4[2]; O[d][4 * g + 3] *= a4[3]; } }
;                 asm volatile("s_waitcnt lgkmcnt(0)" ::: "memory");
;             }
; #pragma unroll
;             for (int r = 0; r < 16; ++r) { p0[r] -= delta; p1[r] -= delta; }
.LatB_recnn_2:
	v_max3_f32 v251, v84, v85, v86
	v_max3_f32 v252, v87, v88, v89
	v_max3_f32 v251, v251, v90, v91
	v_max3_f32 v252, v252, v92, v93
	v_max3_f32 v251, v251, v94, v95
	v_max3_f32 v252, v252, v96, v97
	v_max3_f32 v251, v251, v98, v99
	v_max3_f32 v252, v252, v100, v101
	v_max3_f32 v251, v251, v102, v103
	v_max3_f32 v252, v252, v104, v105
	v_max3_f32 v251, v251, v106, v107
	v_max3_f32 v252, v252, v108, v109
	v_max3_f32 v251, v251, v110, v111
	v_max3_f32 v252, v252, v112, v113
	v_max3_f32 v251, v251, v114, v115
	v_max_f32_e32 v251, v251, v252
	v_mov_b32_e32 v252, v251
	s_nop 1
	v_permlane32_swap_b32_e32 v251, v252
	v_max_f32_e32 v251, v251, v252
	v_max_f32_e32 v253, 0, v251
	v_exp_f32_e64 v254, -v253
	v_add_f32_e32 v186, v186, v253
	s_nop 0
	v_mul_f32_e32 v150, v150, v254
	v_mul_f32_e32 v151, v151, v254
	ds_write_b32 v184, v254
	s_waitcnt lgkmcnt(0)
	ds_read_b128 v[132:135], v185
	ds_read_b128 v[136:139], v185 offset:32
	ds_read_b128 v[140:143], v185 offset:64
	ds_read_b128 v[144:147], v185 offset:96
	s_waitcnt lgkmcnt(0)
	v_pk_mul_f32 v[20:21], v[20:21], v[132:133]
	v_pk_mul_f32 v[22:23], v[22:23], v[134:135]
	v_pk_mul_f32 v[24:25], v[24:25], v[136:137]
	v_pk_mul_f32 v[26:27], v[26:27], v[138:139]
	v_pk_mul_f32 v[28:29], v[28:29], v[140:141]
	v_pk_mul_f32 v[30:31], v[30:31], v[142:143]
	v_pk_mul_f32 v[32:33], v[32:33], v[144:145]
	v_pk_mul_f32 v[34:35], v[34:35], v[146:147]
	v_pk_mul_f32 v[36:37], v[36:37], v[132:133]
	v_pk_mul_f32 v[38:39], v[38:39], v[134:135]
	v_pk_mul_f32 v[40:41], v[40:41], v[136:137]
	v_pk_mul_f32 v[42:43], v[42:43], v[138:139]
	v_pk_mul_f32 v[44:45], v[44:45], v[140:141]
	v_pk_mul_f32 v[46:47], v[46:47], v[142:143]
	v_pk_mul_f32 v[48:49], v[48:49], v[144:145]
	v_pk_mul_f32 v[50:51], v[50:51], v[146:147]
	v_pk_mul_f32 v[52:53], v[52:53], v[132:133]
	v_pk_mul_f32 v[54:55], v[54:55], v[134:135]
	v_pk_mul_f32 v[56:57], v[56:57], v[136:137]
	v_pk_mul_f32 v[58:59], v[58:59], v[138:139]
	v_pk_mul_f32 v[60:61], v[60:61], v[140:141]
	v_pk_mul_f32 v[62:63], v[62:63], v[142:143]
	v_pk_mul_f32 v[64:65], v[64:65], v[144:145]
	v_pk_mul_f32 v[66:67], v[66:67], v[146:147]
	v_pk_mul_f32 v[68:69], v[68:69], v[132:133]
	v_pk_mul_f32 v[70:71], v[70:71], v[134:135]
	v_pk_mul_f32 v[72:73], v[72:73], v[136:137]
	v_pk_mul_f32 v[74:75], v[74:75], v[138:139]
	v_pk_mul_f32 v[76:77], v[76:77], v[140:141]
	v_pk_mul_f32 v[78:79], v[78:79], v[142:143]
	v_pk_mul_f32 v[80:81], v[80:81], v[144:145]
	v_pk_mul_f32 v[82:83], v[82:83], v[146:147]
	v_mov_b32_e32 v252, v253
	v_pk_add_f32 v[84:85], v[84:85], v[252:253] neg_lo:[0,1] neg_hi:[0,1]
	v_pk_add_f32 v[86:87], v[86:87], v[252:253] neg_lo:[0,1] neg_hi:[0,1]
	v_pk_add_f32 v[88:89], v[88:89], v[252:253] neg_lo:[0,1] neg_hi:[0,1]
	v_pk_add_f32 v[90:91], v[90:91], v[252:253] neg_lo:[0,1] neg_hi:[0,1]
	v_pk_add_f32 v[92:93], v[92:93], v[252:253] neg_lo:[0,1] neg_hi:[0,1]
	v_pk_add_f32 v[94:95], v[94:95], v[252:253] neg_lo:[0,1] neg_hi:[0,1]
	v_pk_add_f32 v[96:97], v[96:97], v[252:253] neg_lo:[0,1] neg_hi:[0,1]
	v_pk_add_f32 v[98:99], v[98:99], v[252:253] neg_lo:[0,1] neg_hi:[0,1]
	v_pk_add_f32 v[100:101], v[100:101], v[252:253] neg_lo:[0,1] neg_hi:[0,1]
	v_pk_add_f32 v[102:103], v[102:103], v[252:253] neg_lo:[0,1] neg_hi:[0,1]
	v_pk_add_f32 v[104:105], v[104:105], v[252:253] neg_lo:[0,1] neg_hi:[0,1]
	v_pk_add_f32 v[106:107], v[106:107], v[252:253] neg_lo:[0,1] neg_hi:[0,1]
	v_pk_add_f32 v[108:109], v[108:109], v[252:253] neg_lo:[0,1] neg_hi:[0,1]
	v_pk_add_f32 v[110:111], v[110:111], v[252:253] neg_lo:[0,1] neg_hi:[0,1]
	v_pk_add_f32 v[112:113], v[112:113], v[252:253] neg_lo:[0,1] neg_hi:[0,1]
	v_pk_add_f32 v[114:115], v[114:115], v[252:253] neg_lo:[0,1] neg_hi:[0,1]
	v_pk_add_f32 v[188:189], v[188:189], v[252:253] neg_lo:[0,1] neg_hi:[0,1]
	v_pk_add_f32 v[190:191], v[190:191], v[252:253] neg_lo:[0,1] neg_hi:[0,1]
	v_pk_add_f32 v[192:193], v[192:193], v[252:253] neg_lo:[0,1] neg_hi:[0,1]
	v_pk_add_f32 v[194:195], v[194:195], v[252:253] neg_lo:[0,1] neg_hi:[0,1]
	v_pk_add_f32 v[196:197], v[196:197], v[252:253] neg_lo:[0,1] neg_hi:[0,1]
	v_pk_add_f32 v[198:199], v[198:199], v[252:253] neg_lo:[0,1] neg_hi:[0,1]
	v_pk_add_f32 v[200:201], v[200:201], v[252:253] neg_lo:[0,1] neg_hi:[0,1]
	v_pk_add_f32 v[202:203], v[202:203], v[252:253] neg_lo:[0,1] neg_hi:[0,1]
; __device__ __forceinline__ void attn_unit(LAS unsigned char* lds, const bf16_t* Z, bf16_t* A2, const float* tabg, int seq_base, int S, int h, int qb, float lam) {
;     ...
;         { const float coff = cc - mu;
;           if (__any(!(coff == coff_cur))) { coff_cur = coff;
; #pragma unroll
;               for (int r = 0; r < 16; ++r) cblk[r] = coff;
;               asm volatile("" : "+v"(cblk)); } }
;     ...
;             for (int r = 0; r < 16; ++r) { p0[r] -= delta; p1[r] -= delta; }
;             asm volatile("" : "+v"(p0), "+v"(p1));
;         }
; #pragma unroll
;         for (int r = 0; r < 16; ++r) { p0[r] = __builtin_amdgcn_exp2f(p0[r]); p1[r] = __builtin_amdgcn_exp2f(p1[r]); }
; #pragma unroll
;         for (int r = 0; r < 16; r += 2) { ls2 += (f32x2){p0[r], p0[r + 1]}; ls2 += (f32x2){p1[r], p1[r + 1]}; }
;         bf16x8 pa[4]; pa[0] = pack8(p0, 0); pa[1] = pack8(p0, 8); pa[2] = pack8(p1, 0); pa[3] = pack8(p1, 8);
	v_pk_add_f32 v[204:205], v[204:205], v[252:253] neg_lo:[0,1] neg_hi:[0,1]
	v_pk_add_f32 v[206:207], v[206:207], v[252:253] neg_lo:[0,1] neg_hi:[0,1]
	v_pk_add_f32 v[208:209], v[208:209], v[252:253] neg_lo:[0,1] neg_hi:[0,1]
	v_pk_add_f32 v[210:211], v[210:211], v[252:253] neg_lo:[0,1] neg_hi:[0,1]
	v_pk_add_f32 v[212:213], v[212:213], v[252:253] neg_lo:[0,1] neg_hi:[0,1]
	v_pk_add_f32 v[214:215], v[214:215], v[252:253] neg_lo:[0,1] neg_hi:[0,1]
	v_pk_add_f32 v[216:217], v[216:217], v[252:253] neg_lo:[0,1] neg_hi:[0,1]
	v_pk_add_f32 v[218:219], v[218:219], v[252:253] neg_lo:[0,1] neg_hi:[0,1]
	v_exp_f32_e32 v84, v84
	v_exp_f32_e32 v85, v85
	v_exp_f32_e32 v86, v86
	v_exp_f32_e32 v87, v87
	v_add_f32_e32 v252, v84, v86
	v_exp_f32_e32 v88, v88
	v_add_f32_e32 v253, v85, v87
	v_exp_f32_e32 v89, v89
	v_cvt_pk_bf16_f32 v84, v84, v85
	v_exp_f32_e32 v90, v90
	v_cvt_pk_bf16_f32 v85, v86, v87
	v_exp_f32_e32 v91, v91
	v_add_f32_e32 v252, v252, v88
	v_add_f32_e32 v253, v253, v89
	v_cvt_pk_bf16_f32 v86, v88, v89
	v_add_f32_e32 v252, v252, v90
	v_add_f32_e32 v253, v253, v91
	v_cvt_pk_bf16_f32 v87, v90, v91
	v_exp_f32_e32 v92, v92
	v_exp_f32_e32 v93, v93
	v_exp_f32_e32 v94, v94
	v_add_f32_e32 v252, v252, v92
	v_exp_f32_e32 v95, v95
	v_add_f32_e32 v253, v253, v93
	v_exp_f32_e32 v96, v96
	v_add_f32_e32 v252, v252, v94
	v_exp_f32_e32 v97, v97
	v_add_f32_e32 v253, v253, v95
	v_exp_f32_e32 v98, v98
	v_cvt_pk_bf16_f32 v88, v92, v93
	v_exp_f32_e32 v99, v99
	v_cvt_pk_bf16_f32 v89, v94, v95
	v_add_f32_e32 v252, v252, v96
	v_add_f32_e32 v253, v253, v97
	v_cvt_pk_bf16_f32 v90, v96, v97
	v_add_f32_e32 v252, v252, v98
	v_add_f32_e32 v253, v253, v99
	v_cvt_pk_bf16_f32 v91, v98, v99
	v_exp_f32_e32 v100, v100
	v_exp_f32_e32 v101, v101
	v_exp_f32_e32 v102, v102
	v_add_f32_e32 v252, v252, v100
	v_exp_f32_e32 v103, v103
	v_add_f32_e32 v253, v253, v101
	v_exp_f32_e32 v104, v104
	v_add_f32_e32 v252, v252, v102
	v_exp_f32_e32 v105, v105
	v_add_f32_e32 v253, v253, v103
	v_exp_f32_e32 v106, v106
	v_cvt_pk_bf16_f32 v100, v100, v101
	v_exp_f32_e32 v107, v107
	v_cvt_pk_bf16_f32 v101, v102, v103
	v_add_f32_e32 v252, v252, v104
	v_add_f32_e32 v253, v253, v105
	v_cvt_pk_bf16_f32 v102, v104, v105
	v_add_f32_e32 v252, v252, v106
	v_add_f32_e32 v253, v253, v107
	v_cvt_pk_bf16_f32 v103, v106, v107
	v_exp_f32_e32 v108, v108
	v_exp_f32_e32 v109, v109
	v_exp_f32_e32 v110, v110
	v_add_f32_e32 v252, v252, v108
	v_exp_f32_e32 v111, v111
	v_add_f32_e32 v253, v253, v109
	v_exp_f32_e32 v112, v112
	v_add_f32_e32 v252, v252, v110
	v_exp_f32_e32 v113, v113
	v_add_f32_e32 v253, v253, v111
	v_exp_f32_e32 v114, v114
	v_cvt_pk_bf16_f32 v104, v108, v109
	v_exp_f32_e32 v115, v115
	v_cvt_pk_bf16_f32 v105, v110, v111
	v_add_f32_e32 v252, v252, v112
	v_add_f32_e32 v253, v253, v113
	v_cvt_pk_bf16_f32 v106, v112, v113
	v_add_f32_e32 v252, v252, v114
	v_add_f32_e32 v253, v253, v115
	v_cvt_pk_bf16_f32 v107, v114, v115
	s_mov_b32 s24, s23
	s_mov_b32 s35, s24
	v_mov_b32_e32 v251, 0
	s_cmp_eq_u32 s24, 1
	s_cselect_b64 vcc, -1, 0
	v_cndmask_b32_e32 v251, v251, v177, vcc
	s_cmp_eq_u32 s24, 2
	s_cselect_b64 vcc, -1, 0
	v_cndmask_b32_e32 v251, v251, v178, vcc
	v_sub_f32_e32 v2, v251, v186
	v_mov_b32_e32 v3, v2
	v_mov_b64_e32 v[4:5], v[2:3]
	v_mov_b64_e32 v[6:7], v[2:3]
	v_mov_b64_e32 v[8:9], v[2:3]
	v_mov_b64_e32 v[10:11], v[2:3]
	v_mov_b64_e32 v[12:13], v[2:3]
	v_mov_b64_e32 v[14:15], v[2:3]
	v_mov_b64_e32 v[16:17], v[2:3]
	ds_read_b64_tr_b16 v[132:133], v228 offset:32768
	ds_read_b64_tr_b16 v[134:135], v228 offset:34816
	ds_read_b64_tr_b16 v[136:137], v229 offset:32768
	ds_read_b64_tr_b16 v[138:139], v229 offset:34816
	ds_read_b64_tr_b16 v[140:141], v230 offset:32768
	ds_read_b64_tr_b16 v[142:143], v230 offset:34816
	ds_read_b64_tr_b16 v[144:145], v231 offset:32768
	ds_read_b64_tr_b16 v[146:147], v231 offset:34816
	ds_read_b64_tr_b16 v[220:221], v228 offset:36864
	ds_read_b64_tr_b16 v[222:223], v228 offset:38912
	ds_read_b64_tr_b16 v[224:225], v229 offset:36864
	ds_read_b64_tr_b16 v[226:227], v229 offset:38912
	ds_read_b64_tr_b16 v[232:233], v230 offset:36864
	ds_read_b64_tr_b16 v[234:235], v230 offset:38912
	s_nop 1
	s_cmp_eq_u32 s22, 0
	s_cbranch_scc1 .LatB_recret_h2
	s_cmp_eq_u32 s22, 1
	s_cbranch_scc1 .LatB_recret_m2
	s_branch .LatB_recret_x2

; #define LAS __attribute__((address_space(3)))
; __device__ __forceinline__ float max2f(float a, float b) { float r; asm("v_max_f32_e32 %0, %1, %2" : "=v"(r) : "v"(a), "v"(b)); return r; }
; __device__ __forceinline__ void attn_unit(LAS unsigned char* lds, const bf16_t* Z, bf16_t* A2, const float* tabg, int seq_base, int S, int h, int qb, float lam) {
;     ...
;         float mx = max2f(max16f(p0), max16f(p1));
;         const bool first = (t == 0);
;         if (first || __any(mx > THR)) {
;             { auto rr = __builtin_amdgcn_permlane32_swap(__float_as_uint(mx), __float_as_uint(mx), false, false); mx = max2f(__uint_as_float(rr[0]), __uint_as_float(rr[1])); }
;             const float delta = first ? mx : fmaxf(mx, 0.f);
;             const float alpha = first ? 1.0f : __builtin_amdgcn_exp2f(-delta);
;             mu += delta; ls2 *= alpha;
;             if (!first) {
;                 asm volatile("" ::: "memory");
;                 scr[r32] = alpha;
;                 asm volatile("s_waitcnt lgkmcnt(0)" ::: "memory");
; #pragma unroll
;                 for (int g = 0; g < 4; ++g) { const f32x4 a4 = *(const LAS f32x4*)(scr + 8 * g + 4 * hi);
; #pragma unroll
;                     for (int d = 0; d < 4; ++d) { O[d][4 * g + 0] *= a4[0]; O[d][4 * g + 1] *= a4[1]; O[d][4 * g + 2] *= a4[2]; O[d][4 * g + 3] *= a4[3]; } }
;                 asm volatile("s_waitcnt lgkmcnt(0)" ::: "memory");
;             }
; #pragma unroll
;             for (int r = 0; r < 16; ++r) { p0[r] -= delta; p1[r] -= delta; }
.LatB_recnn_3:
	v_max3_f32 v251, v188, v189, v190
	v_max3_f32 v252, v191, v192, v193
	v_max3_f32 v251, v251, v194, v195
	v_max3_f32 v252, v252, v196, v197
	v_max3_f32 v251, v251, v198, v199
	v_max3_f32 v252, v252, v200, v201
	v_max3_f32 v251, v251, v202, v203
	v_max3_f32 v252, v252, v204, v205
	v_max3_f32 v251, v251, v206, v207
	v_max3_f32 v252, v252, v208, v209
	v_max3_f32 v251, v251, v210, v211
	v_max3_f32 v252, v252, v212, v213
	v_max3_f32 v251, v251, v214, v215
	v_max3_f32 v252, v252, v216, v217
	v_max3_f32 v251, v251, v218, v219
	v_max_f32_e32 v251, v251, v252
	v_mov_b32_e32 v252, v251
	s_nop 1
	v_permlane32_swap_b32_e32 v251, v252
	v_max_f32_e32 v251, v251, v252
	v_max_f32_e32 v253, 0, v251
	v_exp_f32_e64 v254, -v253
	v_add_f32_e32 v186, v186, v253
	s_nop 0
	v_mul_f32_e32 v150, v150, v254
	v_mul_f32_e32 v151, v151, v254
	ds_write_b32 v184, v254
	s_waitcnt lgkmcnt(0)
	ds_read_b128 v[132:135], v185
	ds_read_b128 v[136:139], v185 offset:32
	ds_read_b128 v[140:143], v185 offset:64
	ds_read_b128 v[144:147], v185 offset:96
	s_waitcnt lgkmcnt(0)
	v_pk_mul_f32 v[20:21], v[20:21], v[132:133]
	v_pk_mul_f32 v[22:23], v[22:23], v[134:135]
	v_pk_mul_f32 v[24:25], v[24:25], v[136:137]
	v_pk_mul_f32 v[26:27], v[26:27], v[138:139]
	v_pk_mul_f32 v[28:29], v[28:29], v[140:141]
	v_pk_mul_f32 v[30:31], v[30:31], v[142:143]
	v_pk_mul_f32 v[32:33], v[32:33], v[144:145]
	v_pk_mul_f32 v[34:35], v[34:35], v[146:147]
	v_pk_mul_f32 v[36:37], v[36:37], v[132:133]
	v_pk_mul_f32 v[38:39], v[38:39], v[134:135]
	v_pk_mul_f32 v[40:41], v[40:41], v[136:137]
	v_pk_mul_f32 v[42:43], v[42:43], v[138:139]
	v_pk_mul_f32 v[44:45], v[44:45], v[140:141]
	v_pk_mul_f32 v[46:47], v[46:47], v[142:143]
	v_pk_mul_f32 v[48:49], v[48:49], v[144:145]
	v_pk_mul_f32 v[50:51], v[50:51], v[146:147]
	v_pk_mul_f32 v[52:53], v[52:53], v[132:133]
	v_pk_mul_f32 v[54:55], v[54:55], v[134:135]
	v_pk_mul_f32 v[56:57], v[56:57], v[136:137]
	v_pk_mul_f32 v[58:59], v[58:59], v[138:139]
	v_pk_mul_f32 v[60:61], v[60:61], v[140:141]
	v_pk_mul_f32 v[62:63], v[62:63], v[142:143]
	v_pk_mul_f32 v[64:65], v[64:65], v[144:145]
	v_pk_mul_f32 v[66:67], v[66:67], v[146:147]
	v_pk_mul_f32 v[68:69], v[68:69], v[132:133]
	v_pk_mul_f32 v[70:71], v[70:71], v[134:135]
	v_pk_mul_f32 v[72:73], v[72:73], v[136:137]
	v_pk_mul_f32 v[74:75], v[74:75], v[138:139]
	v_pk_mul_f32 v[76:77], v[76:77], v[140:141]
	v_pk_mul_f32 v[78:79], v[78:79], v[142:143]
	v_pk_mul_f32 v[80:81], v[80:81], v[144:145]
	v_pk_mul_f32 v[82:83], v[82:83], v[146:147]
	v_mov_b32_e32 v252, v253
	v_pk_add_f32 v[188:189], v[188:189], v[252:253] neg_lo:[0,1] neg_hi:[0,1]
	v_pk_add_f32 v[190:191], v[190:191], v[252:253] neg_lo:[0,1] neg_hi:[0,1]
	v_pk_add_f32 v[192:193], v[192:193], v[252:253] neg_lo:[0,1] neg_hi:[0,1]
	v_pk_add_f32 v[194:195], v[194:195], v[252:253] neg_lo:[0,1] neg_hi:[0,1]
	v_pk_add_f32 v[196:197], v[196:197], v[252:253] neg_lo:[0,1] neg_hi:[0,1]
	v_pk_add_f32 v[198:199], v[198:199], v[252:253] neg_lo:[0,1] neg_hi:[0,1]
	v_pk_add_f32 v[200:201], v[200:201], v[252:253] neg_lo:[0,1] neg_hi:[0,1]
	v_pk_add_f32 v[202:203], v[202:203], v[252:253] neg_lo:[0,1] neg_hi:[0,1]
	v_pk_add_f32 v[204:205], v[204:205], v[252:253] neg_lo:[0,1] neg_hi:[0,1]
	v_pk_add_f32 v[206:207], v[206:207], v[252:253] neg_lo:[0,1] neg_hi:[0,1]
	v_pk_add_f32 v[208:209], v[208:209], v[252:253] neg_lo:[0,1] neg_hi:[0,1]
	v_pk_add_f32 v[210:211], v[210:211], v[252:253] neg_lo:[0,1] neg_hi:[0,1]
	v_pk_add_f32 v[212:213], v[212:213], v[252:253] neg_lo:[0,1] neg_hi:[0,1]
	v_pk_add_f32 v[214:215], v[214:215], v[252:253] neg_lo:[0,1] neg_hi:[0,1]
	v_pk_add_f32 v[216:217], v[216:217], v[252:253] neg_lo:[0,1] neg_hi:[0,1]
	v_pk_add_f32 v[218:219], v[218:219], v[252:253] neg_lo:[0,1] neg_hi:[0,1]
	v_pk_add_f32 v[84:85], v[84:85], v[252:253] neg_lo:[0,1] neg_hi:[0,1]
	v_pk_add_f32 v[86:87], v[86:87], v[252:253] neg_lo:[0,1] neg_hi:[0,1]
	v_pk_add_f32 v[88:89], v[88:89], v[252:253] neg_lo:[0,1] neg_hi:[0,1]
	v_pk_add_f32 v[90:91], v[90:91], v[252:253] neg_lo:[0,1] neg_hi:[0,1]
	v_pk_add_f32 v[92:93], v[92:93], v[252:253] neg_lo:[0,1] neg_hi:[0,1]
	v_pk_add_f32 v[94:95], v[94:95], v[252:253] neg_lo:[0,1] neg_hi:[0,1]
	v_pk_add_f32 v[96:97], v[96:97], v[252:253] neg_lo:[0,1] neg_hi:[0,1]
	v_pk_add_f32 v[98:99], v[98:99], v[252:253] neg_lo:[0,1] neg_hi:[0,1]
; __device__ __forceinline__ void attn_unit(LAS unsigned char* lds, const bf16_t* Z, bf16_t* A2, const float* tabg, int seq_base, int S, int h, int qb, float lam) {
;     ...
;         { const float coff = cc - mu;
;           if (__any(!(coff == coff_cur))) { coff_cur = coff;
; #pragma unroll
;               for (int r = 0; r < 16; ++r) cblk[r] = coff;
;               asm volatile("" : "+v"(cblk)); } }
;     ...
;             for (int r = 0; r < 16; ++r) { p0[r] -= delta; p1[r] -= delta; }
;             asm volatile("" : "+v"(p0), "+v"(p1));
;         }
; #pragma unroll
;         for (int r = 0; r < 16; ++r) { p0[r] = __builtin_amdgcn_exp2f(p0[r]); p1[r] = __builtin_amdgcn_exp2f(p1[r]); }
; #pragma unroll
;         for (int r = 0; r < 16; r += 2) { ls2 += (f32x2){p0[r], p0[r + 1]}; ls2 += (f32x2){p1[r], p1[r + 1]}; }
;         bf16x8 pa[4]; pa[0] = pack8(p0, 0); pa[1] = pack8(p0, 8); pa[2] = pack8(p1, 0); pa[3] = pack8(p1, 8);
	v_pk_add_f32 v[100:101], v[100:101], v[252:253] neg_lo:[0,1] neg_hi:[0,1]
	v_pk_add_f32 v[102:103], v[102:103], v[252:253] neg_lo:[0,1] neg_hi:[0,1]
	v_pk_add_f32 v[104:105], v[104:105], v[252:253] neg_lo:[0,1] neg_hi:[0,1]
	v_pk_add_f32 v[106:107], v[106:107], v[252:253] neg_lo:[0,1] neg_hi:[0,1]
	v_pk_add_f32 v[108:109], v[108:109], v[252:253] neg_lo:[0,1] neg_hi:[0,1]
	v_pk_add_f32 v[110:111], v[110:111], v[252:253] neg_lo:[0,1] neg_hi:[0,1]
	v_pk_add_f32 v[112:113], v[112:113], v[252:253] neg_lo:[0,1] neg_hi:[0,1]
	v_pk_add_f32 v[114:115], v[114:115], v[252:253] neg_lo:[0,1] neg_hi:[0,1]
	v_exp_f32_e32 v188, v188
	v_exp_f32_e32 v189, v189
	v_exp_f32_e32 v190, v190
	v_exp_f32_e32 v191, v191
	v_add_f32_e32 v252, v188, v190
	v_exp_f32_e32 v192, v192
	v_add_f32_e32 v253, v189, v191
	v_exp_f32_e32 v193, v193
	v_cvt_pk_bf16_f32 v188, v188, v189
	v_exp_f32_e32 v194, v194
	v_cvt_pk_bf16_f32 v189, v190, v191
	v_exp_f32_e32 v195, v195
	v_add_f32_e32 v252, v252, v192
	v_add_f32_e32 v253, v253, v193
	v_cvt_pk_bf16_f32 v190, v192, v193
	v_add_f32_e32 v252, v252, v194
	v_add_f32_e32 v253, v253, v195
	v_cvt_pk_bf16_f32 v191, v194, v195
	v_exp_f32_e32 v196, v196
	v_exp_f32_e32 v197, v197
	v_exp_f32_e32 v198, v198
	v_add_f32_e32 v252, v252, v196
	v_exp_f32_e32 v199, v199
	v_add_f32_e32 v253, v253, v197
	v_exp_f32_e32 v200, v200
	v_add_f32_e32 v252, v252, v198
	v_exp_f32_e32 v201, v201
	v_add_f32_e32 v253, v253, v199
	v_exp_f32_e32 v202, v202
	v_cvt_pk_bf16_f32 v192, v196, v197
	v_exp_f32_e32 v203, v203
	v_cvt_pk_bf16_f32 v193, v198, v199
	v_add_f32_e32 v252, v252, v200
	v_add_f32_e32 v253, v253, v201
	v_cvt_pk_bf16_f32 v194, v200, v201
	v_add_f32_e32 v252, v252, v202
	v_add_f32_e32 v253, v253, v203
	v_cvt_pk_bf16_f32 v195, v202, v203
	v_exp_f32_e32 v204, v204
	v_exp_f32_e32 v205, v205
	v_exp_f32_e32 v206, v206
	v_add_f32_e32 v252, v252, v204
	v_exp_f32_e32 v207, v207
	v_add_f32_e32 v253, v253, v205
	v_exp_f32_e32 v208, v208
	v_add_f32_e32 v252, v252, v206
	v_exp_f32_e32 v209, v209
	v_add_f32_e32 v253, v253, v207
	v_exp_f32_e32 v210, v210
	v_cvt_pk_bf16_f32 v204, v204, v205
	v_exp_f32_e32 v211, v211
	v_cvt_pk_bf16_f32 v205, v206, v207
	v_add_f32_e32 v252, v252, v208
	v_add_f32_e32 v253, v253, v209
	v_cvt_pk_bf16_f32 v206, v208, v209
	v_add_f32_e32 v252, v252, v210
	v_add_f32_e32 v253, v253, v211
	v_cvt_pk_bf16_f32 v207, v210, v211
	v_exp_f32_e32 v212, v212
	v_exp_f32_e32 v213, v213
	v_exp_f32_e32 v214, v214
	v_add_f32_e32 v252, v252, v212
	v_exp_f32_e32 v215, v215
	v_add_f32_e32 v253, v253, v213
	v_exp_f32_e32 v216, v216
	v_add_f32_e32 v252, v252, v214
	v_exp_f32_e32 v217, v217
	v_add_f32_e32 v253, v253, v215
	v_exp_f32_e32 v218, v218
	v_cvt_pk_bf16_f32 v208, v212, v213
	v_exp_f32_e32 v219, v219
	v_cvt_pk_bf16_f32 v209, v214, v215
	v_add_f32_e32 v252, v252, v216
	v_add_f32_e32 v253, v253, v217
	v_cvt_pk_bf16_f32 v210, v216, v217
	v_add_f32_e32 v252, v252, v218
	v_add_f32_e32 v253, v253, v219
	v_cvt_pk_bf16_f32 v211, v218, v219
	s_mov_b32 s24, s23
	s_mov_b32 s35, s24
	v_mov_b32_e32 v251, 0
	s_cmp_eq_u32 s24, 1
	s_cselect_b64 vcc, -1, 0
	v_cndmask_b32_e32 v251, v251, v177, vcc
	s_cmp_eq_u32 s24, 2
	s_cselect_b64 vcc, -1, 0
	v_cndmask_b32_e32 v251, v251, v178, vcc
	v_sub_f32_e32 v2, v251, v186
	v_mov_b32_e32 v3, v2
	v_mov_b64_e32 v[4:5], v[2:3]
	v_mov_b64_e32 v[6:7], v[2:3]
	v_mov_b64_e32 v[8:9], v[2:3]
	v_mov_b64_e32 v[10:11], v[2:3]
	v_mov_b64_e32 v[12:13], v[2:3]
	v_mov_b64_e32 v[14:15], v[2:3]
	v_mov_b64_e32 v[16:17], v[2:3]
	ds_read_b64_tr_b16 v[132:133], v168 offset:0
	ds_read_b64_tr_b16 v[134:135], v168 offset:2048
	ds_read_b64_tr_b16 v[136:137], v169 offset:0
	ds_read_b64_tr_b16 v[138:139], v169 offset:2048
	ds_read_b64_tr_b16 v[140:141], v170 offset:0
	ds_read_b64_tr_b16 v[142:143], v170 offset:2048
	ds_read_b64_tr_b16 v[144:145], v171 offset:0
	ds_read_b64_tr_b16 v[146:147], v171 offset:2048
	ds_read_b64_tr_b16 v[220:221], v168 offset:4096
	ds_read_b64_tr_b16 v[222:223], v168 offset:6144
	ds_read_b64_tr_b16 v[224:225], v169 offset:4096
	ds_read_b64_tr_b16 v[226:227], v169 offset:6144
	ds_read_b64_tr_b16 v[232:233], v170 offset:4096
	ds_read_b64_tr_b16 v[234:235], v170 offset:6144
	s_nop 1
	s_cmp_eq_u32 s22, 0
	s_cbranch_scc1 .LatB_recret_h3
	s_cmp_eq_u32 s22, 1
	s_cbranch_scc1 .LatB_recret_m3
	s_branch .LatB_recret_x1
